# GEMM K-loops: per-cluster s_setprio flips deleted, one static s_setprio 1 for waves 0-3 at kernel entry
# baseline (speedup 1.0000x reference)
_Z10fwd_kernel4Args:
	s_load_dwordx8 s[68:75], s[0:1], 0xc0
	s_load_dwordx2 s[34:35], s[0:1], 0xe0
	s_add_u32 s8, s0, 0xe0
	v_and_b32_e32 v192, 0x3ff, v0
	s_addc_u32 s9, s1, 0
	v_cmp_gt_u32_e64 s[4:5], 16, v192
	s_and_saveexec_b64 s[6:7], s[4:5]
	v_lshl_add_u32 v1, v192, 2, 0
	v_add_u32_e32 v1, 0x20000, v1
	v_mov_b32_e32 v2, 0
	ds_write_b32 v1, v2
	s_or_b64 exec, exec, s[6:7]
	s_load_dword s90, s[0:1], 0xe8
	s_waitcnt lgkmcnt(0)
	s_barrier
	v_readfirstlane_b32 s3, v192
	s_lshr_b32 s3, s3, 6
	s_cmp_lt_u32 s3, 4
	s_cbranch_scc0 .Lprio_done
	s_setprio 1
.Lprio_done:
	s_add_u32 s88, s72, 0x4810000
	s_getreg_b32 s3, hwreg(HW_REG_XCC_ID, 0, 4)
	s_addc_u32 s89, s73, 0
	s_and_b32 s33, s3, 15
	v_cmp_eq_u32_e64 s[10:11], 0, v192
	s_and_saveexec_b64 s[6:7], s[10:11]
	s_cbranch_execz .LBB0_5
	s_mov_b64 s[12:13], exec
	v_mbcnt_lo_u32_b32 v1, s12, 0
	v_mbcnt_hi_u32_b32 v1, s13, v1
	v_cmp_eq_u32_e32 vcc, 0, v1
	s_and_b64 s[14:15], exec, vcc
	s_mov_b64 exec, s[14:15]
	s_cbranch_execz .LBB0_5
	s_lshl_b32 s3, s33, 8
	s_bcnt1_i32_b64 s12, s[12:13]
	v_mov_b32_e32 v1, s3
	v_mov_b32_e32 v2, s12
	global_atomic_add v1, v2, s[88:89] offset:1024

.LBB0_355:
	s_waitcnt lgkmcnt(0)
	s_barrier
	s_waitcnt lgkmcnt(0)
	v_mfma_f32_16x16x32_bf16 v[60:63], v[144:147], v[184:187], v[60:63]
	v_mfma_f32_16x16x32_bf16 v[56:59], v[152:155], v[184:187], v[56:59]
	v_mfma_f32_16x16x32_bf16 v[44:47], v[144:147], v[176:179], v[44:47]
	v_mfma_f32_16x16x32_bf16 v[40:43], v[152:155], v[176:179], v[40:43]
	v_mfma_f32_16x16x32_bf16 v[28:31], v[144:147], v[168:171], v[28:31]
	v_mfma_f32_16x16x32_bf16 v[24:27], v[152:155], v[168:171], v[24:27]
	v_mfma_f32_16x16x32_bf16 v[12:15], v[144:147], v[160:163], v[12:15]
	v_mfma_f32_16x16x32_bf16 v[8:11], v[152:155], v[160:163], v[8:11]
	v_mfma_f32_16x16x32_bf16 v[60:63], v[148:151], v[188:191], v[60:63]
	v_mfma_f32_16x16x32_bf16 v[56:59], v[156:159], v[188:191], v[56:59]
	v_mfma_f32_16x16x32_bf16 v[44:47], v[148:151], v[180:183], v[44:47]
	v_mfma_f32_16x16x32_bf16 v[40:43], v[156:159], v[180:183], v[40:43]
	v_mfma_f32_16x16x32_bf16 v[28:31], v[148:151], v[172:175], v[28:31]
	v_mfma_f32_16x16x32_bf16 v[24:27], v[156:159], v[172:175], v[24:27]
	v_mfma_f32_16x16x32_bf16 v[12:15], v[148:151], v[164:167], v[12:15]
	v_mfma_f32_16x16x32_bf16 v[8:11], v[156:159], v[164:167], v[8:11]
	v_mfma_f32_16x16x32_bf16 v[52:55], v[128:131], v[184:187], v[52:55]
	v_mfma_f32_16x16x32_bf16 v[48:51], v[136:139], v[184:187], v[48:51]
	v_mfma_f32_16x16x32_bf16 v[36:39], v[128:131], v[176:179], v[36:39]
	v_mfma_f32_16x16x32_bf16 v[32:35], v[136:139], v[176:179], v[32:35]
	v_mfma_f32_16x16x32_bf16 v[20:23], v[128:131], v[168:171], v[20:23]
	v_mfma_f32_16x16x32_bf16 v[16:19], v[136:139], v[168:171], v[16:19]
	v_mfma_f32_16x16x32_bf16 v[4:7], v[128:131], v[160:163], v[4:7]
	v_mfma_f32_16x16x32_bf16 v[0:3], v[136:139], v[160:163], v[0:3]
	v_mfma_f32_16x16x32_bf16 v[52:55], v[132:135], v[188:191], v[52:55]
	v_mfma_f32_16x16x32_bf16 v[48:51], v[140:143], v[188:191], v[48:51]
	v_mfma_f32_16x16x32_bf16 v[36:39], v[132:135], v[180:183], v[36:39]
	v_mfma_f32_16x16x32_bf16 v[32:35], v[140:143], v[180:183], v[32:35]
	v_mfma_f32_16x16x32_bf16 v[20:23], v[132:135], v[172:175], v[20:23]
	v_mfma_f32_16x16x32_bf16 v[16:19], v[140:143], v[172:175], v[16:19]
	v_mfma_f32_16x16x32_bf16 v[4:7], v[132:135], v[164:167], v[4:7]
	v_mfma_f32_16x16x32_bf16 v[0:3], v[140:143], v[164:167], v[0:3]
	s_barrier
	s_add_i32 s50, 0, 0x18000
	s_add_i32 s51, 0, 0x1c000
	v_add_u32_e32 v140, s50, v225
	v_add_u32_e32 v156, s51, v225
	ds_read_b128 v[128:131], v140
	ds_read_b128 v[132:135], v140 offset:1024
	ds_read_b128 v[136:139], v140 offset:2048
	ds_read_b128 v[140:143], v140 offset:3072
	ds_read_b128 v[144:147], v156
	ds_read_b128 v[148:151], v156 offset:1024
	ds_read_b128 v[152:155], v156 offset:2048
	ds_read_b128 v[156:159], v156 offset:3072
	s_add_u32 s46, s48, 0x40000
	s_addc_u32 s47, s49, 0
	s_mov_b32 m0, s60
	v_lshl_add_u64 v[240:241], s[46:47], 0, v[194:195]
	ds_read_b128 v[160:163], v228 offset:32768
	ds_read_b128 v[164:167], v228 offset:33792
	ds_read_b128 v[168:171], v228 offset:34816
	ds_read_b128 v[172:175], v228 offset:35840
	ds_read_b128 v[176:179], v228 offset:36864
	ds_read_b128 v[180:183], v228 offset:37888
	ds_read_b128 v[184:187], v228 offset:38912
	ds_read_b128 v[188:191], v228 offset:39936
	global_load_lds_dwordx4 v[240:241], off
	v_lshl_add_u64 v[240:241], s[46:47], 0, v[198:199]
	s_mov_b32 m0, s61
	s_nop 0
	global_load_lds_dwordx4 v[240:241], off
	s_waitcnt vmcnt(8)
	s_waitcnt lgkmcnt(0)
	s_barrier
	s_waitcnt lgkmcnt(0)
	v_mfma_f32_16x16x32_bf16 v[124:127], v[128:131], v[160:163], v[124:127]
	v_mfma_f32_16x16x32_bf16 v[120:123], v[136:139], v[160:163], v[120:123]
	v_mfma_f32_16x16x32_bf16 v[108:111], v[128:131], v[168:171], v[108:111]
	v_mfma_f32_16x16x32_bf16 v[104:107], v[136:139], v[168:171], v[104:107]
	v_mfma_f32_16x16x32_bf16 v[92:95], v[128:131], v[176:179], v[92:95]
	v_mfma_f32_16x16x32_bf16 v[88:91], v[136:139], v[176:179], v[88:91]
	v_mfma_f32_16x16x32_bf16 v[76:79], v[128:131], v[184:187], v[76:79]
	v_mfma_f32_16x16x32_bf16 v[72:75], v[136:139], v[184:187], v[72:75]
	v_mfma_f32_16x16x32_bf16 v[124:127], v[132:135], v[164:167], v[124:127]
	v_mfma_f32_16x16x32_bf16 v[120:123], v[140:143], v[164:167], v[120:123]
	v_mfma_f32_16x16x32_bf16 v[108:111], v[132:135], v[172:175], v[108:111]
	v_mfma_f32_16x16x32_bf16 v[104:107], v[140:143], v[172:175], v[104:107]
	v_mfma_f32_16x16x32_bf16 v[92:95], v[132:135], v[180:183], v[92:95]
	v_mfma_f32_16x16x32_bf16 v[88:91], v[140:143], v[180:183], v[88:91]
	v_mfma_f32_16x16x32_bf16 v[76:79], v[132:135], v[188:191], v[76:79]
	v_mfma_f32_16x16x32_bf16 v[72:75], v[140:143], v[188:191], v[72:75]
	v_mfma_f32_16x16x32_bf16 v[116:119], v[144:147], v[160:163], v[116:119]
	v_mfma_f32_16x16x32_bf16 v[112:115], v[152:155], v[160:163], v[112:115]
	v_mfma_f32_16x16x32_bf16 v[100:103], v[144:147], v[168:171], v[100:103]
	v_mfma_f32_16x16x32_bf16 v[96:99], v[152:155], v[168:171], v[96:99]
	v_mfma_f32_16x16x32_bf16 v[84:87], v[144:147], v[176:179], v[84:87]
	v_mfma_f32_16x16x32_bf16 v[80:83], v[152:155], v[176:179], v[80:83]
	v_mfma_f32_16x16x32_bf16 v[68:71], v[144:147], v[184:187], v[68:71]
	v_mfma_f32_16x16x32_bf16 v[64:67], v[152:155], v[184:187], v[64:67]
	v_mfma_f32_16x16x32_bf16 v[116:119], v[148:151], v[164:167], v[116:119]
	v_mfma_f32_16x16x32_bf16 v[112:115], v[156:159], v[164:167], v[112:115]
	v_mfma_f32_16x16x32_bf16 v[100:103], v[148:151], v[172:175], v[100:103]
	v_mfma_f32_16x16x32_bf16 v[96:99], v[156:159], v[172:175], v[96:99]
	v_mfma_f32_16x16x32_bf16 v[84:87], v[148:151], v[180:183], v[84:87]
	v_mfma_f32_16x16x32_bf16 v[80:83], v[156:159], v[180:183], v[80:83]
	v_mfma_f32_16x16x32_bf16 v[68:71], v[148:151], v[188:191], v[68:71]
	v_mfma_f32_16x16x32_bf16 v[64:67], v[156:159], v[188:191], v[64:67]
	s_barrier
	s_add_i32 s46, s50, s54
	v_lshl_add_u64 v[222:223], v[222:223], 0, s[20:21]
	s_mov_b32 m0, s46
	ds_read_b128 v[160:163], v228 offset:49152
	ds_read_b128 v[164:167], v228 offset:50176
	ds_read_b128 v[168:171], v228 offset:51200
	ds_read_b128 v[172:175], v228 offset:52224
	ds_read_b128 v[176:179], v228 offset:53248
	ds_read_b128 v[180:183], v228 offset:54272
	ds_read_b128 v[184:187], v228 offset:55296
	ds_read_b128 v[188:191], v228 offset:56320
	global_load_lds_dwordx4 v[222:223], off
	s_add_i32 m0, s46, 0x2000
	s_add_u32 s6, s6, 0x40080
	v_lshl_add_u64 v[220:221], v[220:221], 0, s[20:21]
	s_addc_u32 s7, s7, 0
	s_add_i32 s46, s51, s54
	global_load_lds_dwordx4 v[220:221], off
	v_lshl_add_u64 v[220:221], s[6:7], 0, v[196:197]
	s_mov_b32 m0, s46
	v_lshl_add_u64 v[216:217], v[216:217], 0, s[20:21]
	global_load_lds_dwordx4 v[220:221], off
	v_lshl_add_u64 v[220:221], s[6:7], 0, v[200:201]
	s_add_i32 m0, s46, 0x2000
	s_nop 0
	global_load_lds_dwordx4 v[220:221], off
	s_mov_b32 m0, s64
	s_nop 0
	global_load_lds_dwordx4 v[216:217], off
	v_lshl_add_u64 v[216:217], v[218:219], 0, s[20:21]
	s_mov_b32 m0, s65
	s_nop 0
	global_load_lds_dwordx4 v[216:217], off
	s_waitcnt vmcnt(8)
	s_waitcnt lgkmcnt(0)
	s_barrier
	s_waitcnt lgkmcnt(0)
	v_mfma_f32_16x16x32_bf16 v[60:63], v[128:131], v[160:163], v[60:63]
	v_mfma_f32_16x16x32_bf16 v[56:59], v[136:139], v[160:163], v[56:59]
	v_mfma_f32_16x16x32_bf16 v[44:47], v[128:131], v[168:171], v[44:47]
	v_mfma_f32_16x16x32_bf16 v[40:43], v[136:139], v[168:171], v[40:43]
	v_mfma_f32_16x16x32_bf16 v[28:31], v[128:131], v[176:179], v[28:31]
	v_mfma_f32_16x16x32_bf16 v[24:27], v[136:139], v[176:179], v[24:27]
	v_mfma_f32_16x16x32_bf16 v[12:15], v[128:131], v[184:187], v[12:15]
	v_mfma_f32_16x16x32_bf16 v[8:11], v[136:139], v[184:187], v[8:11]
	v_mfma_f32_16x16x32_bf16 v[60:63], v[132:135], v[164:167], v[60:63]
	v_mfma_f32_16x16x32_bf16 v[56:59], v[140:143], v[164:167], v[56:59]
	v_mfma_f32_16x16x32_bf16 v[44:47], v[132:135], v[172:175], v[44:47]
	v_mfma_f32_16x16x32_bf16 v[40:43], v[140:143], v[172:175], v[40:43]
	v_mfma_f32_16x16x32_bf16 v[28:31], v[132:135], v[180:183], v[28:31]
	v_mfma_f32_16x16x32_bf16 v[24:27], v[140:143], v[180:183], v[24:27]
	v_mfma_f32_16x16x32_bf16 v[12:15], v[132:135], v[188:191], v[12:15]
	v_mfma_f32_16x16x32_bf16 v[8:11], v[140:143], v[188:191], v[8:11]
	v_mfma_f32_16x16x32_bf16 v[52:55], v[144:147], v[160:163], v[52:55]
	v_mfma_f32_16x16x32_bf16 v[48:51], v[152:155], v[160:163], v[48:51]
	v_mfma_f32_16x16x32_bf16 v[36:39], v[144:147], v[168:171], v[36:39]
	v_mfma_f32_16x16x32_bf16 v[32:35], v[152:155], v[168:171], v[32:35]
	v_mfma_f32_16x16x32_bf16 v[20:23], v[144:147], v[176:179], v[20:23]
	v_mfma_f32_16x16x32_bf16 v[16:19], v[152:155], v[176:179], v[16:19]
	v_mfma_f32_16x16x32_bf16 v[4:7], v[144:147], v[184:187], v[4:7]
	v_mfma_f32_16x16x32_bf16 v[0:3], v[152:155], v[184:187], v[0:3]
	v_mfma_f32_16x16x32_bf16 v[52:55], v[148:151], v[164:167], v[52:55]
	v_mfma_f32_16x16x32_bf16 v[48:51], v[156:159], v[164:167], v[48:51]
	v_mfma_f32_16x16x32_bf16 v[36:39], v[148:151], v[172:175], v[36:39]
	v_mfma_f32_16x16x32_bf16 v[32:35], v[156:159], v[172:175], v[32:35]
	v_mfma_f32_16x16x32_bf16 v[20:23], v[148:151], v[180:183], v[20:23]
	v_mfma_f32_16x16x32_bf16 v[16:19], v[156:159], v[180:183], v[16:19]
	v_mfma_f32_16x16x32_bf16 v[4:7], v[148:151], v[188:191], v[4:7]
	v_mfma_f32_16x16x32_bf16 v[0:3], v[156:159], v[188:191], v[0:3]
	s_barrier
	s_add_i32 s83, s83, 2
	s_add_u32 s0, s0, 0x100
	s_addc_u32 s1, s1, 0
	s_add_u32 s81, s81, 0x100
	s_addc_u32 s82, s82, 0
	s_cmp_gt_u32 s83, 13
	s_cbranch_scc1 .LBB0_366

.LBB0_362:
	s_add_u32 s48, s0, 0xfffc0080
	s_addc_u32 s49, s1, -1
	s_waitcnt lgkmcnt(0)
	s_and_b64 s[6:7], s[6:7], exec
	s_cselect_b32 s49, s12, s49
	s_cselect_b32 s48, s37, s48
	s_cselect_b32 s7, s79, s82
	s_cselect_b32 s6, s80, s81
	s_barrier
	s_waitcnt lgkmcnt(0)
	v_mfma_f32_16x16x32_bf16 v[124:127], v[144:147], v[184:187], v[124:127]
	v_mfma_f32_16x16x32_bf16 v[120:123], v[152:155], v[184:187], v[120:123]
	v_mfma_f32_16x16x32_bf16 v[108:111], v[144:147], v[176:179], v[108:111]
	v_mfma_f32_16x16x32_bf16 v[104:107], v[152:155], v[176:179], v[104:107]
	v_mfma_f32_16x16x32_bf16 v[92:95], v[144:147], v[168:171], v[92:95]
	v_mfma_f32_16x16x32_bf16 v[88:91], v[152:155], v[168:171], v[88:91]
	v_mfma_f32_16x16x32_bf16 v[76:79], v[144:147], v[160:163], v[76:79]
	v_mfma_f32_16x16x32_bf16 v[72:75], v[152:155], v[160:163], v[72:75]
	v_mfma_f32_16x16x32_bf16 v[124:127], v[148:151], v[188:191], v[124:127]
	v_mfma_f32_16x16x32_bf16 v[120:123], v[156:159], v[188:191], v[120:123]
	v_mfma_f32_16x16x32_bf16 v[108:111], v[148:151], v[180:183], v[108:111]
	v_mfma_f32_16x16x32_bf16 v[104:107], v[156:159], v[180:183], v[104:107]
	v_mfma_f32_16x16x32_bf16 v[92:95], v[148:151], v[172:175], v[92:95]
	v_mfma_f32_16x16x32_bf16 v[88:91], v[156:159], v[172:175], v[88:91]
	v_mfma_f32_16x16x32_bf16 v[76:79], v[148:151], v[164:167], v[76:79]
	v_mfma_f32_16x16x32_bf16 v[72:75], v[156:159], v[164:167], v[72:75]
	v_mfma_f32_16x16x32_bf16 v[116:119], v[128:131], v[184:187], v[116:119]
	v_mfma_f32_16x16x32_bf16 v[112:115], v[136:139], v[184:187], v[112:115]
	v_mfma_f32_16x16x32_bf16 v[100:103], v[128:131], v[176:179], v[100:103]
	v_mfma_f32_16x16x32_bf16 v[96:99], v[136:139], v[176:179], v[96:99]
	v_mfma_f32_16x16x32_bf16 v[84:87], v[128:131], v[168:171], v[84:87]
	v_mfma_f32_16x16x32_bf16 v[80:83], v[136:139], v[168:171], v[80:83]
	v_mfma_f32_16x16x32_bf16 v[68:71], v[128:131], v[160:163], v[68:71]
	v_mfma_f32_16x16x32_bf16 v[64:67], v[136:139], v[160:163], v[64:67]
	v_mfma_f32_16x16x32_bf16 v[116:119], v[132:135], v[188:191], v[116:119]
	v_mfma_f32_16x16x32_bf16 v[112:115], v[140:143], v[188:191], v[112:115]
	v_mfma_f32_16x16x32_bf16 v[100:103], v[132:135], v[180:183], v[100:103]
	v_mfma_f32_16x16x32_bf16 v[96:99], v[140:143], v[180:183], v[96:99]
	v_mfma_f32_16x16x32_bf16 v[84:87], v[132:135], v[172:175], v[84:87]
	v_mfma_f32_16x16x32_bf16 v[80:83], v[140:143], v[172:175], v[80:83]
	v_mfma_f32_16x16x32_bf16 v[68:71], v[132:135], v[164:167], v[68:71]
	v_mfma_f32_16x16x32_bf16 v[64:67], v[140:143], v[164:167], v[64:67]
	s_barrier
	s_mov_b32 m0, s55
	v_lshl_add_u64 v[222:223], s[6:7], 0, v[196:197]
	s_add_u32 s50, s6, 0x40000
	ds_read_b128 v[184:187], v228 offset:16384
	ds_read_b128 v[188:191], v228 offset:17408
	ds_read_b128 v[176:179], v228 offset:18432
	ds_read_b128 v[180:183], v228 offset:19456
	ds_read_b128 v[168:171], v228 offset:20480
	ds_read_b128 v[172:175], v228 offset:21504
	ds_read_b128 v[160:163], v228 offset:22528
	ds_read_b128 v[164:167], v228 offset:23552
	global_load_lds_dwordx4 v[222:223], off
	v_lshl_add_u64 v[220:221], s[6:7], 0, v[200:201]
	s_mov_b32 m0, s56
	s_addc_u32 s51, s7, 0
	global_load_lds_dwordx4 v[220:221], off
	v_lshl_add_u64 v[216:217], s[50:51], 0, v[196:197]
	s_mov_b32 m0, s57
	v_lshl_add_u64 v[218:219], s[48:49], 0, v[198:199]
	global_load_lds_dwordx4 v[216:217], off
	v_lshl_add_u64 v[216:217], s[50:51], 0, v[200:201]
	s_mov_b32 m0, s58
	s_mov_b64 s[50:51], -1
	global_load_lds_dwordx4 v[216:217], off
	v_lshl_add_u64 v[216:217], s[48:49], 0, v[194:195]
	s_mov_b32 m0, s45
	s_and_b64 vcc, exec, s[46:47]
	global_load_lds_dwordx4 v[216:217], off
	s_mov_b32 m0, s59
	s_nop 0
	global_load_lds_dwordx4 v[218:219], off
	s_cbranch_vccz .LBB0_364
	s_waitcnt vmcnt(8)
	s_mov_b64 s[50:51], 0

.LBB0_490:
	ds_read_b128 v[84:87], v80
	ds_read_b128 v[88:91], v80 offset:1024
	ds_read_b128 v[92:95], v80 offset:2048
	ds_read_b128 v[96:99], v80 offset:3072
	s_add_u32 s38, s36, 0xfffd8080
	s_addc_u32 s39, s37, -1
	s_cmp_eq_u32 s78, 4
	s_cselect_b32 s41, s27, s39
	s_cselect_b32 s40, s26, s38
	s_cselect_b32 s39, s68, s77
	s_cselect_b32 s38, s69, s76
	s_mov_b32 m0, s59
	v_lshl_add_u64 v[124:125], s[36:37], 0, v[76:77]
	ds_read_b128 v[100:103], v81
	ds_read_b128 v[104:107], v81 offset:1024
	ds_read_b128 v[108:111], v81 offset:2048
	ds_read_b128 v[112:115], v81 offset:3072
	ds_read_b128 v[116:119], v81 offset:4096
	ds_read_b128 v[120:123], v81 offset:5120
	ds_read_b128 v[128:131], v81 offset:6144
	ds_read_b128 v[132:135], v81 offset:7168
	global_load_lds_dwordx4 v[124:125], off
	v_lshl_add_u64 v[124:125], s[36:37], 0, v[78:79]
	s_mov_b32 m0, s60
	s_nop 0
	global_load_lds_dwordx4 v[124:125], off
	s_waitcnt vmcnt(8)
	s_waitcnt lgkmcnt(0)
	s_barrier
	s_waitcnt lgkmcnt(0)
	v_mfma_f32_16x16x32_bf16 v[60:63], v[84:87], v[100:103], v[60:63]
	v_mfma_f32_16x16x32_bf16 v[56:59], v[92:95], v[100:103], v[56:59]
	v_mfma_f32_16x16x32_bf16 v[52:55], v[84:87], v[108:111], v[52:55]
	v_mfma_f32_16x16x32_bf16 v[48:51], v[92:95], v[108:111], v[48:51]
	v_mfma_f32_16x16x32_bf16 v[44:47], v[84:87], v[116:119], v[44:47]
	v_mfma_f32_16x16x32_bf16 v[40:43], v[92:95], v[116:119], v[40:43]
	v_mfma_f32_16x16x32_bf16 v[36:39], v[84:87], v[128:131], v[36:39]
	v_mfma_f32_16x16x32_bf16 v[32:35], v[92:95], v[128:131], v[32:35]
	v_mfma_f32_16x16x32_bf16 v[60:63], v[88:91], v[104:107], v[60:63]
	v_mfma_f32_16x16x32_bf16 v[56:59], v[96:99], v[104:107], v[56:59]
	v_mfma_f32_16x16x32_bf16 v[52:55], v[88:91], v[112:115], v[52:55]
	v_mfma_f32_16x16x32_bf16 v[48:51], v[96:99], v[112:115], v[48:51]
	v_mfma_f32_16x16x32_bf16 v[44:47], v[88:91], v[120:123], v[44:47]
	v_mfma_f32_16x16x32_bf16 v[40:43], v[96:99], v[120:123], v[40:43]
	v_mfma_f32_16x16x32_bf16 v[36:39], v[88:91], v[132:135], v[36:39]
	v_mfma_f32_16x16x32_bf16 v[32:35], v[96:99], v[132:135], v[32:35]
	s_barrier
	s_mov_b32 m0, s61
	v_lshl_add_u64 v[124:125], s[38:39], 0, v[70:71]
	s_add_u32 s80, s38, 0x20000
	ds_read_b128 v[100:103], v81 offset:16384
	ds_read_b128 v[104:107], v81 offset:17408
	ds_read_b128 v[108:111], v81 offset:18432
	ds_read_b128 v[112:115], v81 offset:19456
	ds_read_b128 v[116:119], v81 offset:20480
	ds_read_b128 v[120:123], v81 offset:21504
	ds_read_b128 v[128:131], v81 offset:22528
	ds_read_b128 v[132:135], v81 offset:23552
	global_load_lds_dwordx4 v[124:125], off
	v_lshl_add_u64 v[136:137], s[38:39], 0, v[66:67]
	s_mov_b32 m0, s62
	s_addc_u32 s81, s39, 0
	global_load_lds_dwordx4 v[136:137], off
	v_lshl_add_u64 v[138:139], s[80:81], 0, v[70:71]
	s_mov_b32 m0, s47
	v_lshl_add_u64 v[140:141], s[40:41], 0, v[68:69]
	global_load_lds_dwordx4 v[138:139], off
	v_lshl_add_u64 v[138:139], s[80:81], 0, v[66:67]
	s_mov_b32 m0, s48
	s_nop 0
	global_load_lds_dwordx4 v[138:139], off
	v_lshl_add_u64 v[138:139], s[40:41], 0, v[72:73]
	s_mov_b32 m0, s46
	s_nop 0
	global_load_lds_dwordx4 v[138:139], off
	s_mov_b32 m0, s49
	s_nop 0
	global_load_lds_dwordx4 v[140:141], off
	s_waitcnt vmcnt(8)
	s_waitcnt lgkmcnt(0)
	s_barrier
	s_waitcnt lgkmcnt(0)
	v_mfma_f32_16x16x32_bf16 v[28:31], v[84:87], v[100:103], v[28:31]
	v_mfma_f32_16x16x32_bf16 v[24:27], v[92:95], v[100:103], v[24:27]
	v_mfma_f32_16x16x32_bf16 v[20:23], v[84:87], v[108:111], v[20:23]
	v_mfma_f32_16x16x32_bf16 v[16:19], v[92:95], v[108:111], v[16:19]
	v_mfma_f32_16x16x32_bf16 v[12:15], v[84:87], v[116:119], v[12:15]
	v_mfma_f32_16x16x32_bf16 v[8:11], v[92:95], v[116:119], v[8:11]
	v_mfma_f32_16x16x32_bf16 v[4:7], v[84:87], v[128:131], v[4:7]
	v_mfma_f32_16x16x32_bf16 v[0:3], v[92:95], v[128:131], v[0:3]
	v_mfma_f32_16x16x32_bf16 v[28:31], v[88:91], v[104:107], v[28:31]
	v_mfma_f32_16x16x32_bf16 v[24:27], v[96:99], v[104:107], v[24:27]
	v_mfma_f32_16x16x32_bf16 v[20:23], v[88:91], v[112:115], v[20:23]
	v_mfma_f32_16x16x32_bf16 v[16:19], v[96:99], v[112:115], v[16:19]
	v_mfma_f32_16x16x32_bf16 v[12:15], v[88:91], v[120:123], v[12:15]
	v_mfma_f32_16x16x32_bf16 v[8:11], v[96:99], v[120:123], v[8:11]
	v_mfma_f32_16x16x32_bf16 v[4:7], v[88:91], v[132:135], v[4:7]
	v_mfma_f32_16x16x32_bf16 v[0:3], v[96:99], v[132:135], v[0:3]
	s_barrier
	ds_read_b128 v[84:87], v82
	ds_read_b128 v[88:91], v82 offset:1024
	ds_read_b128 v[92:95], v82 offset:2048
	ds_read_b128 v[96:99], v82 offset:3072
	s_add_u32 s40, s40, 0x28000
	s_addc_u32 s41, s41, 0
	s_mov_b32 m0, s50
	v_lshl_add_u64 v[142:143], s[40:41], 0, v[72:73]
	ds_read_b128 v[100:103], v81 offset:32768
	ds_read_b128 v[104:107], v81 offset:33792
	ds_read_b128 v[108:111], v81 offset:34816
	ds_read_b128 v[112:115], v81 offset:35840
	ds_read_b128 v[116:119], v81 offset:36864
	ds_read_b128 v[120:123], v81 offset:37888
	ds_read_b128 v[128:131], v81 offset:38912
	ds_read_b128 v[132:135], v81 offset:39936
	global_load_lds_dwordx4 v[142:143], off
	v_lshl_add_u64 v[142:143], s[40:41], 0, v[68:69]
	s_mov_b32 m0, s51
	s_nop 0
	global_load_lds_dwordx4 v[142:143], off
	s_waitcnt vmcnt(8)
	s_waitcnt lgkmcnt(0)
	s_barrier
	s_waitcnt lgkmcnt(0)
	v_mfma_f32_16x16x32_bf16 v[60:63], v[84:87], v[100:103], v[60:63]
	v_mfma_f32_16x16x32_bf16 v[56:59], v[92:95], v[100:103], v[56:59]
	v_mfma_f32_16x16x32_bf16 v[52:55], v[84:87], v[108:111], v[52:55]
	v_mfma_f32_16x16x32_bf16 v[48:51], v[92:95], v[108:111], v[48:51]
	v_mfma_f32_16x16x32_bf16 v[44:47], v[84:87], v[116:119], v[44:47]
	v_mfma_f32_16x16x32_bf16 v[40:43], v[92:95], v[116:119], v[40:43]
	v_mfma_f32_16x16x32_bf16 v[36:39], v[84:87], v[128:131], v[36:39]
	v_mfma_f32_16x16x32_bf16 v[32:35], v[92:95], v[128:131], v[32:35]
	v_mfma_f32_16x16x32_bf16 v[60:63], v[88:91], v[104:107], v[60:63]
	v_mfma_f32_16x16x32_bf16 v[56:59], v[96:99], v[104:107], v[56:59]
	v_mfma_f32_16x16x32_bf16 v[52:55], v[88:91], v[112:115], v[52:55]
	v_mfma_f32_16x16x32_bf16 v[48:51], v[96:99], v[112:115], v[48:51]
	v_mfma_f32_16x16x32_bf16 v[44:47], v[88:91], v[120:123], v[44:47]
	v_mfma_f32_16x16x32_bf16 v[40:43], v[96:99], v[120:123], v[40:43]
	v_mfma_f32_16x16x32_bf16 v[36:39], v[88:91], v[132:135], v[36:39]
	v_mfma_f32_16x16x32_bf16 v[32:35], v[96:99], v[132:135], v[32:35]
	s_barrier
	s_mov_b32 m0, s63
	v_lshl_add_u64 v[124:125], v[124:125], 0, s[8:9]
	s_add_u32 s38, s38, 0x20080
	ds_read_b128 v[100:103], v81 offset:49152
	ds_read_b128 v[104:107], v81 offset:50176
	ds_read_b128 v[108:111], v81 offset:51200
	ds_read_b128 v[112:115], v81 offset:52224
	ds_read_b128 v[116:119], v81 offset:53248
	ds_read_b128 v[120:123], v81 offset:54272
	ds_read_b128 v[128:131], v81 offset:55296
	ds_read_b128 v[132:135], v81 offset:56320
	global_load_lds_dwordx4 v[124:125], off
	v_lshl_add_u64 v[124:125], v[136:137], 0, s[8:9]
	s_mov_b32 m0, s64
	s_addc_u32 s39, s39, 0
	global_load_lds_dwordx4 v[124:125], off
	v_lshl_add_u64 v[124:125], s[38:39], 0, v[70:71]
	s_mov_b32 m0, s57
	s_nop 0
	global_load_lds_dwordx4 v[124:125], off
	v_lshl_add_u64 v[124:125], s[38:39], 0, v[66:67]
	s_mov_b32 m0, s58
	s_nop 0
	global_load_lds_dwordx4 v[124:125], off
	v_lshl_add_u64 v[124:125], v[138:139], 0, s[8:9]
	s_mov_b32 m0, s55
	s_nop 0
	global_load_lds_dwordx4 v[124:125], off
	v_lshl_add_u64 v[124:125], v[140:141], 0, s[8:9]
	s_mov_b32 m0, s56
	s_nop 0
	global_load_lds_dwordx4 v[124:125], off
	s_waitcnt vmcnt(8)
	s_waitcnt lgkmcnt(0)
	s_barrier
	s_waitcnt lgkmcnt(0)
	v_mfma_f32_16x16x32_bf16 v[28:31], v[84:87], v[100:103], v[28:31]
	v_mfma_f32_16x16x32_bf16 v[24:27], v[92:95], v[100:103], v[24:27]
	v_mfma_f32_16x16x32_bf16 v[20:23], v[84:87], v[108:111], v[20:23]
	v_mfma_f32_16x16x32_bf16 v[16:19], v[92:95], v[108:111], v[16:19]
	v_mfma_f32_16x16x32_bf16 v[12:15], v[84:87], v[116:119], v[12:15]
	v_mfma_f32_16x16x32_bf16 v[8:11], v[92:95], v[116:119], v[8:11]
	v_mfma_f32_16x16x32_bf16 v[4:7], v[84:87], v[128:131], v[4:7]
	v_mfma_f32_16x16x32_bf16 v[0:3], v[92:95], v[128:131], v[0:3]
	v_mfma_f32_16x16x32_bf16 v[28:31], v[88:91], v[104:107], v[28:31]
	v_mfma_f32_16x16x32_bf16 v[24:27], v[96:99], v[104:107], v[24:27]
	v_mfma_f32_16x16x32_bf16 v[20:23], v[88:91], v[112:115], v[20:23]
	v_mfma_f32_16x16x32_bf16 v[16:19], v[96:99], v[112:115], v[16:19]
	v_mfma_f32_16x16x32_bf16 v[12:15], v[88:91], v[120:123], v[12:15]
	v_mfma_f32_16x16x32_bf16 v[8:11], v[96:99], v[120:123], v[8:11]
	v_mfma_f32_16x16x32_bf16 v[4:7], v[88:91], v[132:135], v[4:7]
	v_mfma_f32_16x16x32_bf16 v[0:3], v[96:99], v[132:135], v[0:3]
	s_barrier
	s_add_i32 s78, s78, 2
	s_add_u32 s36, s36, 0x100
	s_addc_u32 s37, s37, 0
	s_add_u32 s76, s76, 0x100
	s_addc_u32 s77, s77, 0
	s_cmp_gt_u32 s78, 5
	s_cbranch_scc0 .LBB0_490
	s_and_b64 vcc, exec, s[12:13]
	s_cbranch_vccz .LBB0_493
	s_barrier

.LBB0_575:
	ds_read_b128 v[142:145], v149
	ds_read_b128 v[152:155], v149 offset:1024
	ds_read_b128 v[162:165], v149 offset:2048
	ds_read_b128 v[166:169], v149 offset:3072
	ds_read_b128 v[170:173], v150
	ds_read_b128 v[174:177], v150 offset:1024
	ds_read_b128 v[178:181], v150 offset:2048
	ds_read_b128 v[182:185], v150 offset:3072
	s_add_u32 s26, s24, 0xfffd8080
	s_addc_u32 s27, s25, -1
	s_cmp_eq_u32 s55, 6
	s_cselect_b32 s29, s19, s27
	s_cselect_b32 s28, s18, s26
	s_cselect_b32 s27, s21, s54
	s_cselect_b32 s26, s20, s53
	s_mov_b32 m0, s46
	v_lshl_add_u64 v[190:191], s[24:25], 0, v[138:139]
	ds_read_b128 v[186:189], v151
	ds_read_b128 v[194:197], v151 offset:1024
	ds_read_b128 v[198:201], v151 offset:2048
	ds_read_b128 v[202:205], v151 offset:3072
	ds_read_b128 v[206:209], v151 offset:4096
	ds_read_b128 v[210:213], v151 offset:5120
	ds_read_b128 v[214:217], v151 offset:6144
	ds_read_b128 v[218:221], v151 offset:7168
	global_load_lds_dwordx4 v[190:191], off
	v_lshl_add_u64 v[190:191], s[24:25], 0, v[140:141]
	s_mov_b32 m0, s47
	s_nop 0
	global_load_lds_dwordx4 v[190:191], off
	s_waitcnt vmcnt(8)
	s_waitcnt lgkmcnt(0)
	s_barrier
	s_waitcnt lgkmcnt(0)
	v_mfma_f32_16x16x32_bf16 v[124:127], v[142:145], v[186:189], v[124:127]
	v_mfma_f32_16x16x32_bf16 v[120:123], v[162:165], v[186:189], v[120:123]
	v_mfma_f32_16x16x32_bf16 v[108:111], v[142:145], v[198:201], v[108:111]
	v_mfma_f32_16x16x32_bf16 v[104:107], v[162:165], v[198:201], v[104:107]
	v_mfma_f32_16x16x32_bf16 v[92:95], v[142:145], v[206:209], v[92:95]
	v_mfma_f32_16x16x32_bf16 v[88:91], v[162:165], v[206:209], v[88:91]
	v_mfma_f32_16x16x32_bf16 v[76:79], v[142:145], v[214:217], v[76:79]
	v_mfma_f32_16x16x32_bf16 v[72:75], v[162:165], v[214:217], v[72:75]
	v_mfma_f32_16x16x32_bf16 v[124:127], v[152:155], v[194:197], v[124:127]
	v_mfma_f32_16x16x32_bf16 v[120:123], v[166:169], v[194:197], v[120:123]
	v_mfma_f32_16x16x32_bf16 v[108:111], v[152:155], v[202:205], v[108:111]
	v_mfma_f32_16x16x32_bf16 v[104:107], v[166:169], v[202:205], v[104:107]
	v_mfma_f32_16x16x32_bf16 v[92:95], v[152:155], v[210:213], v[92:95]
	v_mfma_f32_16x16x32_bf16 v[88:91], v[166:169], v[210:213], v[88:91]
	v_mfma_f32_16x16x32_bf16 v[76:79], v[152:155], v[218:221], v[76:79]
	v_mfma_f32_16x16x32_bf16 v[72:75], v[166:169], v[218:221], v[72:75]
	v_mfma_f32_16x16x32_bf16 v[116:119], v[170:173], v[186:189], v[116:119]
	v_mfma_f32_16x16x32_bf16 v[112:115], v[178:181], v[186:189], v[112:115]
	v_mfma_f32_16x16x32_bf16 v[100:103], v[170:173], v[198:201], v[100:103]
	v_mfma_f32_16x16x32_bf16 v[96:99], v[178:181], v[198:201], v[96:99]
	v_mfma_f32_16x16x32_bf16 v[84:87], v[170:173], v[206:209], v[84:87]
	v_mfma_f32_16x16x32_bf16 v[80:83], v[178:181], v[206:209], v[80:83]
	v_mfma_f32_16x16x32_bf16 v[68:71], v[170:173], v[214:217], v[68:71]
	v_mfma_f32_16x16x32_bf16 v[64:67], v[178:181], v[214:217], v[64:67]
	v_mfma_f32_16x16x32_bf16 v[116:119], v[174:177], v[194:197], v[116:119]
	v_mfma_f32_16x16x32_bf16 v[112:115], v[182:185], v[194:197], v[112:115]
	v_mfma_f32_16x16x32_bf16 v[100:103], v[174:177], v[202:205], v[100:103]
	v_mfma_f32_16x16x32_bf16 v[96:99], v[182:185], v[202:205], v[96:99]
	v_mfma_f32_16x16x32_bf16 v[84:87], v[174:177], v[210:213], v[84:87]
	v_mfma_f32_16x16x32_bf16 v[80:83], v[182:185], v[210:213], v[80:83]
	v_mfma_f32_16x16x32_bf16 v[68:71], v[174:177], v[218:221], v[68:71]
	v_mfma_f32_16x16x32_bf16 v[64:67], v[182:185], v[218:221], v[64:67]
	s_barrier
	s_mov_b32 m0, s48
	v_lshl_add_u64 v[190:191], s[26:27], 0, v[132:133]
	ds_read_b128 v[186:189], v151 offset:16384
	ds_read_b128 v[194:197], v151 offset:17408
	ds_read_b128 v[198:201], v151 offset:18432
	ds_read_b128 v[202:205], v151 offset:19456
	ds_read_b128 v[206:209], v151 offset:20480
	ds_read_b128 v[210:213], v151 offset:21504
	ds_read_b128 v[214:217], v151 offset:22528
	ds_read_b128 v[218:221], v151 offset:23552
	global_load_lds_dwordx4 v[190:191], off
	s_add_i32 m0, s48, 0x2000
	s_add_u32 s56, s26, 0x28000
	v_lshl_add_u64 v[222:223], s[26:27], 0, v[128:129]
	s_addc_u32 s57, s27, 0
	s_add_i32 s58, s44, s31
	global_load_lds_dwordx4 v[222:223], off
	v_lshl_add_u64 v[224:225], s[56:57], 0, v[132:133]
	s_mov_b32 m0, s58
	v_lshl_add_u64 v[226:227], s[28:29], 0, v[130:131]
	global_load_lds_dwordx4 v[224:225], off
	v_lshl_add_u64 v[224:225], s[56:57], 0, v[128:129]
	s_add_i32 m0, s58, 0x2000
	s_nop 0
	global_load_lds_dwordx4 v[224:225], off
	v_lshl_add_u64 v[224:225], s[28:29], 0, v[134:135]
	s_mov_b32 m0, s36
	s_nop 0
	global_load_lds_dwordx4 v[224:225], off
	s_mov_b32 m0, s37
	s_nop 0
	global_load_lds_dwordx4 v[226:227], off
	s_waitcnt vmcnt(8)
	s_waitcnt lgkmcnt(0)
	s_barrier
	s_waitcnt lgkmcnt(0)
	v_mfma_f32_16x16x32_bf16 v[60:63], v[142:145], v[186:189], v[60:63]
	v_mfma_f32_16x16x32_bf16 v[56:59], v[162:165], v[186:189], v[56:59]
	v_mfma_f32_16x16x32_bf16 v[44:47], v[142:145], v[198:201], v[44:47]
	v_mfma_f32_16x16x32_bf16 v[40:43], v[162:165], v[198:201], v[40:43]
	v_mfma_f32_16x16x32_bf16 v[28:31], v[142:145], v[206:209], v[28:31]
	v_mfma_f32_16x16x32_bf16 v[24:27], v[162:165], v[206:209], v[24:27]
	v_mfma_f32_16x16x32_bf16 v[12:15], v[142:145], v[214:217], v[12:15]
	v_mfma_f32_16x16x32_bf16 v[8:11], v[162:165], v[214:217], v[8:11]
	v_mfma_f32_16x16x32_bf16 v[60:63], v[152:155], v[194:197], v[60:63]
	v_mfma_f32_16x16x32_bf16 v[56:59], v[166:169], v[194:197], v[56:59]
	v_mfma_f32_16x16x32_bf16 v[44:47], v[152:155], v[202:205], v[44:47]
	v_mfma_f32_16x16x32_bf16 v[40:43], v[166:169], v[202:205], v[40:43]
	v_mfma_f32_16x16x32_bf16 v[28:31], v[152:155], v[210:213], v[28:31]
	v_mfma_f32_16x16x32_bf16 v[24:27], v[166:169], v[210:213], v[24:27]
	v_mfma_f32_16x16x32_bf16 v[12:15], v[152:155], v[218:221], v[12:15]
	v_mfma_f32_16x16x32_bf16 v[8:11], v[166:169], v[218:221], v[8:11]
	v_mfma_f32_16x16x32_bf16 v[52:55], v[170:173], v[186:189], v[52:55]
	v_mfma_f32_16x16x32_bf16 v[48:51], v[178:181], v[186:189], v[48:51]
	v_mfma_f32_16x16x32_bf16 v[36:39], v[170:173], v[198:201], v[36:39]
	v_mfma_f32_16x16x32_bf16 v[32:35], v[178:181], v[198:201], v[32:35]
	v_mfma_f32_16x16x32_bf16 v[20:23], v[170:173], v[206:209], v[20:23]
	v_mfma_f32_16x16x32_bf16 v[16:19], v[178:181], v[206:209], v[16:19]
	v_mfma_f32_16x16x32_bf16 v[4:7], v[170:173], v[214:217], v[4:7]
	v_mfma_f32_16x16x32_bf16 v[0:3], v[178:181], v[214:217], v[0:3]
	v_mfma_f32_16x16x32_bf16 v[52:55], v[174:177], v[194:197], v[52:55]
	v_mfma_f32_16x16x32_bf16 v[48:51], v[182:185], v[194:197], v[48:51]
	v_mfma_f32_16x16x32_bf16 v[36:39], v[174:177], v[202:205], v[36:39]
	v_mfma_f32_16x16x32_bf16 v[32:35], v[182:185], v[202:205], v[32:35]
	v_mfma_f32_16x16x32_bf16 v[20:23], v[174:177], v[210:213], v[20:23]
	v_mfma_f32_16x16x32_bf16 v[16:19], v[182:185], v[210:213], v[16:19]
	v_mfma_f32_16x16x32_bf16 v[4:7], v[174:177], v[218:221], v[4:7]
	v_mfma_f32_16x16x32_bf16 v[0:3], v[182:185], v[218:221], v[0:3]
	s_barrier
	s_add_i32 s56, 0, 0x18000
	v_add_u32_e32 v136, s56, v146
	s_add_i32 s57, 0, 0x1c000
	ds_read_b128 v[142:145], v136
	ds_read_b128 v[152:155], v136 offset:1024
	ds_read_b128 v[162:165], v136 offset:2048
	ds_read_b128 v[166:169], v136 offset:3072
	v_add_u32_e32 v136, s57, v146
	ds_read_b128 v[170:173], v136
	ds_read_b128 v[174:177], v136 offset:1024
	ds_read_b128 v[178:181], v136 offset:2048
	ds_read_b128 v[182:185], v136 offset:3072
	s_add_u32 s28, s28, 0x28000
	s_addc_u32 s29, s29, 0
	s_mov_b32 m0, s38
	v_lshl_add_u64 v[228:229], s[28:29], 0, v[134:135]
	ds_read_b128 v[186:189], v151 offset:32768
	ds_read_b128 v[194:197], v151 offset:33792
	ds_read_b128 v[198:201], v151 offset:34816
	ds_read_b128 v[202:205], v151 offset:35840
	ds_read_b128 v[206:209], v151 offset:36864
	ds_read_b128 v[210:213], v151 offset:37888
	ds_read_b128 v[214:217], v151 offset:38912
	ds_read_b128 v[218:221], v151 offset:39936
	global_load_lds_dwordx4 v[228:229], off
	v_lshl_add_u64 v[228:229], s[28:29], 0, v[130:131]
	s_mov_b32 m0, s39
	s_nop 0
	global_load_lds_dwordx4 v[228:229], off
	s_waitcnt vmcnt(8)
	s_waitcnt lgkmcnt(0)
	s_barrier
	s_waitcnt lgkmcnt(0)
	v_mfma_f32_16x16x32_bf16 v[124:127], v[142:145], v[186:189], v[124:127]
	v_mfma_f32_16x16x32_bf16 v[120:123], v[162:165], v[186:189], v[120:123]
	v_mfma_f32_16x16x32_bf16 v[108:111], v[142:145], v[198:201], v[108:111]
	v_mfma_f32_16x16x32_bf16 v[104:107], v[162:165], v[198:201], v[104:107]
	v_mfma_f32_16x16x32_bf16 v[92:95], v[142:145], v[206:209], v[92:95]
	v_mfma_f32_16x16x32_bf16 v[88:91], v[162:165], v[206:209], v[88:91]
	v_mfma_f32_16x16x32_bf16 v[76:79], v[142:145], v[214:217], v[76:79]
	v_mfma_f32_16x16x32_bf16 v[72:75], v[162:165], v[214:217], v[72:75]
	v_mfma_f32_16x16x32_bf16 v[124:127], v[152:155], v[194:197], v[124:127]
	v_mfma_f32_16x16x32_bf16 v[120:123], v[166:169], v[194:197], v[120:123]
	v_mfma_f32_16x16x32_bf16 v[108:111], v[152:155], v[202:205], v[108:111]
	v_mfma_f32_16x16x32_bf16 v[104:107], v[166:169], v[202:205], v[104:107]
	v_mfma_f32_16x16x32_bf16 v[92:95], v[152:155], v[210:213], v[92:95]
	v_mfma_f32_16x16x32_bf16 v[88:91], v[166:169], v[210:213], v[88:91]
	v_mfma_f32_16x16x32_bf16 v[76:79], v[152:155], v[218:221], v[76:79]
	v_mfma_f32_16x16x32_bf16 v[72:75], v[166:169], v[218:221], v[72:75]
	v_mfma_f32_16x16x32_bf16 v[116:119], v[170:173], v[186:189], v[116:119]
	v_mfma_f32_16x16x32_bf16 v[112:115], v[178:181], v[186:189], v[112:115]
	v_mfma_f32_16x16x32_bf16 v[100:103], v[170:173], v[198:201], v[100:103]
	v_mfma_f32_16x16x32_bf16 v[96:99], v[178:181], v[198:201], v[96:99]
	v_mfma_f32_16x16x32_bf16 v[84:87], v[170:173], v[206:209], v[84:87]
	v_mfma_f32_16x16x32_bf16 v[80:83], v[178:181], v[206:209], v[80:83]
	v_mfma_f32_16x16x32_bf16 v[68:71], v[170:173], v[214:217], v[68:71]
	v_mfma_f32_16x16x32_bf16 v[64:67], v[178:181], v[214:217], v[64:67]
	v_mfma_f32_16x16x32_bf16 v[116:119], v[174:177], v[194:197], v[116:119]
	v_mfma_f32_16x16x32_bf16 v[112:115], v[182:185], v[194:197], v[112:115]
	v_mfma_f32_16x16x32_bf16 v[100:103], v[174:177], v[202:205], v[100:103]
	v_mfma_f32_16x16x32_bf16 v[96:99], v[182:185], v[202:205], v[96:99]
	v_mfma_f32_16x16x32_bf16 v[84:87], v[174:177], v[210:213], v[84:87]
	v_mfma_f32_16x16x32_bf16 v[80:83], v[182:185], v[210:213], v[80:83]
	v_mfma_f32_16x16x32_bf16 v[68:71], v[174:177], v[218:221], v[68:71]
	v_mfma_f32_16x16x32_bf16 v[64:67], v[182:185], v[218:221], v[64:67]
	s_barrier
	s_add_i32 s28, s56, s31
	v_lshl_add_u64 v[190:191], v[190:191], 0, s[12:13]
	s_mov_b32 m0, s28
	ds_read_b128 v[186:189], v151 offset:49152
	ds_read_b128 v[194:197], v151 offset:50176
	ds_read_b128 v[198:201], v151 offset:51200
	ds_read_b128 v[202:205], v151 offset:52224
	ds_read_b128 v[206:209], v151 offset:53248
	ds_read_b128 v[210:213], v151 offset:54272
	ds_read_b128 v[214:217], v151 offset:55296
	ds_read_b128 v[218:221], v151 offset:56320
	global_load_lds_dwordx4 v[190:191], off
	s_add_i32 m0, s28, 0x2000
	s_add_u32 s26, s26, 0x28080
	v_lshl_add_u64 v[190:191], v[222:223], 0, s[12:13]
	s_addc_u32 s27, s27, 0
	s_add_i32 s28, s57, s31
	global_load_lds_dwordx4 v[190:191], off
	v_lshl_add_u64 v[190:191], s[26:27], 0, v[132:133]
	s_mov_b32 m0, s28
	s_nop 0
	global_load_lds_dwordx4 v[190:191], off
	v_lshl_add_u64 v[190:191], s[26:27], 0, v[128:129]
	s_add_i32 m0, s28, 0x2000
	s_nop 0
	global_load_lds_dwordx4 v[190:191], off
	v_lshl_add_u64 v[190:191], v[224:225], 0, s[12:13]
	s_mov_b32 m0, s42
	s_nop 0
	global_load_lds_dwordx4 v[190:191], off
	v_lshl_add_u64 v[190:191], v[226:227], 0, s[12:13]
	s_mov_b32 m0, s43
	s_nop 0
	global_load_lds_dwordx4 v[190:191], off
	s_waitcnt vmcnt(8)
	s_waitcnt lgkmcnt(0)
	s_barrier
	s_waitcnt lgkmcnt(0)
	v_mfma_f32_16x16x32_bf16 v[60:63], v[142:145], v[186:189], v[60:63]
	v_mfma_f32_16x16x32_bf16 v[56:59], v[162:165], v[186:189], v[56:59]
	v_mfma_f32_16x16x32_bf16 v[44:47], v[142:145], v[198:201], v[44:47]
	v_mfma_f32_16x16x32_bf16 v[40:43], v[162:165], v[198:201], v[40:43]
	v_mfma_f32_16x16x32_bf16 v[28:31], v[142:145], v[206:209], v[28:31]
	v_mfma_f32_16x16x32_bf16 v[24:27], v[162:165], v[206:209], v[24:27]
	v_mfma_f32_16x16x32_bf16 v[12:15], v[142:145], v[214:217], v[12:15]
	v_mfma_f32_16x16x32_bf16 v[8:11], v[162:165], v[214:217], v[8:11]
	v_mfma_f32_16x16x32_bf16 v[60:63], v[152:155], v[194:197], v[60:63]
	v_mfma_f32_16x16x32_bf16 v[56:59], v[166:169], v[194:197], v[56:59]
	v_mfma_f32_16x16x32_bf16 v[44:47], v[152:155], v[202:205], v[44:47]
	v_mfma_f32_16x16x32_bf16 v[40:43], v[166:169], v[202:205], v[40:43]
	v_mfma_f32_16x16x32_bf16 v[28:31], v[152:155], v[210:213], v[28:31]
	v_mfma_f32_16x16x32_bf16 v[24:27], v[166:169], v[210:213], v[24:27]
	v_mfma_f32_16x16x32_bf16 v[12:15], v[152:155], v[218:221], v[12:15]
	v_mfma_f32_16x16x32_bf16 v[8:11], v[166:169], v[218:221], v[8:11]
	v_mfma_f32_16x16x32_bf16 v[52:55], v[170:173], v[186:189], v[52:55]
	v_mfma_f32_16x16x32_bf16 v[48:51], v[178:181], v[186:189], v[48:51]
	v_mfma_f32_16x16x32_bf16 v[36:39], v[170:173], v[198:201], v[36:39]
	v_mfma_f32_16x16x32_bf16 v[32:35], v[178:181], v[198:201], v[32:35]
	v_mfma_f32_16x16x32_bf16 v[20:23], v[170:173], v[206:209], v[20:23]
	v_mfma_f32_16x16x32_bf16 v[16:19], v[178:181], v[206:209], v[16:19]
	v_mfma_f32_16x16x32_bf16 v[4:7], v[170:173], v[214:217], v[4:7]
	v_mfma_f32_16x16x32_bf16 v[0:3], v[178:181], v[214:217], v[0:3]
	v_mfma_f32_16x16x32_bf16 v[52:55], v[174:177], v[194:197], v[52:55]
	v_mfma_f32_16x16x32_bf16 v[48:51], v[182:185], v[194:197], v[48:51]
	v_mfma_f32_16x16x32_bf16 v[36:39], v[174:177], v[202:205], v[36:39]
	v_mfma_f32_16x16x32_bf16 v[32:35], v[182:185], v[202:205], v[32:35]
	v_mfma_f32_16x16x32_bf16 v[20:23], v[174:177], v[210:213], v[20:23]
	v_mfma_f32_16x16x32_bf16 v[16:19], v[182:185], v[210:213], v[16:19]
	v_mfma_f32_16x16x32_bf16 v[4:7], v[174:177], v[218:221], v[4:7]
	v_mfma_f32_16x16x32_bf16 v[0:3], v[182:185], v[218:221], v[0:3]
	s_barrier
	s_add_i32 s55, s55, 2
	s_add_u32 s24, s24, 0x100
	s_addc_u32 s25, s25, 0
	s_add_u32 s53, s53, 0x100
	s_addc_u32 s54, s54, 0
	s_cmp_gt_u32 s55, 7
	s_cbranch_scc0 .LBB0_575
	s_and_b64 vcc, exec, s[14:15]
	s_cbranch_vccz .LBB0_578
	s_barrier

.LBB0_661:
	ds_read_b128 v[142:145], v149
	ds_read_b128 v[152:155], v149 offset:1024
	ds_read_b128 v[156:159], v149 offset:2048
	ds_read_b128 v[160:163], v149 offset:3072
	ds_read_b128 v[164:167], v150
	ds_read_b128 v[168:171], v150 offset:1024
	ds_read_b128 v[172:175], v150 offset:2048
	ds_read_b128 v[176:179], v150 offset:3072
	s_add_u32 s28, s26, 0xfffe0080
	s_addc_u32 s29, s27, -1
	s_cmp_eq_u32 s55, 4
	s_cselect_b32 s31, s17, s29
	s_cselect_b32 s30, s51, s28
	s_cselect_b32 s29, s15, s54
	s_cselect_b32 s28, s52, s53
	v_lshl_add_u64 v[214:215], s[26:27], 0, v[136:137]
	s_add_i32 m0, s25, 0xc000
	ds_read_b128 v[180:183], v151
	ds_read_b128 v[184:187], v151 offset:1024
	ds_read_b128 v[188:191], v151 offset:2048
	ds_read_b128 v[194:197], v151 offset:3072
	ds_read_b128 v[198:201], v151 offset:4096
	ds_read_b128 v[202:205], v151 offset:5120
	ds_read_b128 v[206:209], v151 offset:6144
	ds_read_b128 v[210:213], v151 offset:7168
	global_load_lds_dwordx4 v[214:215], off
	v_lshl_add_u64 v[214:215], s[26:27], 0, v[138:139]
	s_add_i32 m0, s25, 0xe000
	s_nop 0
	global_load_lds_dwordx4 v[214:215], off
	s_waitcnt vmcnt(8)
	s_waitcnt lgkmcnt(0)
	s_barrier
	s_waitcnt lgkmcnt(0)
	v_mfma_f32_16x16x32_bf16 v[124:127], v[142:145], v[180:183], v[124:127]
	v_mfma_f32_16x16x32_bf16 v[120:123], v[156:159], v[180:183], v[120:123]
	v_mfma_f32_16x16x32_bf16 v[108:111], v[142:145], v[188:191], v[108:111]
	v_mfma_f32_16x16x32_bf16 v[104:107], v[156:159], v[188:191], v[104:107]
	v_mfma_f32_16x16x32_bf16 v[92:95], v[142:145], v[198:201], v[92:95]
	v_mfma_f32_16x16x32_bf16 v[88:91], v[156:159], v[198:201], v[88:91]
	v_mfma_f32_16x16x32_bf16 v[76:79], v[142:145], v[206:209], v[76:79]
	v_mfma_f32_16x16x32_bf16 v[72:75], v[156:159], v[206:209], v[72:75]
	v_mfma_f32_16x16x32_bf16 v[124:127], v[152:155], v[184:187], v[124:127]
	v_mfma_f32_16x16x32_bf16 v[120:123], v[160:163], v[184:187], v[120:123]
	v_mfma_f32_16x16x32_bf16 v[108:111], v[152:155], v[194:197], v[108:111]
	v_mfma_f32_16x16x32_bf16 v[104:107], v[160:163], v[194:197], v[104:107]
	v_mfma_f32_16x16x32_bf16 v[92:95], v[152:155], v[202:205], v[92:95]
	v_mfma_f32_16x16x32_bf16 v[88:91], v[160:163], v[202:205], v[88:91]
	v_mfma_f32_16x16x32_bf16 v[76:79], v[152:155], v[210:213], v[76:79]
	v_mfma_f32_16x16x32_bf16 v[72:75], v[160:163], v[210:213], v[72:75]
	v_mfma_f32_16x16x32_bf16 v[116:119], v[164:167], v[180:183], v[116:119]
	v_mfma_f32_16x16x32_bf16 v[112:115], v[172:175], v[180:183], v[112:115]
	v_mfma_f32_16x16x32_bf16 v[100:103], v[164:167], v[188:191], v[100:103]
	v_mfma_f32_16x16x32_bf16 v[96:99], v[172:175], v[188:191], v[96:99]
	v_mfma_f32_16x16x32_bf16 v[84:87], v[164:167], v[198:201], v[84:87]
	v_mfma_f32_16x16x32_bf16 v[80:83], v[172:175], v[198:201], v[80:83]
	v_mfma_f32_16x16x32_bf16 v[68:71], v[164:167], v[206:209], v[68:71]
	v_mfma_f32_16x16x32_bf16 v[64:67], v[172:175], v[206:209], v[64:67]
	v_mfma_f32_16x16x32_bf16 v[116:119], v[168:171], v[184:187], v[116:119]
	v_mfma_f32_16x16x32_bf16 v[112:115], v[176:179], v[184:187], v[112:115]
	v_mfma_f32_16x16x32_bf16 v[100:103], v[168:171], v[194:197], v[100:103]
	v_mfma_f32_16x16x32_bf16 v[96:99], v[176:179], v[194:197], v[96:99]
	v_mfma_f32_16x16x32_bf16 v[84:87], v[168:171], v[202:205], v[84:87]
	v_mfma_f32_16x16x32_bf16 v[80:83], v[176:179], v[202:205], v[80:83]
	v_mfma_f32_16x16x32_bf16 v[68:71], v[168:171], v[210:213], v[68:71]
	v_mfma_f32_16x16x32_bf16 v[64:67], v[176:179], v[210:213], v[64:67]
	s_barrier
	s_add_i32 s56, s48, s37
	v_lshl_add_u64 v[214:215], s[28:29], 0, v[130:131]
	s_mov_b32 m0, s56
	ds_read_b128 v[180:183], v151 offset:16384
	ds_read_b128 v[184:187], v151 offset:17408
	ds_read_b128 v[188:191], v151 offset:18432
	ds_read_b128 v[194:197], v151 offset:19456
	ds_read_b128 v[198:201], v151 offset:20480
	ds_read_b128 v[202:205], v151 offset:21504
	ds_read_b128 v[206:209], v151 offset:22528
	ds_read_b128 v[210:213], v151 offset:23552
	global_load_lds_dwordx4 v[214:215], off
	s_add_i32 m0, s56, 0x2000
	s_add_u32 s56, s28, 0x20000
	v_lshl_add_u64 v[216:217], s[28:29], 0, v[134:135]
	s_addc_u32 s57, s29, 0
	s_add_i32 s58, s49, s37
	global_load_lds_dwordx4 v[216:217], off
	v_lshl_add_u64 v[218:219], s[56:57], 0, v[130:131]
	s_mov_b32 m0, s58
	v_lshl_add_u64 v[220:221], s[30:31], 0, v[132:133]
	global_load_lds_dwordx4 v[218:219], off
	v_lshl_add_u64 v[218:219], s[56:57], 0, v[134:135]
	s_add_i32 m0, s58, 0x2000
	s_nop 0
	global_load_lds_dwordx4 v[218:219], off
	v_lshl_add_u64 v[218:219], s[30:31], 0, v[128:129]
	s_mov_b32 m0, s25
	s_nop 0
	global_load_lds_dwordx4 v[218:219], off
	s_mov_b32 m0, s40
	s_nop 0
	global_load_lds_dwordx4 v[220:221], off
	s_waitcnt vmcnt(8)
	s_waitcnt lgkmcnt(0)
	s_barrier
	s_waitcnt lgkmcnt(0)
	v_mfma_f32_16x16x32_bf16 v[60:63], v[142:145], v[180:183], v[60:63]
	v_mfma_f32_16x16x32_bf16 v[56:59], v[156:159], v[180:183], v[56:59]
	v_mfma_f32_16x16x32_bf16 v[44:47], v[142:145], v[188:191], v[44:47]
	v_mfma_f32_16x16x32_bf16 v[40:43], v[156:159], v[188:191], v[40:43]
	v_mfma_f32_16x16x32_bf16 v[28:31], v[142:145], v[198:201], v[28:31]
	v_mfma_f32_16x16x32_bf16 v[24:27], v[156:159], v[198:201], v[24:27]
	v_mfma_f32_16x16x32_bf16 v[12:15], v[142:145], v[206:209], v[12:15]
	v_mfma_f32_16x16x32_bf16 v[8:11], v[156:159], v[206:209], v[8:11]
	v_mfma_f32_16x16x32_bf16 v[60:63], v[152:155], v[184:187], v[60:63]
	v_mfma_f32_16x16x32_bf16 v[56:59], v[160:163], v[184:187], v[56:59]
	v_mfma_f32_16x16x32_bf16 v[44:47], v[152:155], v[194:197], v[44:47]
	v_mfma_f32_16x16x32_bf16 v[40:43], v[160:163], v[194:197], v[40:43]
	v_mfma_f32_16x16x32_bf16 v[28:31], v[152:155], v[202:205], v[28:31]
	v_mfma_f32_16x16x32_bf16 v[24:27], v[160:163], v[202:205], v[24:27]
	v_mfma_f32_16x16x32_bf16 v[12:15], v[152:155], v[210:213], v[12:15]
	v_mfma_f32_16x16x32_bf16 v[8:11], v[160:163], v[210:213], v[8:11]
	v_mfma_f32_16x16x32_bf16 v[52:55], v[164:167], v[180:183], v[52:55]
	v_mfma_f32_16x16x32_bf16 v[48:51], v[172:175], v[180:183], v[48:51]
	v_mfma_f32_16x16x32_bf16 v[36:39], v[164:167], v[188:191], v[36:39]
	v_mfma_f32_16x16x32_bf16 v[32:35], v[172:175], v[188:191], v[32:35]
	v_mfma_f32_16x16x32_bf16 v[20:23], v[164:167], v[198:201], v[20:23]
	v_mfma_f32_16x16x32_bf16 v[16:19], v[172:175], v[198:201], v[16:19]
	v_mfma_f32_16x16x32_bf16 v[4:7], v[164:167], v[206:209], v[4:7]
	v_mfma_f32_16x16x32_bf16 v[0:3], v[172:175], v[206:209], v[0:3]
	v_mfma_f32_16x16x32_bf16 v[52:55], v[168:171], v[184:187], v[52:55]
	v_mfma_f32_16x16x32_bf16 v[48:51], v[176:179], v[184:187], v[48:51]
	v_mfma_f32_16x16x32_bf16 v[36:39], v[168:171], v[194:197], v[36:39]
	v_mfma_f32_16x16x32_bf16 v[32:35], v[176:179], v[194:197], v[32:35]
	v_mfma_f32_16x16x32_bf16 v[20:23], v[168:171], v[202:205], v[20:23]
	v_mfma_f32_16x16x32_bf16 v[16:19], v[176:179], v[202:205], v[16:19]
	v_mfma_f32_16x16x32_bf16 v[4:7], v[168:171], v[210:213], v[4:7]
	v_mfma_f32_16x16x32_bf16 v[0:3], v[176:179], v[210:213], v[0:3]
	s_barrier
	s_add_i32 s56, 0, 0x18000
	s_add_i32 s57, 0, 0x1c000
	v_add_u32_e32 v160, s56, v147
	v_add_u32_e32 v176, s57, v147
	ds_read_b128 v[142:145], v160
	ds_read_b128 v[152:155], v160 offset:1024
	ds_read_b128 v[156:159], v160 offset:2048
	ds_read_b128 v[160:163], v160 offset:3072
	ds_read_b128 v[164:167], v176
	ds_read_b128 v[168:171], v176 offset:1024
	ds_read_b128 v[172:175], v176 offset:2048
	ds_read_b128 v[176:179], v176 offset:3072
	s_add_u32 s30, s30, 0x20000
	s_addc_u32 s31, s31, 0
	s_mov_b32 m0, s41
	v_lshl_add_u64 v[222:223], s[30:31], 0, v[128:129]
	ds_read_b128 v[180:183], v151 offset:32768
	ds_read_b128 v[184:187], v151 offset:33792
	ds_read_b128 v[188:191], v151 offset:34816
	ds_read_b128 v[194:197], v151 offset:35840
	ds_read_b128 v[198:201], v151 offset:36864
	ds_read_b128 v[202:205], v151 offset:37888
	ds_read_b128 v[206:209], v151 offset:38912
	ds_read_b128 v[210:213], v151 offset:39936
	global_load_lds_dwordx4 v[222:223], off
	v_lshl_add_u64 v[222:223], s[30:31], 0, v[132:133]
	s_mov_b32 m0, s42
	s_nop 0
	global_load_lds_dwordx4 v[222:223], off
	s_waitcnt vmcnt(8)
	s_waitcnt lgkmcnt(0)
	s_barrier
	s_waitcnt lgkmcnt(0)
	v_mfma_f32_16x16x32_bf16 v[124:127], v[142:145], v[180:183], v[124:127]
	v_mfma_f32_16x16x32_bf16 v[120:123], v[156:159], v[180:183], v[120:123]
	v_mfma_f32_16x16x32_bf16 v[108:111], v[142:145], v[188:191], v[108:111]
	v_mfma_f32_16x16x32_bf16 v[104:107], v[156:159], v[188:191], v[104:107]
	v_mfma_f32_16x16x32_bf16 v[92:95], v[142:145], v[198:201], v[92:95]
	v_mfma_f32_16x16x32_bf16 v[88:91], v[156:159], v[198:201], v[88:91]
	v_mfma_f32_16x16x32_bf16 v[76:79], v[142:145], v[206:209], v[76:79]
	v_mfma_f32_16x16x32_bf16 v[72:75], v[156:159], v[206:209], v[72:75]
	v_mfma_f32_16x16x32_bf16 v[124:127], v[152:155], v[184:187], v[124:127]
	v_mfma_f32_16x16x32_bf16 v[120:123], v[160:163], v[184:187], v[120:123]
	v_mfma_f32_16x16x32_bf16 v[108:111], v[152:155], v[194:197], v[108:111]
	v_mfma_f32_16x16x32_bf16 v[104:107], v[160:163], v[194:197], v[104:107]
	v_mfma_f32_16x16x32_bf16 v[92:95], v[152:155], v[202:205], v[92:95]
	v_mfma_f32_16x16x32_bf16 v[88:91], v[160:163], v[202:205], v[88:91]
	v_mfma_f32_16x16x32_bf16 v[76:79], v[152:155], v[210:213], v[76:79]
	v_mfma_f32_16x16x32_bf16 v[72:75], v[160:163], v[210:213], v[72:75]
	v_mfma_f32_16x16x32_bf16 v[116:119], v[164:167], v[180:183], v[116:119]
	v_mfma_f32_16x16x32_bf16 v[112:115], v[172:175], v[180:183], v[112:115]
	v_mfma_f32_16x16x32_bf16 v[100:103], v[164:167], v[188:191], v[100:103]
	v_mfma_f32_16x16x32_bf16 v[96:99], v[172:175], v[188:191], v[96:99]
	v_mfma_f32_16x16x32_bf16 v[84:87], v[164:167], v[198:201], v[84:87]
	v_mfma_f32_16x16x32_bf16 v[80:83], v[172:175], v[198:201], v[80:83]
	v_mfma_f32_16x16x32_bf16 v[68:71], v[164:167], v[206:209], v[68:71]
	v_mfma_f32_16x16x32_bf16 v[64:67], v[172:175], v[206:209], v[64:67]
	v_mfma_f32_16x16x32_bf16 v[116:119], v[168:171], v[184:187], v[116:119]
	v_mfma_f32_16x16x32_bf16 v[112:115], v[176:179], v[184:187], v[112:115]
	v_mfma_f32_16x16x32_bf16 v[100:103], v[168:171], v[194:197], v[100:103]
	v_mfma_f32_16x16x32_bf16 v[96:99], v[176:179], v[194:197], v[96:99]
	v_mfma_f32_16x16x32_bf16 v[84:87], v[168:171], v[202:205], v[84:87]
	v_mfma_f32_16x16x32_bf16 v[80:83], v[176:179], v[202:205], v[80:83]
	v_mfma_f32_16x16x32_bf16 v[68:71], v[168:171], v[210:213], v[68:71]
	v_mfma_f32_16x16x32_bf16 v[64:67], v[176:179], v[210:213], v[64:67]
	s_barrier
	s_add_i32 s30, s56, s37
	v_lshl_add_u64 v[214:215], v[214:215], 0, s[8:9]
	s_mov_b32 m0, s30
	ds_read_b128 v[180:183], v151 offset:49152
	ds_read_b128 v[184:187], v151 offset:50176
	ds_read_b128 v[188:191], v151 offset:51200
	ds_read_b128 v[194:197], v151 offset:52224
	ds_read_b128 v[198:201], v151 offset:53248
	ds_read_b128 v[202:205], v151 offset:54272
	ds_read_b128 v[206:209], v151 offset:55296
	ds_read_b128 v[210:213], v151 offset:56320
	global_load_lds_dwordx4 v[214:215], off
	s_add_i32 m0, s30, 0x2000
	s_add_u32 s28, s28, 0x20080
	v_lshl_add_u64 v[214:215], v[216:217], 0, s[8:9]
	s_addc_u32 s29, s29, 0
	s_add_i32 s30, s57, s37
	global_load_lds_dwordx4 v[214:215], off
	v_lshl_add_u64 v[214:215], s[28:29], 0, v[130:131]
	s_mov_b32 m0, s30
	s_nop 0
	global_load_lds_dwordx4 v[214:215], off
	v_lshl_add_u64 v[214:215], s[28:29], 0, v[134:135]
	s_add_i32 m0, s30, 0x2000
	s_nop 0
	global_load_lds_dwordx4 v[214:215], off
	v_lshl_add_u64 v[214:215], v[218:219], 0, s[8:9]
	s_mov_b32 m0, s45
	s_nop 0
	global_load_lds_dwordx4 v[214:215], off
	v_lshl_add_u64 v[214:215], v[220:221], 0, s[8:9]
	s_mov_b32 m0, s46
	s_nop 0
	global_load_lds_dwordx4 v[214:215], off
	s_waitcnt vmcnt(8)
	s_waitcnt lgkmcnt(0)
	s_barrier
	s_waitcnt lgkmcnt(0)
	v_mfma_f32_16x16x32_bf16 v[60:63], v[142:145], v[180:183], v[60:63]
	v_mfma_f32_16x16x32_bf16 v[56:59], v[156:159], v[180:183], v[56:59]
	v_mfma_f32_16x16x32_bf16 v[44:47], v[142:145], v[188:191], v[44:47]
	v_mfma_f32_16x16x32_bf16 v[40:43], v[156:159], v[188:191], v[40:43]
	v_mfma_f32_16x16x32_bf16 v[28:31], v[142:145], v[198:201], v[28:31]
	v_mfma_f32_16x16x32_bf16 v[24:27], v[156:159], v[198:201], v[24:27]
	v_mfma_f32_16x16x32_bf16 v[12:15], v[142:145], v[206:209], v[12:15]
	v_mfma_f32_16x16x32_bf16 v[8:11], v[156:159], v[206:209], v[8:11]
	v_mfma_f32_16x16x32_bf16 v[60:63], v[152:155], v[184:187], v[60:63]
	v_mfma_f32_16x16x32_bf16 v[56:59], v[160:163], v[184:187], v[56:59]
	v_mfma_f32_16x16x32_bf16 v[44:47], v[152:155], v[194:197], v[44:47]
	v_mfma_f32_16x16x32_bf16 v[40:43], v[160:163], v[194:197], v[40:43]
	v_mfma_f32_16x16x32_bf16 v[28:31], v[152:155], v[202:205], v[28:31]
	v_mfma_f32_16x16x32_bf16 v[24:27], v[160:163], v[202:205], v[24:27]
	v_mfma_f32_16x16x32_bf16 v[12:15], v[152:155], v[210:213], v[12:15]
	v_mfma_f32_16x16x32_bf16 v[8:11], v[160:163], v[210:213], v[8:11]
	v_mfma_f32_16x16x32_bf16 v[52:55], v[164:167], v[180:183], v[52:55]
	v_mfma_f32_16x16x32_bf16 v[48:51], v[172:175], v[180:183], v[48:51]
	v_mfma_f32_16x16x32_bf16 v[36:39], v[164:167], v[188:191], v[36:39]
	v_mfma_f32_16x16x32_bf16 v[32:35], v[172:175], v[188:191], v[32:35]
	v_mfma_f32_16x16x32_bf16 v[20:23], v[164:167], v[198:201], v[20:23]
	v_mfma_f32_16x16x32_bf16 v[16:19], v[172:175], v[198:201], v[16:19]
	v_mfma_f32_16x16x32_bf16 v[4:7], v[164:167], v[206:209], v[4:7]
	v_mfma_f32_16x16x32_bf16 v[0:3], v[172:175], v[206:209], v[0:3]
	v_mfma_f32_16x16x32_bf16 v[52:55], v[168:171], v[184:187], v[52:55]
	v_mfma_f32_16x16x32_bf16 v[48:51], v[176:179], v[184:187], v[48:51]
	v_mfma_f32_16x16x32_bf16 v[36:39], v[168:171], v[194:197], v[36:39]
	v_mfma_f32_16x16x32_bf16 v[32:35], v[176:179], v[194:197], v[32:35]
	v_mfma_f32_16x16x32_bf16 v[20:23], v[168:171], v[202:205], v[20:23]
	v_mfma_f32_16x16x32_bf16 v[16:19], v[176:179], v[202:205], v[16:19]
	v_mfma_f32_16x16x32_bf16 v[4:7], v[168:171], v[210:213], v[4:7]
	v_mfma_f32_16x16x32_bf16 v[0:3], v[176:179], v[210:213], v[0:3]
	s_barrier
	s_add_i32 s55, s55, 2
	s_add_u32 s26, s26, 0x100
	s_addc_u32 s27, s27, 0
	s_add_u32 s53, s53, 0x100
	s_addc_u32 s54, s54, 0
	s_cmp_gt_u32 s55, 5
	s_cbranch_scc0 .LBB0_661
	s_and_b64 vcc, exec, s[12:13]
	s_cbranch_vccz .LBB0_664
	s_barrier

.LBB0_743:
	ds_read_b128 v[128:131], v187
	ds_read_b128 v[132:135], v187 offset:1024
	ds_read_b128 v[136:139], v187 offset:2048
	ds_read_b128 v[140:143], v187 offset:3072
	ds_read_b128 v[144:147], v188
	ds_read_b128 v[148:151], v188 offset:1024
	ds_read_b128 v[166:169], v188 offset:2048
	ds_read_b128 v[170:173], v188 offset:3072
	s_add_u32 s40, s38, 0xfffc0080
	s_addc_u32 s41, s39, -1
	s_cmp_eq_u32 s63, 12
	s_cselect_b32 s43, s23, s41
	s_cselect_b32 s42, s31, s40
	s_cselect_b32 s41, s21, s62
	s_cselect_b32 s40, s60, s61
	v_lshl_add_u64 v[182:183], s[38:39], 0, v[160:161]
	s_add_i32 m0, s37, 0xc000
	ds_read_b128 v[174:177], v189
	ds_read_b128 v[178:181], v189 offset:1024
	ds_read_b128 v[194:197], v189 offset:2048
	ds_read_b128 v[198:201], v189 offset:3072
	ds_read_b128 v[202:205], v189 offset:4096
	ds_read_b128 v[206:209], v189 offset:5120
	ds_read_b128 v[210:213], v189 offset:6144
	ds_read_b128 v[214:217], v189 offset:7168
	global_load_lds_dwordx4 v[182:183], off
	v_lshl_add_u64 v[182:183], s[38:39], 0, v[162:163]
	s_add_i32 m0, s37, 0xe000
	s_nop 0
	global_load_lds_dwordx4 v[182:183], off
	s_waitcnt vmcnt(8)
	s_waitcnt lgkmcnt(0)
	s_barrier
	s_waitcnt lgkmcnt(0)
	v_mfma_f32_16x16x32_bf16 v[124:127], v[128:131], v[174:177], v[124:127]
	v_mfma_f32_16x16x32_bf16 v[120:123], v[136:139], v[174:177], v[120:123]
	v_mfma_f32_16x16x32_bf16 v[108:111], v[128:131], v[194:197], v[108:111]
	v_mfma_f32_16x16x32_bf16 v[104:107], v[136:139], v[194:197], v[104:107]
	v_mfma_f32_16x16x32_bf16 v[92:95], v[128:131], v[202:205], v[92:95]
	v_mfma_f32_16x16x32_bf16 v[88:91], v[136:139], v[202:205], v[88:91]
	v_mfma_f32_16x16x32_bf16 v[76:79], v[128:131], v[210:213], v[76:79]
	v_mfma_f32_16x16x32_bf16 v[72:75], v[136:139], v[210:213], v[72:75]
	v_mfma_f32_16x16x32_bf16 v[124:127], v[132:135], v[178:181], v[124:127]
	v_mfma_f32_16x16x32_bf16 v[120:123], v[140:143], v[178:181], v[120:123]
	v_mfma_f32_16x16x32_bf16 v[108:111], v[132:135], v[198:201], v[108:111]
	v_mfma_f32_16x16x32_bf16 v[104:107], v[140:143], v[198:201], v[104:107]
	v_mfma_f32_16x16x32_bf16 v[92:95], v[132:135], v[206:209], v[92:95]
	v_mfma_f32_16x16x32_bf16 v[88:91], v[140:143], v[206:209], v[88:91]
	v_mfma_f32_16x16x32_bf16 v[76:79], v[132:135], v[214:217], v[76:79]
	v_mfma_f32_16x16x32_bf16 v[72:75], v[140:143], v[214:217], v[72:75]
	v_mfma_f32_16x16x32_bf16 v[116:119], v[144:147], v[174:177], v[116:119]
	v_mfma_f32_16x16x32_bf16 v[112:115], v[166:169], v[174:177], v[112:115]
	v_mfma_f32_16x16x32_bf16 v[100:103], v[144:147], v[194:197], v[100:103]
	v_mfma_f32_16x16x32_bf16 v[96:99], v[166:169], v[194:197], v[96:99]
	v_mfma_f32_16x16x32_bf16 v[84:87], v[144:147], v[202:205], v[84:87]
	v_mfma_f32_16x16x32_bf16 v[80:83], v[166:169], v[202:205], v[80:83]
	v_mfma_f32_16x16x32_bf16 v[68:71], v[144:147], v[210:213], v[68:71]
	v_mfma_f32_16x16x32_bf16 v[64:67], v[166:169], v[210:213], v[64:67]
	v_mfma_f32_16x16x32_bf16 v[116:119], v[148:151], v[178:181], v[116:119]
	v_mfma_f32_16x16x32_bf16 v[112:115], v[170:173], v[178:181], v[112:115]
	v_mfma_f32_16x16x32_bf16 v[100:103], v[148:151], v[198:201], v[100:103]
	v_mfma_f32_16x16x32_bf16 v[96:99], v[170:173], v[198:201], v[96:99]
	v_mfma_f32_16x16x32_bf16 v[84:87], v[148:151], v[206:209], v[84:87]
	v_mfma_f32_16x16x32_bf16 v[80:83], v[170:173], v[206:209], v[80:83]
	v_mfma_f32_16x16x32_bf16 v[68:71], v[148:151], v[214:217], v[68:71]
	v_mfma_f32_16x16x32_bf16 v[64:67], v[170:173], v[214:217], v[64:67]
	s_barrier
	s_add_i32 s64, s58, s48
	v_lshl_add_u64 v[182:183], s[40:41], 0, v[154:155]
	s_mov_b32 m0, s64
	ds_read_b128 v[174:177], v189 offset:16384
	ds_read_b128 v[178:181], v189 offset:17408
	ds_read_b128 v[194:197], v189 offset:18432
	ds_read_b128 v[198:201], v189 offset:19456
	ds_read_b128 v[202:205], v189 offset:20480
	ds_read_b128 v[206:209], v189 offset:21504
	ds_read_b128 v[210:213], v189 offset:22528
	ds_read_b128 v[214:217], v189 offset:23552
	global_load_lds_dwordx4 v[182:183], off
	s_add_i32 m0, s64, 0x2000
	s_add_u32 s64, s40, 0x40000
	v_lshl_add_u64 v[218:219], s[40:41], 0, v[158:159]
	s_addc_u32 s65, s41, 0
	s_add_i32 s66, s59, s48
	global_load_lds_dwordx4 v[218:219], off
	v_lshl_add_u64 v[220:221], s[64:65], 0, v[154:155]
	s_mov_b32 m0, s66
	v_lshl_add_u64 v[222:223], s[42:43], 0, v[156:157]
	global_load_lds_dwordx4 v[220:221], off
	v_lshl_add_u64 v[220:221], s[64:65], 0, v[158:159]
	s_add_i32 m0, s66, 0x2000
	s_nop 0
	global_load_lds_dwordx4 v[220:221], off
	v_lshl_add_u64 v[220:221], s[42:43], 0, v[152:153]
	s_mov_b32 m0, s37
	s_nop 0
	global_load_lds_dwordx4 v[220:221], off
	s_mov_b32 m0, s49
	s_nop 0
	global_load_lds_dwordx4 v[222:223], off
	s_waitcnt vmcnt(8)
	s_waitcnt lgkmcnt(0)
	s_barrier
	s_waitcnt lgkmcnt(0)
	v_mfma_f32_16x16x32_bf16 v[60:63], v[128:131], v[174:177], v[60:63]
	v_mfma_f32_16x16x32_bf16 v[56:59], v[136:139], v[174:177], v[56:59]
	v_mfma_f32_16x16x32_bf16 v[44:47], v[128:131], v[194:197], v[44:47]
	v_mfma_f32_16x16x32_bf16 v[40:43], v[136:139], v[194:197], v[40:43]
	v_mfma_f32_16x16x32_bf16 v[28:31], v[128:131], v[202:205], v[28:31]
	v_mfma_f32_16x16x32_bf16 v[24:27], v[136:139], v[202:205], v[24:27]
	v_mfma_f32_16x16x32_bf16 v[12:15], v[128:131], v[210:213], v[12:15]
	v_mfma_f32_16x16x32_bf16 v[8:11], v[136:139], v[210:213], v[8:11]
	v_mfma_f32_16x16x32_bf16 v[60:63], v[132:135], v[178:181], v[60:63]
	v_mfma_f32_16x16x32_bf16 v[56:59], v[140:143], v[178:181], v[56:59]
	v_mfma_f32_16x16x32_bf16 v[44:47], v[132:135], v[198:201], v[44:47]
	v_mfma_f32_16x16x32_bf16 v[40:43], v[140:143], v[198:201], v[40:43]
	v_mfma_f32_16x16x32_bf16 v[28:31], v[132:135], v[206:209], v[28:31]
	v_mfma_f32_16x16x32_bf16 v[24:27], v[140:143], v[206:209], v[24:27]
	v_mfma_f32_16x16x32_bf16 v[12:15], v[132:135], v[214:217], v[12:15]
	v_mfma_f32_16x16x32_bf16 v[8:11], v[140:143], v[214:217], v[8:11]
	v_mfma_f32_16x16x32_bf16 v[52:55], v[144:147], v[174:177], v[52:55]
	v_mfma_f32_16x16x32_bf16 v[48:51], v[166:169], v[174:177], v[48:51]
	v_mfma_f32_16x16x32_bf16 v[36:39], v[144:147], v[194:197], v[36:39]
	v_mfma_f32_16x16x32_bf16 v[32:35], v[166:169], v[194:197], v[32:35]
	v_mfma_f32_16x16x32_bf16 v[20:23], v[144:147], v[202:205], v[20:23]
	v_mfma_f32_16x16x32_bf16 v[16:19], v[166:169], v[202:205], v[16:19]
	v_mfma_f32_16x16x32_bf16 v[4:7], v[144:147], v[210:213], v[4:7]
	v_mfma_f32_16x16x32_bf16 v[0:3], v[166:169], v[210:213], v[0:3]
	v_mfma_f32_16x16x32_bf16 v[52:55], v[148:151], v[178:181], v[52:55]
	v_mfma_f32_16x16x32_bf16 v[48:51], v[170:173], v[178:181], v[48:51]
	v_mfma_f32_16x16x32_bf16 v[36:39], v[148:151], v[198:201], v[36:39]
	v_mfma_f32_16x16x32_bf16 v[32:35], v[170:173], v[198:201], v[32:35]
	v_mfma_f32_16x16x32_bf16 v[20:23], v[148:151], v[206:209], v[20:23]
	v_mfma_f32_16x16x32_bf16 v[16:19], v[170:173], v[206:209], v[16:19]
	v_mfma_f32_16x16x32_bf16 v[4:7], v[148:151], v[214:217], v[4:7]
	v_mfma_f32_16x16x32_bf16 v[0:3], v[170:173], v[214:217], v[0:3]
	s_barrier
	s_add_i32 s64, 0, 0x18000
	s_add_i32 s65, 0, 0x1c000
	v_add_u32_e32 v140, s64, v185
	v_add_u32_e32 v170, s65, v185
	ds_read_b128 v[128:131], v140
	ds_read_b128 v[132:135], v140 offset:1024
	ds_read_b128 v[136:139], v140 offset:2048
	ds_read_b128 v[140:143], v140 offset:3072
	ds_read_b128 v[144:147], v170
	ds_read_b128 v[148:151], v170 offset:1024
	ds_read_b128 v[166:169], v170 offset:2048
	ds_read_b128 v[170:173], v170 offset:3072
	s_add_u32 s42, s42, 0x40000
	s_addc_u32 s43, s43, 0
	s_mov_b32 m0, s50
	v_lshl_add_u64 v[224:225], s[42:43], 0, v[152:153]
	ds_read_b128 v[174:177], v189 offset:32768
	ds_read_b128 v[178:181], v189 offset:33792
	ds_read_b128 v[194:197], v189 offset:34816
	ds_read_b128 v[198:201], v189 offset:35840
	ds_read_b128 v[202:205], v189 offset:36864
	ds_read_b128 v[206:209], v189 offset:37888
	ds_read_b128 v[210:213], v189 offset:38912
	ds_read_b128 v[214:217], v189 offset:39936
	global_load_lds_dwordx4 v[224:225], off
	v_lshl_add_u64 v[224:225], s[42:43], 0, v[156:157]
	s_mov_b32 m0, s51
	s_nop 0
	global_load_lds_dwordx4 v[224:225], off
	s_waitcnt vmcnt(8)
	s_waitcnt lgkmcnt(0)
	s_barrier
	s_waitcnt lgkmcnt(0)
	v_mfma_f32_16x16x32_bf16 v[124:127], v[128:131], v[174:177], v[124:127]
	v_mfma_f32_16x16x32_bf16 v[120:123], v[136:139], v[174:177], v[120:123]
	v_mfma_f32_16x16x32_bf16 v[108:111], v[128:131], v[194:197], v[108:111]
	v_mfma_f32_16x16x32_bf16 v[104:107], v[136:139], v[194:197], v[104:107]
	v_mfma_f32_16x16x32_bf16 v[92:95], v[128:131], v[202:205], v[92:95]
	v_mfma_f32_16x16x32_bf16 v[88:91], v[136:139], v[202:205], v[88:91]
	v_mfma_f32_16x16x32_bf16 v[76:79], v[128:131], v[210:213], v[76:79]
	v_mfma_f32_16x16x32_bf16 v[72:75], v[136:139], v[210:213], v[72:75]
	v_mfma_f32_16x16x32_bf16 v[124:127], v[132:135], v[178:181], v[124:127]
	v_mfma_f32_16x16x32_bf16 v[120:123], v[140:143], v[178:181], v[120:123]
	v_mfma_f32_16x16x32_bf16 v[108:111], v[132:135], v[198:201], v[108:111]
	v_mfma_f32_16x16x32_bf16 v[104:107], v[140:143], v[198:201], v[104:107]
	v_mfma_f32_16x16x32_bf16 v[92:95], v[132:135], v[206:209], v[92:95]
	v_mfma_f32_16x16x32_bf16 v[88:91], v[140:143], v[206:209], v[88:91]
	v_mfma_f32_16x16x32_bf16 v[76:79], v[132:135], v[214:217], v[76:79]
	v_mfma_f32_16x16x32_bf16 v[72:75], v[140:143], v[214:217], v[72:75]
	v_mfma_f32_16x16x32_bf16 v[116:119], v[144:147], v[174:177], v[116:119]
	v_mfma_f32_16x16x32_bf16 v[112:115], v[166:169], v[174:177], v[112:115]
	v_mfma_f32_16x16x32_bf16 v[100:103], v[144:147], v[194:197], v[100:103]
	v_mfma_f32_16x16x32_bf16 v[96:99], v[166:169], v[194:197], v[96:99]
	v_mfma_f32_16x16x32_bf16 v[84:87], v[144:147], v[202:205], v[84:87]
	v_mfma_f32_16x16x32_bf16 v[80:83], v[166:169], v[202:205], v[80:83]
	v_mfma_f32_16x16x32_bf16 v[68:71], v[144:147], v[210:213], v[68:71]
	v_mfma_f32_16x16x32_bf16 v[64:67], v[166:169], v[210:213], v[64:67]
	v_mfma_f32_16x16x32_bf16 v[116:119], v[148:151], v[178:181], v[116:119]
	v_mfma_f32_16x16x32_bf16 v[112:115], v[170:173], v[178:181], v[112:115]
	v_mfma_f32_16x16x32_bf16 v[100:103], v[148:151], v[198:201], v[100:103]
	v_mfma_f32_16x16x32_bf16 v[96:99], v[170:173], v[198:201], v[96:99]
	v_mfma_f32_16x16x32_bf16 v[84:87], v[148:151], v[206:209], v[84:87]
	v_mfma_f32_16x16x32_bf16 v[80:83], v[170:173], v[206:209], v[80:83]
	v_mfma_f32_16x16x32_bf16 v[68:71], v[148:151], v[214:217], v[68:71]
	v_mfma_f32_16x16x32_bf16 v[64:67], v[170:173], v[214:217], v[64:67]
	s_barrier
	s_add_i32 s42, s64, s48
	v_lshl_add_u64 v[182:183], v[182:183], 0, s[16:17]
	s_mov_b32 m0, s42
	ds_read_b128 v[174:177], v189 offset:49152
	ds_read_b128 v[178:181], v189 offset:50176
	ds_read_b128 v[194:197], v189 offset:51200
	ds_read_b128 v[198:201], v189 offset:52224
	ds_read_b128 v[202:205], v189 offset:53248
	ds_read_b128 v[206:209], v189 offset:54272
	ds_read_b128 v[210:213], v189 offset:55296
	ds_read_b128 v[214:217], v189 offset:56320
	global_load_lds_dwordx4 v[182:183], off
	s_add_i32 m0, s42, 0x2000
	s_add_u32 s40, s40, 0x40080
	v_lshl_add_u64 v[182:183], v[218:219], 0, s[16:17]
	s_addc_u32 s41, s41, 0
	s_add_i32 s42, s65, s48
	global_load_lds_dwordx4 v[182:183], off
	v_lshl_add_u64 v[182:183], s[40:41], 0, v[154:155]
	s_mov_b32 m0, s42
	s_nop 0
	global_load_lds_dwordx4 v[182:183], off
	v_lshl_add_u64 v[182:183], s[40:41], 0, v[158:159]
	s_add_i32 m0, s42, 0x2000
	s_nop 0
	global_load_lds_dwordx4 v[182:183], off
	v_lshl_add_u64 v[182:183], v[220:221], 0, s[16:17]
	s_mov_b32 m0, s53
	s_nop 0
	global_load_lds_dwordx4 v[182:183], off
	v_lshl_add_u64 v[182:183], v[222:223], 0, s[16:17]
	s_mov_b32 m0, s54
	s_nop 0
	global_load_lds_dwordx4 v[182:183], off
	s_waitcnt vmcnt(8)
	s_waitcnt lgkmcnt(0)
	s_barrier
	s_waitcnt lgkmcnt(0)
	v_mfma_f32_16x16x32_bf16 v[60:63], v[128:131], v[174:177], v[60:63]
	v_mfma_f32_16x16x32_bf16 v[56:59], v[136:139], v[174:177], v[56:59]
	v_mfma_f32_16x16x32_bf16 v[44:47], v[128:131], v[194:197], v[44:47]
	v_mfma_f32_16x16x32_bf16 v[40:43], v[136:139], v[194:197], v[40:43]
	v_mfma_f32_16x16x32_bf16 v[28:31], v[128:131], v[202:205], v[28:31]
	v_mfma_f32_16x16x32_bf16 v[24:27], v[136:139], v[202:205], v[24:27]
	v_mfma_f32_16x16x32_bf16 v[12:15], v[128:131], v[210:213], v[12:15]
	v_mfma_f32_16x16x32_bf16 v[8:11], v[136:139], v[210:213], v[8:11]
	v_mfma_f32_16x16x32_bf16 v[60:63], v[132:135], v[178:181], v[60:63]
	v_mfma_f32_16x16x32_bf16 v[56:59], v[140:143], v[178:181], v[56:59]
	v_mfma_f32_16x16x32_bf16 v[44:47], v[132:135], v[198:201], v[44:47]
	v_mfma_f32_16x16x32_bf16 v[40:43], v[140:143], v[198:201], v[40:43]
	v_mfma_f32_16x16x32_bf16 v[28:31], v[132:135], v[206:209], v[28:31]
	v_mfma_f32_16x16x32_bf16 v[24:27], v[140:143], v[206:209], v[24:27]
	v_mfma_f32_16x16x32_bf16 v[12:15], v[132:135], v[214:217], v[12:15]
	v_mfma_f32_16x16x32_bf16 v[8:11], v[140:143], v[214:217], v[8:11]
	v_mfma_f32_16x16x32_bf16 v[52:55], v[144:147], v[174:177], v[52:55]
	v_mfma_f32_16x16x32_bf16 v[48:51], v[166:169], v[174:177], v[48:51]
	v_mfma_f32_16x16x32_bf16 v[36:39], v[144:147], v[194:197], v[36:39]
	v_mfma_f32_16x16x32_bf16 v[32:35], v[166:169], v[194:197], v[32:35]
	v_mfma_f32_16x16x32_bf16 v[20:23], v[144:147], v[202:205], v[20:23]
	v_mfma_f32_16x16x32_bf16 v[16:19], v[166:169], v[202:205], v[16:19]
	v_mfma_f32_16x16x32_bf16 v[4:7], v[144:147], v[210:213], v[4:7]
	v_mfma_f32_16x16x32_bf16 v[0:3], v[166:169], v[210:213], v[0:3]
	v_mfma_f32_16x16x32_bf16 v[52:55], v[148:151], v[178:181], v[52:55]
	v_mfma_f32_16x16x32_bf16 v[48:51], v[170:173], v[178:181], v[48:51]
	v_mfma_f32_16x16x32_bf16 v[36:39], v[148:151], v[198:201], v[36:39]
	v_mfma_f32_16x16x32_bf16 v[32:35], v[170:173], v[198:201], v[32:35]
	v_mfma_f32_16x16x32_bf16 v[20:23], v[148:151], v[206:209], v[20:23]
	v_mfma_f32_16x16x32_bf16 v[16:19], v[170:173], v[206:209], v[16:19]
	v_mfma_f32_16x16x32_bf16 v[4:7], v[148:151], v[214:217], v[4:7]
	v_mfma_f32_16x16x32_bf16 v[0:3], v[170:173], v[214:217], v[0:3]
	s_barrier
	s_add_i32 s63, s63, 2
	s_add_u32 s38, s38, 0x100
	s_addc_u32 s39, s39, 0
	s_add_u32 s61, s61, 0x100
	s_addc_u32 s62, s62, 0
	s_cmp_gt_u32 s63, 13
	s_cbranch_scc0 .LBB0_743
	s_and_b64 vcc, exec, s[18:19]
	s_cbranch_vccz .LBB0_746
	s_barrier

.LBB0_839:
	s_waitcnt lgkmcnt(0)
	s_barrier
	s_waitcnt lgkmcnt(0)
	v_mfma_f32_16x16x32_bf16 v[60:63], v[144:147], v[184:187], v[60:63]
	v_mfma_f32_16x16x32_bf16 v[56:59], v[152:155], v[184:187], v[56:59]
	v_mfma_f32_16x16x32_bf16 v[44:47], v[144:147], v[176:179], v[44:47]
	v_mfma_f32_16x16x32_bf16 v[40:43], v[152:155], v[176:179], v[40:43]
	v_mfma_f32_16x16x32_bf16 v[28:31], v[144:147], v[168:171], v[28:31]
	v_mfma_f32_16x16x32_bf16 v[24:27], v[152:155], v[168:171], v[24:27]
	v_mfma_f32_16x16x32_bf16 v[12:15], v[144:147], v[160:163], v[12:15]
	v_mfma_f32_16x16x32_bf16 v[8:11], v[152:155], v[160:163], v[8:11]
	v_mfma_f32_16x16x32_bf16 v[60:63], v[148:151], v[188:191], v[60:63]
	v_mfma_f32_16x16x32_bf16 v[56:59], v[156:159], v[188:191], v[56:59]
	v_mfma_f32_16x16x32_bf16 v[44:47], v[148:151], v[180:183], v[44:47]
	v_mfma_f32_16x16x32_bf16 v[40:43], v[156:159], v[180:183], v[40:43]
	v_mfma_f32_16x16x32_bf16 v[28:31], v[148:151], v[172:175], v[28:31]
	v_mfma_f32_16x16x32_bf16 v[24:27], v[156:159], v[172:175], v[24:27]
	v_mfma_f32_16x16x32_bf16 v[12:15], v[148:151], v[164:167], v[12:15]
	v_mfma_f32_16x16x32_bf16 v[8:11], v[156:159], v[164:167], v[8:11]
	v_mfma_f32_16x16x32_bf16 v[52:55], v[128:131], v[184:187], v[52:55]
	v_mfma_f32_16x16x32_bf16 v[48:51], v[136:139], v[184:187], v[48:51]
	v_mfma_f32_16x16x32_bf16 v[36:39], v[128:131], v[176:179], v[36:39]
	v_mfma_f32_16x16x32_bf16 v[32:35], v[136:139], v[176:179], v[32:35]
	v_mfma_f32_16x16x32_bf16 v[20:23], v[128:131], v[168:171], v[20:23]
	v_mfma_f32_16x16x32_bf16 v[16:19], v[136:139], v[168:171], v[16:19]
	v_mfma_f32_16x16x32_bf16 v[4:7], v[128:131], v[160:163], v[4:7]
	v_mfma_f32_16x16x32_bf16 v[0:3], v[136:139], v[160:163], v[0:3]
	v_mfma_f32_16x16x32_bf16 v[52:55], v[132:135], v[188:191], v[52:55]
	v_mfma_f32_16x16x32_bf16 v[48:51], v[140:143], v[188:191], v[48:51]
	v_mfma_f32_16x16x32_bf16 v[36:39], v[132:135], v[180:183], v[36:39]
	v_mfma_f32_16x16x32_bf16 v[32:35], v[140:143], v[180:183], v[32:35]
	v_mfma_f32_16x16x32_bf16 v[20:23], v[132:135], v[172:175], v[20:23]
	v_mfma_f32_16x16x32_bf16 v[16:19], v[140:143], v[172:175], v[16:19]
	v_mfma_f32_16x16x32_bf16 v[4:7], v[132:135], v[164:167], v[4:7]
	v_mfma_f32_16x16x32_bf16 v[0:3], v[140:143], v[164:167], v[0:3]
	s_barrier
	s_add_i32 s48, 0, 0x18000
	s_add_i32 s49, 0, 0x1c000
	v_add_u32_e32 v140, s48, v220
	v_add_u32_e32 v156, s49, v220
	ds_read_b128 v[128:131], v140
	ds_read_b128 v[132:135], v140 offset:1024
	ds_read_b128 v[136:139], v140 offset:2048
	ds_read_b128 v[140:143], v140 offset:3072
	ds_read_b128 v[144:147], v156
	ds_read_b128 v[148:151], v156 offset:1024
	ds_read_b128 v[152:155], v156 offset:2048
	ds_read_b128 v[156:159], v156 offset:3072
	s_add_u32 s44, s46, 0x40000
	s_addc_u32 s45, s47, 0
	s_mov_b32 m0, s60
	v_lshl_add_u64 v[232:233], s[44:45], 0, v[194:195]
	ds_read_b128 v[160:163], v223 offset:32768
	ds_read_b128 v[164:167], v223 offset:33792
	ds_read_b128 v[168:171], v223 offset:34816
	ds_read_b128 v[172:175], v223 offset:35840
	ds_read_b128 v[176:179], v223 offset:36864
	ds_read_b128 v[180:183], v223 offset:37888
	ds_read_b128 v[184:187], v223 offset:38912
	ds_read_b128 v[188:191], v223 offset:39936
	global_load_lds_dwordx4 v[232:233], off
	v_lshl_add_u64 v[232:233], s[44:45], 0, v[198:199]
	s_mov_b32 m0, s61
	s_nop 0
	global_load_lds_dwordx4 v[232:233], off
	s_waitcnt vmcnt(8)
	s_waitcnt lgkmcnt(0)
	s_barrier
	s_waitcnt lgkmcnt(0)
	v_mfma_f32_16x16x32_bf16 v[124:127], v[128:131], v[160:163], v[124:127]
	v_mfma_f32_16x16x32_bf16 v[120:123], v[136:139], v[160:163], v[120:123]
	v_mfma_f32_16x16x32_bf16 v[108:111], v[128:131], v[168:171], v[108:111]
	v_mfma_f32_16x16x32_bf16 v[104:107], v[136:139], v[168:171], v[104:107]
	v_mfma_f32_16x16x32_bf16 v[92:95], v[128:131], v[176:179], v[92:95]
	v_mfma_f32_16x16x32_bf16 v[88:91], v[136:139], v[176:179], v[88:91]
	v_mfma_f32_16x16x32_bf16 v[76:79], v[128:131], v[184:187], v[76:79]
	v_mfma_f32_16x16x32_bf16 v[72:75], v[136:139], v[184:187], v[72:75]
	v_mfma_f32_16x16x32_bf16 v[124:127], v[132:135], v[164:167], v[124:127]
	v_mfma_f32_16x16x32_bf16 v[120:123], v[140:143], v[164:167], v[120:123]
	v_mfma_f32_16x16x32_bf16 v[108:111], v[132:135], v[172:175], v[108:111]
	v_mfma_f32_16x16x32_bf16 v[104:107], v[140:143], v[172:175], v[104:107]
	v_mfma_f32_16x16x32_bf16 v[92:95], v[132:135], v[180:183], v[92:95]
	v_mfma_f32_16x16x32_bf16 v[88:91], v[140:143], v[180:183], v[88:91]
	v_mfma_f32_16x16x32_bf16 v[76:79], v[132:135], v[188:191], v[76:79]
	v_mfma_f32_16x16x32_bf16 v[72:75], v[140:143], v[188:191], v[72:75]
	v_mfma_f32_16x16x32_bf16 v[116:119], v[144:147], v[160:163], v[116:119]
	v_mfma_f32_16x16x32_bf16 v[112:115], v[152:155], v[160:163], v[112:115]
	v_mfma_f32_16x16x32_bf16 v[100:103], v[144:147], v[168:171], v[100:103]
	v_mfma_f32_16x16x32_bf16 v[96:99], v[152:155], v[168:171], v[96:99]
	v_mfma_f32_16x16x32_bf16 v[84:87], v[144:147], v[176:179], v[84:87]
	v_mfma_f32_16x16x32_bf16 v[80:83], v[152:155], v[176:179], v[80:83]
	v_mfma_f32_16x16x32_bf16 v[68:71], v[144:147], v[184:187], v[68:71]
	v_mfma_f32_16x16x32_bf16 v[64:67], v[152:155], v[184:187], v[64:67]
	v_mfma_f32_16x16x32_bf16 v[116:119], v[148:151], v[164:167], v[116:119]
	v_mfma_f32_16x16x32_bf16 v[112:115], v[156:159], v[164:167], v[112:115]
	v_mfma_f32_16x16x32_bf16 v[100:103], v[148:151], v[172:175], v[100:103]
	v_mfma_f32_16x16x32_bf16 v[96:99], v[156:159], v[172:175], v[96:99]
	v_mfma_f32_16x16x32_bf16 v[84:87], v[148:151], v[180:183], v[84:87]
	v_mfma_f32_16x16x32_bf16 v[80:83], v[156:159], v[180:183], v[80:83]
	v_mfma_f32_16x16x32_bf16 v[68:71], v[148:151], v[188:191], v[68:71]
	v_mfma_f32_16x16x32_bf16 v[64:67], v[156:159], v[188:191], v[64:67]
	s_barrier
	s_add_i32 s44, s48, s53
	v_lshl_add_u64 v[218:219], v[218:219], 0, s[14:15]
	s_mov_b32 m0, s44
	ds_read_b128 v[160:163], v223 offset:49152
	ds_read_b128 v[164:167], v223 offset:50176
	ds_read_b128 v[168:171], v223 offset:51200
	ds_read_b128 v[172:175], v223 offset:52224
	ds_read_b128 v[176:179], v223 offset:53248
	ds_read_b128 v[180:183], v223 offset:54272
	ds_read_b128 v[184:187], v223 offset:55296
	ds_read_b128 v[188:191], v223 offset:56320
	global_load_lds_dwordx4 v[218:219], off
	s_add_i32 m0, s44, 0x2000
	s_add_u32 s42, s42, 0x40080
	v_lshl_add_u64 v[216:217], v[216:217], 0, s[14:15]
	s_addc_u32 s43, s43, 0
	s_add_i32 s44, s49, s53
	global_load_lds_dwordx4 v[216:217], off
	v_lshl_add_u64 v[216:217], s[42:43], 0, v[196:197]
	s_mov_b32 m0, s44
	v_lshl_add_u64 v[212:213], v[212:213], 0, s[14:15]
	global_load_lds_dwordx4 v[216:217], off
	v_lshl_add_u64 v[216:217], s[42:43], 0, v[200:201]
	s_add_i32 m0, s44, 0x2000
	s_nop 0
	global_load_lds_dwordx4 v[216:217], off
	s_mov_b32 m0, s63
	s_nop 0
	global_load_lds_dwordx4 v[212:213], off
	v_lshl_add_u64 v[212:213], v[214:215], 0, s[14:15]
	s_mov_b32 m0, s64
	s_nop 0
	global_load_lds_dwordx4 v[212:213], off
	s_waitcnt vmcnt(8)
	s_waitcnt lgkmcnt(0)
	s_barrier
	s_waitcnt lgkmcnt(0)
	v_mfma_f32_16x16x32_bf16 v[60:63], v[128:131], v[160:163], v[60:63]
	v_mfma_f32_16x16x32_bf16 v[56:59], v[136:139], v[160:163], v[56:59]
	v_mfma_f32_16x16x32_bf16 v[44:47], v[128:131], v[168:171], v[44:47]
	v_mfma_f32_16x16x32_bf16 v[40:43], v[136:139], v[168:171], v[40:43]
	v_mfma_f32_16x16x32_bf16 v[28:31], v[128:131], v[176:179], v[28:31]
	v_mfma_f32_16x16x32_bf16 v[24:27], v[136:139], v[176:179], v[24:27]
	v_mfma_f32_16x16x32_bf16 v[12:15], v[128:131], v[184:187], v[12:15]
	v_mfma_f32_16x16x32_bf16 v[8:11], v[136:139], v[184:187], v[8:11]
	v_mfma_f32_16x16x32_bf16 v[60:63], v[132:135], v[164:167], v[60:63]
	v_mfma_f32_16x16x32_bf16 v[56:59], v[140:143], v[164:167], v[56:59]
	v_mfma_f32_16x16x32_bf16 v[44:47], v[132:135], v[172:175], v[44:47]
	v_mfma_f32_16x16x32_bf16 v[40:43], v[140:143], v[172:175], v[40:43]
	v_mfma_f32_16x16x32_bf16 v[28:31], v[132:135], v[180:183], v[28:31]
	v_mfma_f32_16x16x32_bf16 v[24:27], v[140:143], v[180:183], v[24:27]
	v_mfma_f32_16x16x32_bf16 v[12:15], v[132:135], v[188:191], v[12:15]
	v_mfma_f32_16x16x32_bf16 v[8:11], v[140:143], v[188:191], v[8:11]
	v_mfma_f32_16x16x32_bf16 v[52:55], v[144:147], v[160:163], v[52:55]
	v_mfma_f32_16x16x32_bf16 v[48:51], v[152:155], v[160:163], v[48:51]
	v_mfma_f32_16x16x32_bf16 v[36:39], v[144:147], v[168:171], v[36:39]
	v_mfma_f32_16x16x32_bf16 v[32:35], v[152:155], v[168:171], v[32:35]
	v_mfma_f32_16x16x32_bf16 v[20:23], v[144:147], v[176:179], v[20:23]
	v_mfma_f32_16x16x32_bf16 v[16:19], v[152:155], v[176:179], v[16:19]
	v_mfma_f32_16x16x32_bf16 v[4:7], v[144:147], v[184:187], v[4:7]
	v_mfma_f32_16x16x32_bf16 v[0:3], v[152:155], v[184:187], v[0:3]
	v_mfma_f32_16x16x32_bf16 v[52:55], v[148:151], v[164:167], v[52:55]
	v_mfma_f32_16x16x32_bf16 v[48:51], v[156:159], v[164:167], v[48:51]
	v_mfma_f32_16x16x32_bf16 v[36:39], v[148:151], v[172:175], v[36:39]
	v_mfma_f32_16x16x32_bf16 v[32:35], v[156:159], v[172:175], v[32:35]
	v_mfma_f32_16x16x32_bf16 v[20:23], v[148:151], v[180:183], v[20:23]
	v_mfma_f32_16x16x32_bf16 v[16:19], v[156:159], v[180:183], v[16:19]
	v_mfma_f32_16x16x32_bf16 v[4:7], v[148:151], v[188:191], v[4:7]
	v_mfma_f32_16x16x32_bf16 v[0:3], v[156:159], v[188:191], v[0:3]
	s_barrier
	s_add_i32 s83, s83, 2
	s_add_u32 s40, s40, 0x100
	s_addc_u32 s41, s41, 0
	s_add_u32 s81, s81, 0x100
	s_addc_u32 s82, s82, 0
	s_cmp_gt_u32 s83, 13
	s_cbranch_scc1 .LBB0_850

.LBB0_846:
	s_add_u32 s46, s40, 0xfffc0080
	s_addc_u32 s47, s41, -1
	s_waitcnt lgkmcnt(0)
	s_and_b64 s[42:43], s[42:43], exec
	s_cselect_b32 s47, s29, s47
	s_cselect_b32 s46, s79, s46
	s_cselect_b32 s43, s27, s82
	s_cselect_b32 s42, s80, s81
	s_barrier
	s_waitcnt lgkmcnt(0)
	v_mfma_f32_16x16x32_bf16 v[124:127], v[144:147], v[184:187], v[124:127]
	v_mfma_f32_16x16x32_bf16 v[120:123], v[152:155], v[184:187], v[120:123]
	v_mfma_f32_16x16x32_bf16 v[108:111], v[144:147], v[176:179], v[108:111]
	v_mfma_f32_16x16x32_bf16 v[104:107], v[152:155], v[176:179], v[104:107]
	v_mfma_f32_16x16x32_bf16 v[92:95], v[144:147], v[168:171], v[92:95]
	v_mfma_f32_16x16x32_bf16 v[88:91], v[152:155], v[168:171], v[88:91]
	v_mfma_f32_16x16x32_bf16 v[76:79], v[144:147], v[160:163], v[76:79]
	v_mfma_f32_16x16x32_bf16 v[72:75], v[152:155], v[160:163], v[72:75]
	v_mfma_f32_16x16x32_bf16 v[124:127], v[148:151], v[188:191], v[124:127]
	v_mfma_f32_16x16x32_bf16 v[120:123], v[156:159], v[188:191], v[120:123]
	v_mfma_f32_16x16x32_bf16 v[108:111], v[148:151], v[180:183], v[108:111]
	v_mfma_f32_16x16x32_bf16 v[104:107], v[156:159], v[180:183], v[104:107]
	v_mfma_f32_16x16x32_bf16 v[92:95], v[148:151], v[172:175], v[92:95]
	v_mfma_f32_16x16x32_bf16 v[88:91], v[156:159], v[172:175], v[88:91]
	v_mfma_f32_16x16x32_bf16 v[76:79], v[148:151], v[164:167], v[76:79]
	v_mfma_f32_16x16x32_bf16 v[72:75], v[156:159], v[164:167], v[72:75]
	v_mfma_f32_16x16x32_bf16 v[116:119], v[128:131], v[184:187], v[116:119]
	v_mfma_f32_16x16x32_bf16 v[112:115], v[136:139], v[184:187], v[112:115]
	v_mfma_f32_16x16x32_bf16 v[100:103], v[128:131], v[176:179], v[100:103]
	v_mfma_f32_16x16x32_bf16 v[96:99], v[136:139], v[176:179], v[96:99]
	v_mfma_f32_16x16x32_bf16 v[84:87], v[128:131], v[168:171], v[84:87]
	v_mfma_f32_16x16x32_bf16 v[80:83], v[136:139], v[168:171], v[80:83]
	v_mfma_f32_16x16x32_bf16 v[68:71], v[128:131], v[160:163], v[68:71]
	v_mfma_f32_16x16x32_bf16 v[64:67], v[136:139], v[160:163], v[64:67]
	v_mfma_f32_16x16x32_bf16 v[116:119], v[132:135], v[188:191], v[116:119]
	v_mfma_f32_16x16x32_bf16 v[112:115], v[140:143], v[188:191], v[112:115]
	v_mfma_f32_16x16x32_bf16 v[100:103], v[132:135], v[180:183], v[100:103]
	v_mfma_f32_16x16x32_bf16 v[96:99], v[140:143], v[180:183], v[96:99]
	v_mfma_f32_16x16x32_bf16 v[84:87], v[132:135], v[172:175], v[84:87]
	v_mfma_f32_16x16x32_bf16 v[80:83], v[140:143], v[172:175], v[80:83]
	v_mfma_f32_16x16x32_bf16 v[68:71], v[132:135], v[164:167], v[68:71]
	v_mfma_f32_16x16x32_bf16 v[64:67], v[140:143], v[164:167], v[64:67]
	s_barrier
	s_mov_b32 m0, s55
	v_lshl_add_u64 v[218:219], s[42:43], 0, v[196:197]
	s_add_u32 s48, s42, 0x40000
	ds_read_b128 v[184:187], v223 offset:16384
	ds_read_b128 v[188:191], v223 offset:17408
	ds_read_b128 v[176:179], v223 offset:18432
	ds_read_b128 v[180:183], v223 offset:19456
	ds_read_b128 v[168:171], v223 offset:20480
	ds_read_b128 v[172:175], v223 offset:21504
	ds_read_b128 v[160:163], v223 offset:22528
	ds_read_b128 v[164:167], v223 offset:23552
	global_load_lds_dwordx4 v[218:219], off
	v_lshl_add_u64 v[216:217], s[42:43], 0, v[200:201]
	s_mov_b32 m0, s56
	s_addc_u32 s49, s43, 0
	global_load_lds_dwordx4 v[216:217], off
	v_lshl_add_u64 v[212:213], s[48:49], 0, v[196:197]
	s_mov_b32 m0, s57
	v_lshl_add_u64 v[214:215], s[46:47], 0, v[198:199]
	global_load_lds_dwordx4 v[212:213], off
	v_lshl_add_u64 v[212:213], s[48:49], 0, v[200:201]
	s_mov_b32 m0, s58
	s_mov_b64 s[48:49], -1
	global_load_lds_dwordx4 v[212:213], off
	v_lshl_add_u64 v[212:213], s[46:47], 0, v[194:195]
	s_mov_b32 m0, s54
	s_and_b64 vcc, exec, s[44:45]
	global_load_lds_dwordx4 v[212:213], off
	s_mov_b32 m0, s59
	s_nop 0
	global_load_lds_dwordx4 v[214:215], off
	s_cbranch_vccz .LBB0_848
	s_waitcnt vmcnt(8)
	s_mov_b64 s[48:49], 0

.LBB0_934:
	ds_read_b128 v[128:131], v202
	ds_read_b128 v[132:135], v202 offset:1024
	ds_read_b128 v[136:139], v202 offset:2048
	ds_read_b128 v[140:143], v202 offset:3072
	ds_read_b128 v[144:147], v203
	ds_read_b128 v[148:151], v203 offset:1024
	ds_read_b128 v[166:169], v203 offset:2048
	ds_read_b128 v[170:173], v203 offset:3072
	s_add_u32 s42, s40, 0xfff00080
	s_addc_u32 s43, s41, -1
	s_cmp_eq_u32 s64, 60
	s_cselect_b32 s45, s25, s43
	s_cselect_b32 s44, s37, s42
	s_cselect_b32 s43, s23, s63
	s_cselect_b32 s42, s61, s62
	v_lshl_add_u64 v[182:183], s[40:41], 0, v[160:161]
	s_add_i32 m0, s39, 0xc000
	ds_read_b128 v[174:177], v204
	ds_read_b128 v[178:181], v204 offset:1024
	ds_read_b128 v[206:209], v204 offset:2048
	ds_read_b128 v[210:213], v204 offset:3072
	ds_read_b128 v[214:217], v204 offset:4096
	ds_read_b128 v[218:221], v204 offset:5120
	ds_read_b128 v[222:225], v204 offset:6144
	ds_read_b128 v[226:229], v204 offset:7168
	global_load_lds_dwordx4 v[182:183], off
	v_lshl_add_u64 v[182:183], s[40:41], 0, v[162:163]
	s_add_i32 m0, s39, 0xe000
	s_nop 0
	global_load_lds_dwordx4 v[182:183], off
	s_waitcnt vmcnt(8)
	s_waitcnt lgkmcnt(0)
	s_barrier
	s_waitcnt lgkmcnt(0)
	v_mfma_f32_16x16x32_bf16 v[124:127], v[128:131], v[174:177], v[124:127]
	v_mfma_f32_16x16x32_bf16 v[120:123], v[136:139], v[174:177], v[120:123]
	v_mfma_f32_16x16x32_bf16 v[108:111], v[128:131], v[206:209], v[108:111]
	v_mfma_f32_16x16x32_bf16 v[104:107], v[136:139], v[206:209], v[104:107]
	v_mfma_f32_16x16x32_bf16 v[92:95], v[128:131], v[214:217], v[92:95]
	v_mfma_f32_16x16x32_bf16 v[88:91], v[136:139], v[214:217], v[88:91]
	v_mfma_f32_16x16x32_bf16 v[76:79], v[128:131], v[222:225], v[76:79]
	v_mfma_f32_16x16x32_bf16 v[72:75], v[136:139], v[222:225], v[72:75]
	v_mfma_f32_16x16x32_bf16 v[124:127], v[132:135], v[178:181], v[124:127]
	v_mfma_f32_16x16x32_bf16 v[120:123], v[140:143], v[178:181], v[120:123]
	v_mfma_f32_16x16x32_bf16 v[108:111], v[132:135], v[210:213], v[108:111]
	v_mfma_f32_16x16x32_bf16 v[104:107], v[140:143], v[210:213], v[104:107]
	v_mfma_f32_16x16x32_bf16 v[92:95], v[132:135], v[218:221], v[92:95]
	v_mfma_f32_16x16x32_bf16 v[88:91], v[140:143], v[218:221], v[88:91]
	v_mfma_f32_16x16x32_bf16 v[76:79], v[132:135], v[226:229], v[76:79]
	v_mfma_f32_16x16x32_bf16 v[72:75], v[140:143], v[226:229], v[72:75]
	v_mfma_f32_16x16x32_bf16 v[116:119], v[144:147], v[174:177], v[116:119]
	v_mfma_f32_16x16x32_bf16 v[112:115], v[166:169], v[174:177], v[112:115]
	v_mfma_f32_16x16x32_bf16 v[100:103], v[144:147], v[206:209], v[100:103]
	v_mfma_f32_16x16x32_bf16 v[96:99], v[166:169], v[206:209], v[96:99]
	v_mfma_f32_16x16x32_bf16 v[84:87], v[144:147], v[214:217], v[84:87]
	v_mfma_f32_16x16x32_bf16 v[80:83], v[166:169], v[214:217], v[80:83]
	v_mfma_f32_16x16x32_bf16 v[68:71], v[144:147], v[222:225], v[68:71]
	v_mfma_f32_16x16x32_bf16 v[64:67], v[166:169], v[222:225], v[64:67]
	v_mfma_f32_16x16x32_bf16 v[116:119], v[148:151], v[178:181], v[116:119]
	v_mfma_f32_16x16x32_bf16 v[112:115], v[170:173], v[178:181], v[112:115]
	v_mfma_f32_16x16x32_bf16 v[100:103], v[148:151], v[210:213], v[100:103]
	v_mfma_f32_16x16x32_bf16 v[96:99], v[170:173], v[210:213], v[96:99]
	v_mfma_f32_16x16x32_bf16 v[84:87], v[148:151], v[218:221], v[84:87]
	v_mfma_f32_16x16x32_bf16 v[80:83], v[170:173], v[218:221], v[80:83]
	v_mfma_f32_16x16x32_bf16 v[68:71], v[148:151], v[226:229], v[68:71]
	v_mfma_f32_16x16x32_bf16 v[64:67], v[170:173], v[226:229], v[64:67]
	s_barrier
	s_add_i32 s65, s58, s50
	v_lshl_add_u64 v[182:183], s[42:43], 0, v[154:155]
	s_mov_b32 m0, s65
	ds_read_b128 v[174:177], v204 offset:16384
	ds_read_b128 v[178:181], v204 offset:17408
	ds_read_b128 v[206:209], v204 offset:18432
	ds_read_b128 v[210:213], v204 offset:19456
	ds_read_b128 v[214:217], v204 offset:20480
	ds_read_b128 v[218:221], v204 offset:21504
	ds_read_b128 v[222:225], v204 offset:22528
	ds_read_b128 v[226:229], v204 offset:23552
	global_load_lds_dwordx4 v[182:183], off
	s_add_i32 m0, s65, 0x2000
	s_add_u32 s66, s42, 0x100000
	v_lshl_add_u64 v[230:231], s[42:43], 0, v[158:159]
	s_addc_u32 s67, s43, 0
	s_add_i32 s65, s59, s50
	global_load_lds_dwordx4 v[230:231], off
	v_lshl_add_u64 v[232:233], s[66:67], 0, v[154:155]
	s_mov_b32 m0, s65
	v_lshl_add_u64 v[234:235], s[44:45], 0, v[156:157]
	global_load_lds_dwordx4 v[232:233], off
	v_lshl_add_u64 v[232:233], s[66:67], 0, v[158:159]
	s_add_i32 m0, s65, 0x2000
	s_nop 0
	global_load_lds_dwordx4 v[232:233], off
	v_lshl_add_u64 v[232:233], s[44:45], 0, v[152:153]
	s_mov_b32 m0, s39
	s_nop 0
	global_load_lds_dwordx4 v[232:233], off
	s_mov_b32 m0, s51
	s_nop 0
	global_load_lds_dwordx4 v[234:235], off
	s_waitcnt vmcnt(8)
	s_waitcnt lgkmcnt(0)
	s_barrier
	s_waitcnt lgkmcnt(0)
	v_mfma_f32_16x16x32_bf16 v[60:63], v[128:131], v[174:177], v[60:63]
	v_mfma_f32_16x16x32_bf16 v[56:59], v[136:139], v[174:177], v[56:59]
	v_mfma_f32_16x16x32_bf16 v[44:47], v[128:131], v[206:209], v[44:47]
	v_mfma_f32_16x16x32_bf16 v[40:43], v[136:139], v[206:209], v[40:43]
	v_mfma_f32_16x16x32_bf16 v[28:31], v[128:131], v[214:217], v[28:31]
	v_mfma_f32_16x16x32_bf16 v[24:27], v[136:139], v[214:217], v[24:27]
	v_mfma_f32_16x16x32_bf16 v[12:15], v[128:131], v[222:225], v[12:15]
	v_mfma_f32_16x16x32_bf16 v[8:11], v[136:139], v[222:225], v[8:11]
	v_mfma_f32_16x16x32_bf16 v[60:63], v[132:135], v[178:181], v[60:63]
	v_mfma_f32_16x16x32_bf16 v[56:59], v[140:143], v[178:181], v[56:59]
	v_mfma_f32_16x16x32_bf16 v[44:47], v[132:135], v[210:213], v[44:47]
	v_mfma_f32_16x16x32_bf16 v[40:43], v[140:143], v[210:213], v[40:43]
	v_mfma_f32_16x16x32_bf16 v[28:31], v[132:135], v[218:221], v[28:31]
	v_mfma_f32_16x16x32_bf16 v[24:27], v[140:143], v[218:221], v[24:27]
	v_mfma_f32_16x16x32_bf16 v[12:15], v[132:135], v[226:229], v[12:15]
	v_mfma_f32_16x16x32_bf16 v[8:11], v[140:143], v[226:229], v[8:11]
	v_mfma_f32_16x16x32_bf16 v[52:55], v[144:147], v[174:177], v[52:55]
	v_mfma_f32_16x16x32_bf16 v[48:51], v[166:169], v[174:177], v[48:51]
	v_mfma_f32_16x16x32_bf16 v[36:39], v[144:147], v[206:209], v[36:39]
	v_mfma_f32_16x16x32_bf16 v[32:35], v[166:169], v[206:209], v[32:35]
	v_mfma_f32_16x16x32_bf16 v[20:23], v[144:147], v[214:217], v[20:23]
	v_mfma_f32_16x16x32_bf16 v[16:19], v[166:169], v[214:217], v[16:19]
	v_mfma_f32_16x16x32_bf16 v[4:7], v[144:147], v[222:225], v[4:7]
	v_mfma_f32_16x16x32_bf16 v[0:3], v[166:169], v[222:225], v[0:3]
	v_mfma_f32_16x16x32_bf16 v[52:55], v[148:151], v[178:181], v[52:55]
	v_mfma_f32_16x16x32_bf16 v[48:51], v[170:173], v[178:181], v[48:51]
	v_mfma_f32_16x16x32_bf16 v[36:39], v[148:151], v[210:213], v[36:39]
	v_mfma_f32_16x16x32_bf16 v[32:35], v[170:173], v[210:213], v[32:35]
	v_mfma_f32_16x16x32_bf16 v[20:23], v[148:151], v[218:221], v[20:23]
	v_mfma_f32_16x16x32_bf16 v[16:19], v[170:173], v[218:221], v[16:19]
	v_mfma_f32_16x16x32_bf16 v[4:7], v[148:151], v[226:229], v[4:7]
	v_mfma_f32_16x16x32_bf16 v[0:3], v[170:173], v[226:229], v[0:3]
	s_barrier
	s_add_i32 s65, 0, 0x18000
	s_add_i32 s66, 0, 0x1c000
	v_add_u32_e32 v140, s65, v200
	v_add_u32_e32 v170, s66, v200
	ds_read_b128 v[128:131], v140
	ds_read_b128 v[132:135], v140 offset:1024
	ds_read_b128 v[136:139], v140 offset:2048
	ds_read_b128 v[140:143], v140 offset:3072
	ds_read_b128 v[144:147], v170
	ds_read_b128 v[148:151], v170 offset:1024
	ds_read_b128 v[166:169], v170 offset:2048
	ds_read_b128 v[170:173], v170 offset:3072
	s_add_u32 s44, s44, 0x100000
	s_addc_u32 s45, s45, 0
	s_mov_b32 m0, s52
	v_lshl_add_u64 v[236:237], s[44:45], 0, v[152:153]
	ds_read_b128 v[174:177], v204 offset:32768
	ds_read_b128 v[178:181], v204 offset:33792
	ds_read_b128 v[206:209], v204 offset:34816
	ds_read_b128 v[210:213], v204 offset:35840
	ds_read_b128 v[214:217], v204 offset:36864
	ds_read_b128 v[218:221], v204 offset:37888
	ds_read_b128 v[222:225], v204 offset:38912
	ds_read_b128 v[226:229], v204 offset:39936
	global_load_lds_dwordx4 v[236:237], off
	v_lshl_add_u64 v[236:237], s[44:45], 0, v[156:157]
	s_mov_b32 m0, s53
	s_nop 0
	global_load_lds_dwordx4 v[236:237], off
	s_waitcnt vmcnt(8)
	s_waitcnt lgkmcnt(0)
	s_barrier
	s_waitcnt lgkmcnt(0)
	v_mfma_f32_16x16x32_bf16 v[124:127], v[128:131], v[174:177], v[124:127]
	v_mfma_f32_16x16x32_bf16 v[120:123], v[136:139], v[174:177], v[120:123]
	v_mfma_f32_16x16x32_bf16 v[108:111], v[128:131], v[206:209], v[108:111]
	v_mfma_f32_16x16x32_bf16 v[104:107], v[136:139], v[206:209], v[104:107]
	v_mfma_f32_16x16x32_bf16 v[92:95], v[128:131], v[214:217], v[92:95]
	v_mfma_f32_16x16x32_bf16 v[88:91], v[136:139], v[214:217], v[88:91]
	v_mfma_f32_16x16x32_bf16 v[76:79], v[128:131], v[222:225], v[76:79]
	v_mfma_f32_16x16x32_bf16 v[72:75], v[136:139], v[222:225], v[72:75]
	v_mfma_f32_16x16x32_bf16 v[124:127], v[132:135], v[178:181], v[124:127]
	v_mfma_f32_16x16x32_bf16 v[120:123], v[140:143], v[178:181], v[120:123]
	v_mfma_f32_16x16x32_bf16 v[108:111], v[132:135], v[210:213], v[108:111]
	v_mfma_f32_16x16x32_bf16 v[104:107], v[140:143], v[210:213], v[104:107]
	v_mfma_f32_16x16x32_bf16 v[92:95], v[132:135], v[218:221], v[92:95]
	v_mfma_f32_16x16x32_bf16 v[88:91], v[140:143], v[218:221], v[88:91]
	v_mfma_f32_16x16x32_bf16 v[76:79], v[132:135], v[226:229], v[76:79]
	v_mfma_f32_16x16x32_bf16 v[72:75], v[140:143], v[226:229], v[72:75]
	v_mfma_f32_16x16x32_bf16 v[116:119], v[144:147], v[174:177], v[116:119]
	v_mfma_f32_16x16x32_bf16 v[112:115], v[166:169], v[174:177], v[112:115]
	v_mfma_f32_16x16x32_bf16 v[100:103], v[144:147], v[206:209], v[100:103]
	v_mfma_f32_16x16x32_bf16 v[96:99], v[166:169], v[206:209], v[96:99]
	v_mfma_f32_16x16x32_bf16 v[84:87], v[144:147], v[214:217], v[84:87]
	v_mfma_f32_16x16x32_bf16 v[80:83], v[166:169], v[214:217], v[80:83]
	v_mfma_f32_16x16x32_bf16 v[68:71], v[144:147], v[222:225], v[68:71]
	v_mfma_f32_16x16x32_bf16 v[64:67], v[166:169], v[222:225], v[64:67]
	v_mfma_f32_16x16x32_bf16 v[116:119], v[148:151], v[178:181], v[116:119]
	v_mfma_f32_16x16x32_bf16 v[112:115], v[170:173], v[178:181], v[112:115]
	v_mfma_f32_16x16x32_bf16 v[100:103], v[148:151], v[210:213], v[100:103]
	v_mfma_f32_16x16x32_bf16 v[96:99], v[170:173], v[210:213], v[96:99]
	v_mfma_f32_16x16x32_bf16 v[84:87], v[148:151], v[218:221], v[84:87]
	v_mfma_f32_16x16x32_bf16 v[80:83], v[170:173], v[218:221], v[80:83]
	v_mfma_f32_16x16x32_bf16 v[68:71], v[148:151], v[226:229], v[68:71]
	v_mfma_f32_16x16x32_bf16 v[64:67], v[170:173], v[226:229], v[64:67]
	s_barrier
	s_add_i32 s44, s65, s50
	v_lshl_add_u64 v[182:183], v[182:183], 0, s[18:19]
	s_mov_b32 m0, s44
	ds_read_b128 v[174:177], v204 offset:49152
	ds_read_b128 v[178:181], v204 offset:50176
	ds_read_b128 v[206:209], v204 offset:51200
	ds_read_b128 v[210:213], v204 offset:52224
	ds_read_b128 v[214:217], v204 offset:53248
	ds_read_b128 v[218:221], v204 offset:54272
	ds_read_b128 v[222:225], v204 offset:55296
	ds_read_b128 v[226:229], v204 offset:56320
	global_load_lds_dwordx4 v[182:183], off
	s_add_i32 m0, s44, 0x2000
	s_add_u32 s42, s42, 0x100080
	v_lshl_add_u64 v[182:183], v[230:231], 0, s[18:19]
	s_addc_u32 s43, s43, 0
	s_add_i32 s44, s66, s50
	global_load_lds_dwordx4 v[182:183], off
	v_lshl_add_u64 v[182:183], s[42:43], 0, v[154:155]
	s_mov_b32 m0, s44
	s_nop 0
	global_load_lds_dwordx4 v[182:183], off
	v_lshl_add_u64 v[182:183], s[42:43], 0, v[158:159]
	s_add_i32 m0, s44, 0x2000
	s_nop 0
	global_load_lds_dwordx4 v[182:183], off
	v_lshl_add_u64 v[182:183], v[232:233], 0, s[18:19]
	s_mov_b32 m0, s54
	s_nop 0
	global_load_lds_dwordx4 v[182:183], off
	v_lshl_add_u64 v[182:183], v[234:235], 0, s[18:19]
	s_mov_b32 m0, s55
	s_nop 0
	global_load_lds_dwordx4 v[182:183], off
	s_waitcnt vmcnt(8)
	s_waitcnt lgkmcnt(0)
	s_barrier
	s_waitcnt lgkmcnt(0)
	v_mfma_f32_16x16x32_bf16 v[60:63], v[128:131], v[174:177], v[60:63]
	v_mfma_f32_16x16x32_bf16 v[56:59], v[136:139], v[174:177], v[56:59]
	v_mfma_f32_16x16x32_bf16 v[44:47], v[128:131], v[206:209], v[44:47]
	v_mfma_f32_16x16x32_bf16 v[40:43], v[136:139], v[206:209], v[40:43]
	v_mfma_f32_16x16x32_bf16 v[28:31], v[128:131], v[214:217], v[28:31]
	v_mfma_f32_16x16x32_bf16 v[24:27], v[136:139], v[214:217], v[24:27]
	v_mfma_f32_16x16x32_bf16 v[12:15], v[128:131], v[222:225], v[12:15]
	v_mfma_f32_16x16x32_bf16 v[8:11], v[136:139], v[222:225], v[8:11]
	v_mfma_f32_16x16x32_bf16 v[60:63], v[132:135], v[178:181], v[60:63]
	v_mfma_f32_16x16x32_bf16 v[56:59], v[140:143], v[178:181], v[56:59]
	v_mfma_f32_16x16x32_bf16 v[44:47], v[132:135], v[210:213], v[44:47]
	v_mfma_f32_16x16x32_bf16 v[40:43], v[140:143], v[210:213], v[40:43]
	v_mfma_f32_16x16x32_bf16 v[28:31], v[132:135], v[218:221], v[28:31]
	v_mfma_f32_16x16x32_bf16 v[24:27], v[140:143], v[218:221], v[24:27]
	v_mfma_f32_16x16x32_bf16 v[12:15], v[132:135], v[226:229], v[12:15]
	v_mfma_f32_16x16x32_bf16 v[8:11], v[140:143], v[226:229], v[8:11]
	v_mfma_f32_16x16x32_bf16 v[52:55], v[144:147], v[174:177], v[52:55]
	v_mfma_f32_16x16x32_bf16 v[48:51], v[166:169], v[174:177], v[48:51]
	v_mfma_f32_16x16x32_bf16 v[36:39], v[144:147], v[206:209], v[36:39]
	v_mfma_f32_16x16x32_bf16 v[32:35], v[166:169], v[206:209], v[32:35]
	v_mfma_f32_16x16x32_bf16 v[20:23], v[144:147], v[214:217], v[20:23]
	v_mfma_f32_16x16x32_bf16 v[16:19], v[166:169], v[214:217], v[16:19]
	v_mfma_f32_16x16x32_bf16 v[4:7], v[144:147], v[222:225], v[4:7]
	v_mfma_f32_16x16x32_bf16 v[0:3], v[166:169], v[222:225], v[0:3]
	v_mfma_f32_16x16x32_bf16 v[52:55], v[148:151], v[178:181], v[52:55]
	v_mfma_f32_16x16x32_bf16 v[48:51], v[170:173], v[178:181], v[48:51]
	v_mfma_f32_16x16x32_bf16 v[36:39], v[148:151], v[210:213], v[36:39]
	v_mfma_f32_16x16x32_bf16 v[32:35], v[170:173], v[210:213], v[32:35]
	v_mfma_f32_16x16x32_bf16 v[20:23], v[148:151], v[218:221], v[20:23]
	v_mfma_f32_16x16x32_bf16 v[16:19], v[170:173], v[218:221], v[16:19]
	v_mfma_f32_16x16x32_bf16 v[4:7], v[148:151], v[226:229], v[4:7]
	v_mfma_f32_16x16x32_bf16 v[0:3], v[170:173], v[226:229], v[0:3]
	s_barrier
	s_add_i32 s64, s64, 2
	s_add_u32 s40, s40, 0x100
	s_addc_u32 s41, s41, 0
	s_add_u32 s62, s62, 0x100
	s_addc_u32 s63, s63, 0
	s_cmp_gt_u32 s64, 61
	s_cbranch_scc0 .LBB0_934
	s_and_b64 vcc, exec, s[20:21]
	s_cbranch_vccz .LBB0_937
	s_barrier

.LBB0_981:
	ds_read_b128 v[148:151], v145
	ds_read_b128 v[152:155], v145 offset:1024
	ds_read_b128 v[156:159], v145 offset:2048
	ds_read_b128 v[160:163], v145 offset:3072
	ds_read_b128 v[164:167], v146
	ds_read_b128 v[168:171], v146 offset:1024
	ds_read_b128 v[172:175], v146 offset:2048
	ds_read_b128 v[176:179], v146 offset:3072
	s_add_i32 s78, s42, 2
	s_add_u32 s79, s40, 0x80
	s_addc_u32 s43, s41, 0
	s_cmp_eq_u32 s60, s42
	s_cselect_b32 s42, s36, s79
	s_cselect_b32 s43, s37, s43
	s_cselect_b32 s81, s39, s77
	s_cselect_b32 s80, s38, s76
	v_lshl_add_u64 v[214:215], s[40:41], 0, v[136:137]
	s_add_i32 m0, s50, 0xc000
	ds_read_b128 v[180:183], v147
	ds_read_b128 v[184:187], v147 offset:1024
	ds_read_b128 v[188:191], v147 offset:2048
	ds_read_b128 v[194:197], v147 offset:3072
	ds_read_b128 v[198:201], v147 offset:4096
	ds_read_b128 v[202:205], v147 offset:5120
	ds_read_b128 v[206:209], v147 offset:6144
	ds_read_b128 v[210:213], v147 offset:7168
	global_load_lds_dwordx4 v[214:215], off
	v_lshl_add_u64 v[214:215], s[40:41], 0, v[138:139]
	s_add_i32 m0, s50, 0xe000
	s_nop 0
	global_load_lds_dwordx4 v[214:215], off
	s_waitcnt vmcnt(8)
	s_waitcnt lgkmcnt(0)
	s_barrier
	s_waitcnt lgkmcnt(0)
	v_mfma_f32_16x16x32_bf16 v[120:123], v[148:151], v[180:183], v[120:123]
	v_mfma_f32_16x16x32_bf16 v[124:127], v[156:159], v[180:183], v[124:127]
	v_mfma_f32_16x16x32_bf16 v[108:111], v[148:151], v[188:191], v[108:111]
	v_mfma_f32_16x16x32_bf16 v[104:107], v[156:159], v[188:191], v[104:107]
	v_mfma_f32_16x16x32_bf16 v[92:95], v[148:151], v[198:201], v[92:95]
	v_mfma_f32_16x16x32_bf16 v[88:91], v[156:159], v[198:201], v[88:91]
	v_mfma_f32_16x16x32_bf16 v[76:79], v[148:151], v[206:209], v[76:79]
	v_mfma_f32_16x16x32_bf16 v[72:75], v[156:159], v[206:209], v[72:75]
	v_mfma_f32_16x16x32_bf16 v[120:123], v[152:155], v[184:187], v[120:123]
	v_mfma_f32_16x16x32_bf16 v[124:127], v[160:163], v[184:187], v[124:127]
	v_mfma_f32_16x16x32_bf16 v[108:111], v[152:155], v[194:197], v[108:111]
	v_mfma_f32_16x16x32_bf16 v[104:107], v[160:163], v[194:197], v[104:107]
	v_mfma_f32_16x16x32_bf16 v[92:95], v[152:155], v[202:205], v[92:95]
	v_mfma_f32_16x16x32_bf16 v[88:91], v[160:163], v[202:205], v[88:91]
	v_mfma_f32_16x16x32_bf16 v[76:79], v[152:155], v[210:213], v[76:79]
	v_mfma_f32_16x16x32_bf16 v[72:75], v[160:163], v[210:213], v[72:75]
	v_mfma_f32_16x16x32_bf16 v[116:119], v[164:167], v[180:183], v[116:119]
	v_mfma_f32_16x16x32_bf16 v[112:115], v[172:175], v[180:183], v[112:115]
	v_mfma_f32_16x16x32_bf16 v[100:103], v[164:167], v[188:191], v[100:103]
	v_mfma_f32_16x16x32_bf16 v[96:99], v[172:175], v[188:191], v[96:99]
	v_mfma_f32_16x16x32_bf16 v[84:87], v[164:167], v[198:201], v[84:87]
	v_mfma_f32_16x16x32_bf16 v[80:83], v[172:175], v[198:201], v[80:83]
	v_mfma_f32_16x16x32_bf16 v[68:71], v[164:167], v[206:209], v[68:71]
	v_mfma_f32_16x16x32_bf16 v[64:67], v[172:175], v[206:209], v[64:67]
	v_mfma_f32_16x16x32_bf16 v[116:119], v[168:171], v[184:187], v[116:119]
	v_mfma_f32_16x16x32_bf16 v[112:115], v[176:179], v[184:187], v[112:115]
	v_mfma_f32_16x16x32_bf16 v[100:103], v[168:171], v[194:197], v[100:103]
	v_mfma_f32_16x16x32_bf16 v[96:99], v[176:179], v[194:197], v[96:99]
	v_mfma_f32_16x16x32_bf16 v[84:87], v[168:171], v[202:205], v[84:87]
	v_mfma_f32_16x16x32_bf16 v[80:83], v[176:179], v[202:205], v[80:83]
	v_mfma_f32_16x16x32_bf16 v[68:71], v[168:171], v[210:213], v[68:71]
	v_mfma_f32_16x16x32_bf16 v[64:67], v[176:179], v[210:213], v[64:67]
	s_barrier
	s_add_i32 s79, s61, s49
	v_lshl_add_u64 v[214:215], s[80:81], 0, v[130:131]
	s_mov_b32 m0, s79
	ds_read_b128 v[180:183], v147 offset:16384
	ds_read_b128 v[184:187], v147 offset:17408
	ds_read_b128 v[188:191], v147 offset:18432
	ds_read_b128 v[194:197], v147 offset:19456
	ds_read_b128 v[198:201], v147 offset:20480
	ds_read_b128 v[202:205], v147 offset:21504
	ds_read_b128 v[206:209], v147 offset:22528
	ds_read_b128 v[210:213], v147 offset:23552
	global_load_lds_dwordx4 v[214:215], off
	s_add_i32 m0, s79, 0x2000
	v_lshl_add_u64 v[216:217], s[80:81], 0, v[134:135]
	s_add_u32 s80, s80, s6
	s_addc_u32 s81, s81, s7
	s_add_i32 s79, s62, s49
	global_load_lds_dwordx4 v[216:217], off
	v_lshl_add_u64 v[218:219], s[80:81], 0, v[130:131]
	s_mov_b32 m0, s79
	v_lshl_add_u64 v[220:221], s[80:81], 0, v[134:135]
	global_load_lds_dwordx4 v[218:219], off
	s_add_i32 m0, s79, 0x2000
	v_lshl_add_u64 v[222:223], s[42:43], 0, v[128:129]
	global_load_lds_dwordx4 v[220:221], off
	s_mov_b32 m0, s50
	v_lshl_add_u64 v[224:225], s[42:43], 0, v[132:133]
	global_load_lds_dwordx4 v[222:223], off
	s_mov_b32 m0, s51
	s_nop 0
	global_load_lds_dwordx4 v[224:225], off
	s_waitcnt vmcnt(8)
	s_waitcnt lgkmcnt(0)
	s_barrier
	s_waitcnt lgkmcnt(0)
	v_mfma_f32_16x16x32_bf16 v[60:63], v[148:151], v[180:183], v[60:63]
	v_mfma_f32_16x16x32_bf16 v[56:59], v[156:159], v[180:183], v[56:59]
	v_mfma_f32_16x16x32_bf16 v[44:47], v[148:151], v[188:191], v[44:47]
	v_mfma_f32_16x16x32_bf16 v[40:43], v[156:159], v[188:191], v[40:43]
	v_mfma_f32_16x16x32_bf16 v[28:31], v[148:151], v[198:201], v[28:31]
	v_mfma_f32_16x16x32_bf16 v[24:27], v[156:159], v[198:201], v[24:27]
	v_mfma_f32_16x16x32_bf16 v[12:15], v[148:151], v[206:209], v[12:15]
	v_mfma_f32_16x16x32_bf16 v[8:11], v[156:159], v[206:209], v[8:11]
	v_mfma_f32_16x16x32_bf16 v[60:63], v[152:155], v[184:187], v[60:63]
	v_mfma_f32_16x16x32_bf16 v[56:59], v[160:163], v[184:187], v[56:59]
	v_mfma_f32_16x16x32_bf16 v[44:47], v[152:155], v[194:197], v[44:47]
	v_mfma_f32_16x16x32_bf16 v[40:43], v[160:163], v[194:197], v[40:43]
	v_mfma_f32_16x16x32_bf16 v[28:31], v[152:155], v[202:205], v[28:31]
	v_mfma_f32_16x16x32_bf16 v[24:27], v[160:163], v[202:205], v[24:27]
	v_mfma_f32_16x16x32_bf16 v[12:15], v[152:155], v[210:213], v[12:15]
	v_mfma_f32_16x16x32_bf16 v[8:11], v[160:163], v[210:213], v[8:11]
	v_mfma_f32_16x16x32_bf16 v[52:55], v[164:167], v[180:183], v[52:55]
	v_mfma_f32_16x16x32_bf16 v[48:51], v[172:175], v[180:183], v[48:51]
	v_mfma_f32_16x16x32_bf16 v[36:39], v[164:167], v[188:191], v[36:39]
	v_mfma_f32_16x16x32_bf16 v[32:35], v[172:175], v[188:191], v[32:35]
	v_mfma_f32_16x16x32_bf16 v[20:23], v[164:167], v[198:201], v[20:23]
	v_mfma_f32_16x16x32_bf16 v[16:19], v[172:175], v[198:201], v[16:19]
	v_mfma_f32_16x16x32_bf16 v[4:7], v[164:167], v[206:209], v[4:7]
	v_mfma_f32_16x16x32_bf16 v[0:3], v[172:175], v[206:209], v[0:3]
	v_mfma_f32_16x16x32_bf16 v[52:55], v[168:171], v[184:187], v[52:55]
	v_mfma_f32_16x16x32_bf16 v[48:51], v[176:179], v[184:187], v[48:51]
	v_mfma_f32_16x16x32_bf16 v[36:39], v[168:171], v[194:197], v[36:39]
	v_mfma_f32_16x16x32_bf16 v[32:35], v[176:179], v[194:197], v[32:35]
	v_mfma_f32_16x16x32_bf16 v[20:23], v[168:171], v[202:205], v[20:23]
	v_mfma_f32_16x16x32_bf16 v[16:19], v[176:179], v[202:205], v[16:19]
	v_mfma_f32_16x16x32_bf16 v[4:7], v[168:171], v[210:213], v[4:7]
	v_mfma_f32_16x16x32_bf16 v[0:3], v[176:179], v[210:213], v[0:3]
	s_barrier
	s_add_i32 s79, 0, 0x18000
	s_add_i32 s80, 0, 0x1c000
	v_add_u32_e32 v160, s79, v143
	v_add_u32_e32 v176, s80, v143
	ds_read_b128 v[148:151], v160
	ds_read_b128 v[152:155], v160 offset:1024
	ds_read_b128 v[156:159], v160 offset:2048
	ds_read_b128 v[160:163], v160 offset:3072
	ds_read_b128 v[164:167], v176
	ds_read_b128 v[168:171], v176 offset:1024
	ds_read_b128 v[172:175], v176 offset:2048
	ds_read_b128 v[176:179], v176 offset:3072
	s_add_u32 s42, s42, s6
	s_addc_u32 s43, s43, s7
	s_mov_b32 m0, s52
	v_lshl_add_u64 v[226:227], s[42:43], 0, v[128:129]
	ds_read_b128 v[180:183], v147 offset:32768
	ds_read_b128 v[184:187], v147 offset:33792
	ds_read_b128 v[188:191], v147 offset:34816
	ds_read_b128 v[194:197], v147 offset:35840
	ds_read_b128 v[198:201], v147 offset:36864
	ds_read_b128 v[202:205], v147 offset:37888
	ds_read_b128 v[206:209], v147 offset:38912
	ds_read_b128 v[210:213], v147 offset:39936
	global_load_lds_dwordx4 v[226:227], off
	v_lshl_add_u64 v[226:227], s[42:43], 0, v[132:133]
	s_mov_b32 m0, s53
	s_nop 0
	global_load_lds_dwordx4 v[226:227], off
	s_waitcnt vmcnt(8)
	s_waitcnt lgkmcnt(0)
	s_barrier
	s_waitcnt lgkmcnt(0)
	v_mfma_f32_16x16x32_bf16 v[120:123], v[148:151], v[180:183], v[120:123]
	v_mfma_f32_16x16x32_bf16 v[124:127], v[156:159], v[180:183], v[124:127]
	v_mfma_f32_16x16x32_bf16 v[108:111], v[148:151], v[188:191], v[108:111]
	v_mfma_f32_16x16x32_bf16 v[104:107], v[156:159], v[188:191], v[104:107]
	v_mfma_f32_16x16x32_bf16 v[92:95], v[148:151], v[198:201], v[92:95]
	v_mfma_f32_16x16x32_bf16 v[88:91], v[156:159], v[198:201], v[88:91]
	v_mfma_f32_16x16x32_bf16 v[76:79], v[148:151], v[206:209], v[76:79]
	v_mfma_f32_16x16x32_bf16 v[72:75], v[156:159], v[206:209], v[72:75]
	v_mfma_f32_16x16x32_bf16 v[120:123], v[152:155], v[184:187], v[120:123]
	v_mfma_f32_16x16x32_bf16 v[124:127], v[160:163], v[184:187], v[124:127]
	v_mfma_f32_16x16x32_bf16 v[108:111], v[152:155], v[194:197], v[108:111]
	v_mfma_f32_16x16x32_bf16 v[104:107], v[160:163], v[194:197], v[104:107]
	v_mfma_f32_16x16x32_bf16 v[92:95], v[152:155], v[202:205], v[92:95]
	v_mfma_f32_16x16x32_bf16 v[88:91], v[160:163], v[202:205], v[88:91]
	v_mfma_f32_16x16x32_bf16 v[76:79], v[152:155], v[210:213], v[76:79]
	v_mfma_f32_16x16x32_bf16 v[72:75], v[160:163], v[210:213], v[72:75]
	v_mfma_f32_16x16x32_bf16 v[116:119], v[164:167], v[180:183], v[116:119]
	v_mfma_f32_16x16x32_bf16 v[112:115], v[172:175], v[180:183], v[112:115]
	v_mfma_f32_16x16x32_bf16 v[100:103], v[164:167], v[188:191], v[100:103]
	v_mfma_f32_16x16x32_bf16 v[96:99], v[172:175], v[188:191], v[96:99]
	v_mfma_f32_16x16x32_bf16 v[84:87], v[164:167], v[198:201], v[84:87]
	v_mfma_f32_16x16x32_bf16 v[80:83], v[172:175], v[198:201], v[80:83]
	v_mfma_f32_16x16x32_bf16 v[68:71], v[164:167], v[206:209], v[68:71]
	v_mfma_f32_16x16x32_bf16 v[64:67], v[172:175], v[206:209], v[64:67]
	v_mfma_f32_16x16x32_bf16 v[116:119], v[168:171], v[184:187], v[116:119]
	v_mfma_f32_16x16x32_bf16 v[112:115], v[176:179], v[184:187], v[112:115]
	v_mfma_f32_16x16x32_bf16 v[100:103], v[168:171], v[194:197], v[100:103]
	v_mfma_f32_16x16x32_bf16 v[96:99], v[176:179], v[194:197], v[96:99]
	v_mfma_f32_16x16x32_bf16 v[84:87], v[168:171], v[202:205], v[84:87]
	v_mfma_f32_16x16x32_bf16 v[80:83], v[176:179], v[202:205], v[80:83]
	v_mfma_f32_16x16x32_bf16 v[68:71], v[168:171], v[210:213], v[68:71]
	v_mfma_f32_16x16x32_bf16 v[64:67], v[176:179], v[210:213], v[64:67]
	s_barrier
	s_add_i32 s42, s79, s49
	v_lshl_add_u64 v[214:215], v[214:215], 0, s[18:19]
	s_mov_b32 m0, s42
	ds_read_b128 v[180:183], v147 offset:49152
	ds_read_b128 v[184:187], v147 offset:50176
	ds_read_b128 v[188:191], v147 offset:51200
	ds_read_b128 v[194:197], v147 offset:52224
	ds_read_b128 v[198:201], v147 offset:53248
	ds_read_b128 v[202:205], v147 offset:54272
	ds_read_b128 v[206:209], v147 offset:55296
	ds_read_b128 v[210:213], v147 offset:56320
	global_load_lds_dwordx4 v[214:215], off
	v_lshl_add_u64 v[214:215], v[216:217], 0, s[18:19]
	s_add_i32 m0, s42, 0x2000
	s_add_i32 s42, s80, s49
	global_load_lds_dwordx4 v[214:215], off
	v_lshl_add_u64 v[214:215], v[218:219], 0, s[18:19]
	s_mov_b32 m0, s42
	s_nop 0
	global_load_lds_dwordx4 v[214:215], off
	v_lshl_add_u64 v[214:215], v[220:221], 0, s[18:19]
	s_add_i32 m0, s42, 0x2000
	s_nop 0
	global_load_lds_dwordx4 v[214:215], off
	v_lshl_add_u64 v[214:215], v[222:223], 0, s[18:19]
	s_mov_b32 m0, s55
	s_nop 0
	global_load_lds_dwordx4 v[214:215], off
	v_lshl_add_u64 v[214:215], v[224:225], 0, s[18:19]
	s_mov_b32 m0, s56
	s_nop 0
	global_load_lds_dwordx4 v[214:215], off
	s_waitcnt vmcnt(8)
	s_waitcnt lgkmcnt(0)
	s_barrier
	s_waitcnt lgkmcnt(0)
	v_mfma_f32_16x16x32_bf16 v[60:63], v[148:151], v[180:183], v[60:63]
	v_mfma_f32_16x16x32_bf16 v[56:59], v[156:159], v[180:183], v[56:59]
	v_mfma_f32_16x16x32_bf16 v[44:47], v[148:151], v[188:191], v[44:47]
	v_mfma_f32_16x16x32_bf16 v[40:43], v[156:159], v[188:191], v[40:43]
	v_mfma_f32_16x16x32_bf16 v[28:31], v[148:151], v[198:201], v[28:31]
	v_mfma_f32_16x16x32_bf16 v[24:27], v[156:159], v[198:201], v[24:27]
	v_mfma_f32_16x16x32_bf16 v[12:15], v[148:151], v[206:209], v[12:15]
	v_mfma_f32_16x16x32_bf16 v[8:11], v[156:159], v[206:209], v[8:11]
	v_mfma_f32_16x16x32_bf16 v[60:63], v[152:155], v[184:187], v[60:63]
	v_mfma_f32_16x16x32_bf16 v[56:59], v[160:163], v[184:187], v[56:59]
	v_mfma_f32_16x16x32_bf16 v[44:47], v[152:155], v[194:197], v[44:47]
	v_mfma_f32_16x16x32_bf16 v[40:43], v[160:163], v[194:197], v[40:43]
	v_mfma_f32_16x16x32_bf16 v[28:31], v[152:155], v[202:205], v[28:31]
	v_mfma_f32_16x16x32_bf16 v[24:27], v[160:163], v[202:205], v[24:27]
	v_mfma_f32_16x16x32_bf16 v[12:15], v[152:155], v[210:213], v[12:15]
	v_mfma_f32_16x16x32_bf16 v[8:11], v[160:163], v[210:213], v[8:11]
	v_mfma_f32_16x16x32_bf16 v[52:55], v[164:167], v[180:183], v[52:55]
	v_mfma_f32_16x16x32_bf16 v[48:51], v[172:175], v[180:183], v[48:51]
	v_mfma_f32_16x16x32_bf16 v[36:39], v[164:167], v[188:191], v[36:39]
	v_mfma_f32_16x16x32_bf16 v[32:35], v[172:175], v[188:191], v[32:35]
	v_mfma_f32_16x16x32_bf16 v[20:23], v[164:167], v[198:201], v[20:23]
	v_mfma_f32_16x16x32_bf16 v[16:19], v[172:175], v[198:201], v[16:19]
	v_mfma_f32_16x16x32_bf16 v[4:7], v[164:167], v[206:209], v[4:7]
	v_mfma_f32_16x16x32_bf16 v[0:3], v[172:175], v[206:209], v[0:3]
	v_mfma_f32_16x16x32_bf16 v[52:55], v[168:171], v[184:187], v[52:55]
	v_mfma_f32_16x16x32_bf16 v[48:51], v[176:179], v[184:187], v[48:51]
	v_mfma_f32_16x16x32_bf16 v[36:39], v[168:171], v[194:197], v[36:39]
	v_mfma_f32_16x16x32_bf16 v[32:35], v[176:179], v[194:197], v[32:35]
	v_mfma_f32_16x16x32_bf16 v[20:23], v[168:171], v[202:205], v[20:23]
	v_mfma_f32_16x16x32_bf16 v[16:19], v[176:179], v[202:205], v[16:19]
	v_mfma_f32_16x16x32_bf16 v[4:7], v[168:171], v[210:213], v[4:7]
	v_mfma_f32_16x16x32_bf16 v[0:3], v[176:179], v[210:213], v[0:3]
	s_barrier
	s_add_u32 s40, s40, 0x100
	s_addc_u32 s41, s41, 0
	s_add_u32 s76, s76, 0x100
	s_addc_u32 s77, s77, 0
	s_cmp_ge_i32 s78, s59
	s_mov_b32 s42, s78
	s_cbranch_scc0 .LBB0_981

.LBB0_1063:
	s_waitcnt lgkmcnt(0)
	s_barrier
	s_waitcnt lgkmcnt(0)
	v_mfma_f32_16x16x32_bf16 v[60:63], v[144:147], v[184:187], v[60:63]
	v_mfma_f32_16x16x32_bf16 v[56:59], v[152:155], v[184:187], v[56:59]
	v_mfma_f32_16x16x32_bf16 v[44:47], v[144:147], v[176:179], v[44:47]
	v_mfma_f32_16x16x32_bf16 v[40:43], v[152:155], v[176:179], v[40:43]
	v_mfma_f32_16x16x32_bf16 v[28:31], v[144:147], v[168:171], v[28:31]
	v_mfma_f32_16x16x32_bf16 v[24:27], v[152:155], v[168:171], v[24:27]
	v_mfma_f32_16x16x32_bf16 v[12:15], v[144:147], v[160:163], v[12:15]
	v_mfma_f32_16x16x32_bf16 v[8:11], v[152:155], v[160:163], v[8:11]
	v_mfma_f32_16x16x32_bf16 v[60:63], v[148:151], v[188:191], v[60:63]
	v_mfma_f32_16x16x32_bf16 v[56:59], v[156:159], v[188:191], v[56:59]
	v_mfma_f32_16x16x32_bf16 v[44:47], v[148:151], v[180:183], v[44:47]
	v_mfma_f32_16x16x32_bf16 v[40:43], v[156:159], v[180:183], v[40:43]
	v_mfma_f32_16x16x32_bf16 v[28:31], v[148:151], v[172:175], v[28:31]
	v_mfma_f32_16x16x32_bf16 v[24:27], v[156:159], v[172:175], v[24:27]
	v_mfma_f32_16x16x32_bf16 v[12:15], v[148:151], v[164:167], v[12:15]
	v_mfma_f32_16x16x32_bf16 v[8:11], v[156:159], v[164:167], v[8:11]
	v_mfma_f32_16x16x32_bf16 v[52:55], v[124:127], v[184:187], v[52:55]
	v_mfma_f32_16x16x32_bf16 v[48:51], v[136:139], v[184:187], v[48:51]
	v_mfma_f32_16x16x32_bf16 v[36:39], v[124:127], v[176:179], v[36:39]
	v_mfma_f32_16x16x32_bf16 v[32:35], v[136:139], v[176:179], v[32:35]
	v_mfma_f32_16x16x32_bf16 v[20:23], v[124:127], v[168:171], v[20:23]
	v_mfma_f32_16x16x32_bf16 v[16:19], v[136:139], v[168:171], v[16:19]
	v_mfma_f32_16x16x32_bf16 v[4:7], v[124:127], v[160:163], v[4:7]
	v_mfma_f32_16x16x32_bf16 v[0:3], v[136:139], v[160:163], v[0:3]
	v_mfma_f32_16x16x32_bf16 v[52:55], v[132:135], v[188:191], v[52:55]
	v_mfma_f32_16x16x32_bf16 v[48:51], v[140:143], v[188:191], v[48:51]
	v_mfma_f32_16x16x32_bf16 v[36:39], v[132:135], v[180:183], v[36:39]
	v_mfma_f32_16x16x32_bf16 v[32:35], v[140:143], v[180:183], v[32:35]
	v_mfma_f32_16x16x32_bf16 v[20:23], v[132:135], v[172:175], v[20:23]
	v_mfma_f32_16x16x32_bf16 v[16:19], v[140:143], v[172:175], v[16:19]
	v_mfma_f32_16x16x32_bf16 v[4:7], v[132:135], v[164:167], v[4:7]
	v_mfma_f32_16x16x32_bf16 v[0:3], v[140:143], v[164:167], v[0:3]
	s_barrier
	s_add_i32 s46, 0, 0x18000
	s_add_i32 s47, 0, 0x1c000
	v_add_u32_e32 v140, s46, v220
	v_add_u32_e32 v156, s47, v220
	ds_read_b128 v[124:127], v140
	ds_read_b128 v[132:135], v140 offset:1024
	ds_read_b128 v[136:139], v140 offset:2048
	ds_read_b128 v[140:143], v140 offset:3072
	ds_read_b128 v[144:147], v156
	ds_read_b128 v[148:151], v156 offset:1024
	ds_read_b128 v[152:155], v156 offset:2048
	ds_read_b128 v[156:159], v156 offset:3072
	s_add_u32 s42, s44, 0x40000
	s_addc_u32 s43, s45, 0
	s_mov_b32 m0, s57
	v_lshl_add_u64 v[234:235], s[42:43], 0, v[194:195]
	ds_read_b128 v[160:163], v224 offset:32768
	ds_read_b128 v[164:167], v224 offset:33792
	ds_read_b128 v[168:171], v224 offset:34816
	ds_read_b128 v[172:175], v224 offset:35840
	ds_read_b128 v[176:179], v224 offset:36864
	ds_read_b128 v[180:183], v224 offset:37888
	ds_read_b128 v[184:187], v224 offset:38912
	ds_read_b128 v[188:191], v224 offset:39936
	global_load_lds_dwordx4 v[234:235], off
	v_lshl_add_u64 v[234:235], s[42:43], 0, v[198:199]
	s_mov_b32 m0, s58
	s_nop 0
	global_load_lds_dwordx4 v[234:235], off
	s_waitcnt vmcnt(8)
	s_waitcnt lgkmcnt(0)
	s_barrier
	s_waitcnt lgkmcnt(0)
	v_mfma_f32_16x16x32_bf16 v[128:131], v[124:127], v[160:163], v[128:131]
	v_mfma_f32_16x16x32_bf16 v[120:123], v[136:139], v[160:163], v[120:123]
	v_mfma_f32_16x16x32_bf16 v[108:111], v[124:127], v[168:171], v[108:111]
	v_mfma_f32_16x16x32_bf16 v[104:107], v[136:139], v[168:171], v[104:107]
	v_mfma_f32_16x16x32_bf16 v[92:95], v[124:127], v[176:179], v[92:95]
	v_mfma_f32_16x16x32_bf16 v[88:91], v[136:139], v[176:179], v[88:91]
	v_mfma_f32_16x16x32_bf16 v[76:79], v[124:127], v[184:187], v[76:79]
	v_mfma_f32_16x16x32_bf16 v[72:75], v[136:139], v[184:187], v[72:75]
	v_mfma_f32_16x16x32_bf16 v[128:131], v[132:135], v[164:167], v[128:131]
	v_mfma_f32_16x16x32_bf16 v[120:123], v[140:143], v[164:167], v[120:123]
	v_mfma_f32_16x16x32_bf16 v[108:111], v[132:135], v[172:175], v[108:111]
	v_mfma_f32_16x16x32_bf16 v[104:107], v[140:143], v[172:175], v[104:107]
	v_mfma_f32_16x16x32_bf16 v[92:95], v[132:135], v[180:183], v[92:95]
	v_mfma_f32_16x16x32_bf16 v[88:91], v[140:143], v[180:183], v[88:91]
	v_mfma_f32_16x16x32_bf16 v[76:79], v[132:135], v[188:191], v[76:79]
	v_mfma_f32_16x16x32_bf16 v[72:75], v[140:143], v[188:191], v[72:75]
	v_mfma_f32_16x16x32_bf16 v[116:119], v[144:147], v[160:163], v[116:119]
	v_mfma_f32_16x16x32_bf16 v[112:115], v[152:155], v[160:163], v[112:115]
	v_mfma_f32_16x16x32_bf16 v[100:103], v[144:147], v[168:171], v[100:103]
	v_mfma_f32_16x16x32_bf16 v[96:99], v[152:155], v[168:171], v[96:99]
	v_mfma_f32_16x16x32_bf16 v[84:87], v[144:147], v[176:179], v[84:87]
	v_mfma_f32_16x16x32_bf16 v[80:83], v[152:155], v[176:179], v[80:83]
	v_mfma_f32_16x16x32_bf16 v[68:71], v[144:147], v[184:187], v[68:71]
	v_mfma_f32_16x16x32_bf16 v[64:67], v[152:155], v[184:187], v[64:67]
	v_mfma_f32_16x16x32_bf16 v[116:119], v[148:151], v[164:167], v[116:119]
	v_mfma_f32_16x16x32_bf16 v[112:115], v[156:159], v[164:167], v[112:115]
	v_mfma_f32_16x16x32_bf16 v[100:103], v[148:151], v[172:175], v[100:103]
	v_mfma_f32_16x16x32_bf16 v[96:99], v[156:159], v[172:175], v[96:99]
	v_mfma_f32_16x16x32_bf16 v[84:87], v[148:151], v[180:183], v[84:87]
	v_mfma_f32_16x16x32_bf16 v[80:83], v[156:159], v[180:183], v[80:83]
	v_mfma_f32_16x16x32_bf16 v[68:71], v[148:151], v[188:191], v[68:71]
	v_mfma_f32_16x16x32_bf16 v[64:67], v[156:159], v[188:191], v[64:67]
	s_barrier
	s_add_i32 s42, s46, s50
	v_lshl_add_u64 v[218:219], v[218:219], 0, s[18:19]
	s_mov_b32 m0, s42
	ds_read_b128 v[160:163], v224 offset:49152
	ds_read_b128 v[164:167], v224 offset:50176
	ds_read_b128 v[168:171], v224 offset:51200
	ds_read_b128 v[172:175], v224 offset:52224
	ds_read_b128 v[176:179], v224 offset:53248
	ds_read_b128 v[180:183], v224 offset:54272
	ds_read_b128 v[184:187], v224 offset:55296
	ds_read_b128 v[188:191], v224 offset:56320
	global_load_lds_dwordx4 v[218:219], off
	s_add_i32 m0, s42, 0x2000
	s_add_u32 s40, s40, 0x40080
	v_lshl_add_u64 v[216:217], v[216:217], 0, s[18:19]
	s_addc_u32 s41, s41, 0
	s_add_i32 s42, s47, s50
	global_load_lds_dwordx4 v[216:217], off
	v_lshl_add_u64 v[216:217], s[40:41], 0, v[196:197]
	s_mov_b32 m0, s42
	v_lshl_add_u64 v[212:213], v[212:213], 0, s[18:19]
	global_load_lds_dwordx4 v[216:217], off
	v_lshl_add_u64 v[216:217], s[40:41], 0, v[200:201]
	s_add_i32 m0, s42, 0x2000
	s_nop 0
	global_load_lds_dwordx4 v[216:217], off
	s_mov_b32 m0, s60
	s_nop 0
	global_load_lds_dwordx4 v[212:213], off
	v_lshl_add_u64 v[212:213], v[214:215], 0, s[18:19]
	s_mov_b32 m0, s61
	s_nop 0
	global_load_lds_dwordx4 v[212:213], off
	s_waitcnt vmcnt(8)
	s_waitcnt lgkmcnt(0)
	s_barrier
	s_waitcnt lgkmcnt(0)
	v_mfma_f32_16x16x32_bf16 v[60:63], v[124:127], v[160:163], v[60:63]
	v_mfma_f32_16x16x32_bf16 v[56:59], v[136:139], v[160:163], v[56:59]
	v_mfma_f32_16x16x32_bf16 v[44:47], v[124:127], v[168:171], v[44:47]
	v_mfma_f32_16x16x32_bf16 v[40:43], v[136:139], v[168:171], v[40:43]
	v_mfma_f32_16x16x32_bf16 v[28:31], v[124:127], v[176:179], v[28:31]
	v_mfma_f32_16x16x32_bf16 v[24:27], v[136:139], v[176:179], v[24:27]
	v_mfma_f32_16x16x32_bf16 v[12:15], v[124:127], v[184:187], v[12:15]
	v_mfma_f32_16x16x32_bf16 v[8:11], v[136:139], v[184:187], v[8:11]
	v_mfma_f32_16x16x32_bf16 v[60:63], v[132:135], v[164:167], v[60:63]
	v_mfma_f32_16x16x32_bf16 v[56:59], v[140:143], v[164:167], v[56:59]
	v_mfma_f32_16x16x32_bf16 v[44:47], v[132:135], v[172:175], v[44:47]
	v_mfma_f32_16x16x32_bf16 v[40:43], v[140:143], v[172:175], v[40:43]
	v_mfma_f32_16x16x32_bf16 v[28:31], v[132:135], v[180:183], v[28:31]
	v_mfma_f32_16x16x32_bf16 v[24:27], v[140:143], v[180:183], v[24:27]
	v_mfma_f32_16x16x32_bf16 v[12:15], v[132:135], v[188:191], v[12:15]
	v_mfma_f32_16x16x32_bf16 v[8:11], v[140:143], v[188:191], v[8:11]
	v_mfma_f32_16x16x32_bf16 v[52:55], v[144:147], v[160:163], v[52:55]
	v_mfma_f32_16x16x32_bf16 v[48:51], v[152:155], v[160:163], v[48:51]
	v_mfma_f32_16x16x32_bf16 v[36:39], v[144:147], v[168:171], v[36:39]
	v_mfma_f32_16x16x32_bf16 v[32:35], v[152:155], v[168:171], v[32:35]
	v_mfma_f32_16x16x32_bf16 v[20:23], v[144:147], v[176:179], v[20:23]
	v_mfma_f32_16x16x32_bf16 v[16:19], v[152:155], v[176:179], v[16:19]
	v_mfma_f32_16x16x32_bf16 v[4:7], v[144:147], v[184:187], v[4:7]
	v_mfma_f32_16x16x32_bf16 v[0:3], v[152:155], v[184:187], v[0:3]
	v_mfma_f32_16x16x32_bf16 v[52:55], v[148:151], v[164:167], v[52:55]
	v_mfma_f32_16x16x32_bf16 v[48:51], v[156:159], v[164:167], v[48:51]
	v_mfma_f32_16x16x32_bf16 v[36:39], v[148:151], v[172:175], v[36:39]
	v_mfma_f32_16x16x32_bf16 v[32:35], v[156:159], v[172:175], v[32:35]
	v_mfma_f32_16x16x32_bf16 v[20:23], v[148:151], v[180:183], v[20:23]
	v_mfma_f32_16x16x32_bf16 v[16:19], v[156:159], v[180:183], v[16:19]
	v_mfma_f32_16x16x32_bf16 v[4:7], v[148:151], v[188:191], v[4:7]
	v_mfma_f32_16x16x32_bf16 v[0:3], v[156:159], v[188:191], v[0:3]
	s_barrier
	s_add_i32 s69, s69, 2
	s_add_u32 s38, s38, 0x100
	s_addc_u32 s39, s39, 0
	s_add_u32 s67, s67, 0x100
	s_addc_u32 s68, s68, 0
	s_cmp_gt_u32 s69, 13
	s_cbranch_scc1 .LBB0_1074

.LBB0_1070:
	s_add_u32 s44, s38, 0xfffc0080
	s_addc_u32 s45, s39, -1
	s_waitcnt lgkmcnt(0)
	s_and_b64 s[40:41], s[40:41], exec
	s_cselect_b32 s45, s25, s45
	s_cselect_b32 s44, s37, s44
	s_cselect_b32 s41, s23, s68
	s_cselect_b32 s40, s66, s67
	s_barrier
	s_waitcnt lgkmcnt(0)
	v_mfma_f32_16x16x32_bf16 v[128:131], v[144:147], v[184:187], v[128:131]
	v_mfma_f32_16x16x32_bf16 v[120:123], v[152:155], v[184:187], v[120:123]
	v_mfma_f32_16x16x32_bf16 v[108:111], v[144:147], v[176:179], v[108:111]
	v_mfma_f32_16x16x32_bf16 v[104:107], v[152:155], v[176:179], v[104:107]
	v_mfma_f32_16x16x32_bf16 v[92:95], v[144:147], v[168:171], v[92:95]
	v_mfma_f32_16x16x32_bf16 v[88:91], v[152:155], v[168:171], v[88:91]
	v_mfma_f32_16x16x32_bf16 v[76:79], v[144:147], v[160:163], v[76:79]
	v_mfma_f32_16x16x32_bf16 v[72:75], v[152:155], v[160:163], v[72:75]
	v_mfma_f32_16x16x32_bf16 v[128:131], v[148:151], v[188:191], v[128:131]
	v_mfma_f32_16x16x32_bf16 v[120:123], v[156:159], v[188:191], v[120:123]
	v_mfma_f32_16x16x32_bf16 v[108:111], v[148:151], v[180:183], v[108:111]
	v_mfma_f32_16x16x32_bf16 v[104:107], v[156:159], v[180:183], v[104:107]
	v_mfma_f32_16x16x32_bf16 v[92:95], v[148:151], v[172:175], v[92:95]
	v_mfma_f32_16x16x32_bf16 v[88:91], v[156:159], v[172:175], v[88:91]
	v_mfma_f32_16x16x32_bf16 v[76:79], v[148:151], v[164:167], v[76:79]
	v_mfma_f32_16x16x32_bf16 v[72:75], v[156:159], v[164:167], v[72:75]
	v_mfma_f32_16x16x32_bf16 v[116:119], v[124:127], v[184:187], v[116:119]
	v_mfma_f32_16x16x32_bf16 v[112:115], v[136:139], v[184:187], v[112:115]
	v_mfma_f32_16x16x32_bf16 v[100:103], v[124:127], v[176:179], v[100:103]
	v_mfma_f32_16x16x32_bf16 v[96:99], v[136:139], v[176:179], v[96:99]
	v_mfma_f32_16x16x32_bf16 v[84:87], v[124:127], v[168:171], v[84:87]
	v_mfma_f32_16x16x32_bf16 v[80:83], v[136:139], v[168:171], v[80:83]
	v_mfma_f32_16x16x32_bf16 v[68:71], v[124:127], v[160:163], v[68:71]
	v_mfma_f32_16x16x32_bf16 v[64:67], v[136:139], v[160:163], v[64:67]
	v_mfma_f32_16x16x32_bf16 v[116:119], v[132:135], v[188:191], v[116:119]
	v_mfma_f32_16x16x32_bf16 v[112:115], v[140:143], v[188:191], v[112:115]
	v_mfma_f32_16x16x32_bf16 v[100:103], v[132:135], v[180:183], v[100:103]
	v_mfma_f32_16x16x32_bf16 v[96:99], v[140:143], v[180:183], v[96:99]
	v_mfma_f32_16x16x32_bf16 v[84:87], v[132:135], v[172:175], v[84:87]
	v_mfma_f32_16x16x32_bf16 v[80:83], v[140:143], v[172:175], v[80:83]
	v_mfma_f32_16x16x32_bf16 v[68:71], v[132:135], v[164:167], v[68:71]
	v_mfma_f32_16x16x32_bf16 v[64:67], v[140:143], v[164:167], v[64:67]
	s_barrier
	s_mov_b32 m0, s52
	v_lshl_add_u64 v[218:219], s[40:41], 0, v[196:197]
	s_add_u32 s46, s40, 0x40000
	ds_read_b128 v[184:187], v224 offset:16384
	ds_read_b128 v[188:191], v224 offset:17408
	ds_read_b128 v[176:179], v224 offset:18432
	ds_read_b128 v[180:183], v224 offset:19456
	ds_read_b128 v[168:171], v224 offset:20480
	ds_read_b128 v[172:175], v224 offset:21504
	ds_read_b128 v[160:163], v224 offset:22528
	ds_read_b128 v[164:167], v224 offset:23552
	global_load_lds_dwordx4 v[218:219], off
	v_lshl_add_u64 v[216:217], s[40:41], 0, v[200:201]
	s_mov_b32 m0, s53
	s_addc_u32 s47, s41, 0
	global_load_lds_dwordx4 v[216:217], off
	v_lshl_add_u64 v[212:213], s[46:47], 0, v[196:197]
	s_mov_b32 m0, s54
	v_lshl_add_u64 v[214:215], s[44:45], 0, v[198:199]
	global_load_lds_dwordx4 v[212:213], off
	v_lshl_add_u64 v[212:213], s[46:47], 0, v[200:201]
	s_mov_b32 m0, s55
	s_mov_b64 s[46:47], -1
	global_load_lds_dwordx4 v[212:213], off
	v_lshl_add_u64 v[212:213], s[44:45], 0, v[194:195]
	s_mov_b32 m0, s51
	s_and_b64 vcc, exec, s[42:43]
	global_load_lds_dwordx4 v[212:213], off
	s_mov_b32 m0, s56
	s_nop 0
	global_load_lds_dwordx4 v[214:215], off
	s_cbranch_vccz .LBB0_1072
	s_waitcnt vmcnt(8)
	s_mov_b64 s[46:47], 0

.LBB0_1189:
	ds_read_b128 v[128:131], v184
	ds_read_b128 v[132:135], v184 offset:1024
	ds_read_b128 v[136:139], v184 offset:2048
	ds_read_b128 v[140:143], v184 offset:3072
	ds_read_b128 v[144:147], v185
	ds_read_b128 v[148:151], v185 offset:1024
	ds_read_b128 v[166:169], v185 offset:2048
	ds_read_b128 v[170:173], v185 offset:3072
	s_add_i32 s68, s38, 2
	s_add_u32 s69, s36, 0x80
	s_addc_u32 s39, s37, 0
	s_cmp_eq_u32 s51, s38
	s_cselect_b32 s38, s28, s69
	s_cselect_b32 s39, s29, s39
	s_cselect_b32 s77, s31, s67
	s_cselect_b32 s76, s30, s66
	s_mov_b32 m0, s52
	v_lshl_add_u64 v[190:191], s[36:37], 0, v[162:163]
	ds_read_b128 v[174:177], v186
	ds_read_b128 v[178:181], v186 offset:1024
	ds_read_b128 v[194:197], v186 offset:2048
	ds_read_b128 v[198:201], v186 offset:3072
	ds_read_b128 v[202:205], v186 offset:4096
	ds_read_b128 v[206:209], v186 offset:5120
	ds_read_b128 v[210:213], v186 offset:6144
	ds_read_b128 v[214:217], v186 offset:7168
	global_load_lds_dwordx4 v[190:191], off
	v_lshl_add_u64 v[190:191], s[36:37], 0, v[164:165]
	s_mov_b32 m0, s53
	s_nop 0
	global_load_lds_dwordx4 v[190:191], off
	s_waitcnt vmcnt(8)
	s_waitcnt lgkmcnt(0)
	s_barrier
	s_waitcnt lgkmcnt(0)
	v_mfma_f32_16x16x32_bf16 v[124:127], v[128:131], v[174:177], v[124:127]
	v_mfma_f32_16x16x32_bf16 v[120:123], v[136:139], v[174:177], v[120:123]
	v_mfma_f32_16x16x32_bf16 v[108:111], v[128:131], v[194:197], v[108:111]
	v_mfma_f32_16x16x32_bf16 v[104:107], v[136:139], v[194:197], v[104:107]
	v_mfma_f32_16x16x32_bf16 v[92:95], v[128:131], v[202:205], v[92:95]
	v_mfma_f32_16x16x32_bf16 v[88:91], v[136:139], v[202:205], v[88:91]
	v_mfma_f32_16x16x32_bf16 v[76:79], v[128:131], v[210:213], v[76:79]
	v_mfma_f32_16x16x32_bf16 v[72:75], v[136:139], v[210:213], v[72:75]
	v_mfma_f32_16x16x32_bf16 v[124:127], v[132:135], v[178:181], v[124:127]
	v_mfma_f32_16x16x32_bf16 v[120:123], v[140:143], v[178:181], v[120:123]
	v_mfma_f32_16x16x32_bf16 v[108:111], v[132:135], v[198:201], v[108:111]
	v_mfma_f32_16x16x32_bf16 v[104:107], v[140:143], v[198:201], v[104:107]
	v_mfma_f32_16x16x32_bf16 v[92:95], v[132:135], v[206:209], v[92:95]
	v_mfma_f32_16x16x32_bf16 v[88:91], v[140:143], v[206:209], v[88:91]
	v_mfma_f32_16x16x32_bf16 v[76:79], v[132:135], v[214:217], v[76:79]
	v_mfma_f32_16x16x32_bf16 v[72:75], v[140:143], v[214:217], v[72:75]
	v_mfma_f32_16x16x32_bf16 v[116:119], v[144:147], v[174:177], v[116:119]
	v_mfma_f32_16x16x32_bf16 v[112:115], v[166:169], v[174:177], v[112:115]
	v_mfma_f32_16x16x32_bf16 v[100:103], v[144:147], v[194:197], v[100:103]
	v_mfma_f32_16x16x32_bf16 v[96:99], v[166:169], v[194:197], v[96:99]
	v_mfma_f32_16x16x32_bf16 v[84:87], v[144:147], v[202:205], v[84:87]
	v_mfma_f32_16x16x32_bf16 v[80:83], v[166:169], v[202:205], v[80:83]
	v_mfma_f32_16x16x32_bf16 v[68:71], v[144:147], v[210:213], v[68:71]
	v_mfma_f32_16x16x32_bf16 v[64:67], v[166:169], v[210:213], v[64:67]
	v_mfma_f32_16x16x32_bf16 v[116:119], v[148:151], v[178:181], v[116:119]
	v_mfma_f32_16x16x32_bf16 v[112:115], v[170:173], v[178:181], v[112:115]
	v_mfma_f32_16x16x32_bf16 v[100:103], v[148:151], v[198:201], v[100:103]
	v_mfma_f32_16x16x32_bf16 v[96:99], v[170:173], v[198:201], v[96:99]
	v_mfma_f32_16x16x32_bf16 v[84:87], v[148:151], v[206:209], v[84:87]
	v_mfma_f32_16x16x32_bf16 v[80:83], v[170:173], v[206:209], v[80:83]
	v_mfma_f32_16x16x32_bf16 v[68:71], v[148:151], v[214:217], v[68:71]
	v_mfma_f32_16x16x32_bf16 v[64:67], v[170:173], v[214:217], v[64:67]
	s_barrier
	s_mov_b32 m0, s54
	v_lshl_add_u64 v[190:191], s[76:77], 0, v[156:157]
	v_lshl_add_u64 v[218:219], s[76:77], 0, v[152:153]
	s_add_u32 s76, s76, s0
	ds_read_b128 v[174:177], v186 offset:16384
	ds_read_b128 v[178:181], v186 offset:17408
	ds_read_b128 v[194:197], v186 offset:18432
	ds_read_b128 v[198:201], v186 offset:19456
	ds_read_b128 v[202:205], v186 offset:20480
	ds_read_b128 v[206:209], v186 offset:21504
	ds_read_b128 v[210:213], v186 offset:22528
	ds_read_b128 v[214:217], v186 offset:23552
	global_load_lds_dwordx4 v[190:191], off
	s_mov_b32 m0, s55
	s_addc_u32 s77, s77, s1
	global_load_lds_dwordx4 v[218:219], off
	v_lshl_add_u64 v[220:221], s[76:77], 0, v[156:157]
	s_mov_b32 m0, s56
	v_lshl_add_u64 v[222:223], s[76:77], 0, v[152:153]
	global_load_lds_dwordx4 v[220:221], off
	s_mov_b32 m0, s57
	v_lshl_add_u64 v[224:225], s[38:39], 0, v[158:159]
	global_load_lds_dwordx4 v[222:223], off
	s_mov_b32 m0, s43
	v_lshl_add_u64 v[226:227], s[38:39], 0, v[154:155]
	global_load_lds_dwordx4 v[224:225], off
	s_mov_b32 m0, s44
	s_nop 0
	global_load_lds_dwordx4 v[226:227], off
	s_waitcnt vmcnt(8)
	s_waitcnt lgkmcnt(0)
	s_barrier
	s_waitcnt lgkmcnt(0)
	v_mfma_f32_16x16x32_bf16 v[60:63], v[128:131], v[174:177], v[60:63]
	v_mfma_f32_16x16x32_bf16 v[56:59], v[136:139], v[174:177], v[56:59]
	v_mfma_f32_16x16x32_bf16 v[44:47], v[128:131], v[194:197], v[44:47]
	v_mfma_f32_16x16x32_bf16 v[40:43], v[136:139], v[194:197], v[40:43]
	v_mfma_f32_16x16x32_bf16 v[28:31], v[128:131], v[202:205], v[28:31]
	v_mfma_f32_16x16x32_bf16 v[24:27], v[136:139], v[202:205], v[24:27]
	v_mfma_f32_16x16x32_bf16 v[12:15], v[128:131], v[210:213], v[12:15]
	v_mfma_f32_16x16x32_bf16 v[8:11], v[136:139], v[210:213], v[8:11]
	v_mfma_f32_16x16x32_bf16 v[60:63], v[132:135], v[178:181], v[60:63]
	v_mfma_f32_16x16x32_bf16 v[56:59], v[140:143], v[178:181], v[56:59]
	v_mfma_f32_16x16x32_bf16 v[44:47], v[132:135], v[198:201], v[44:47]
	v_mfma_f32_16x16x32_bf16 v[40:43], v[140:143], v[198:201], v[40:43]
	v_mfma_f32_16x16x32_bf16 v[28:31], v[132:135], v[206:209], v[28:31]
	v_mfma_f32_16x16x32_bf16 v[24:27], v[140:143], v[206:209], v[24:27]
	v_mfma_f32_16x16x32_bf16 v[12:15], v[132:135], v[214:217], v[12:15]
	v_mfma_f32_16x16x32_bf16 v[8:11], v[140:143], v[214:217], v[8:11]
	v_mfma_f32_16x16x32_bf16 v[52:55], v[144:147], v[174:177], v[52:55]
	v_mfma_f32_16x16x32_bf16 v[48:51], v[166:169], v[174:177], v[48:51]
	v_mfma_f32_16x16x32_bf16 v[36:39], v[144:147], v[194:197], v[36:39]
	v_mfma_f32_16x16x32_bf16 v[32:35], v[166:169], v[194:197], v[32:35]
	v_mfma_f32_16x16x32_bf16 v[20:23], v[144:147], v[202:205], v[20:23]
	v_mfma_f32_16x16x32_bf16 v[16:19], v[166:169], v[202:205], v[16:19]
	v_mfma_f32_16x16x32_bf16 v[4:7], v[144:147], v[210:213], v[4:7]
	v_mfma_f32_16x16x32_bf16 v[0:3], v[166:169], v[210:213], v[0:3]
	v_mfma_f32_16x16x32_bf16 v[52:55], v[148:151], v[178:181], v[52:55]
	v_mfma_f32_16x16x32_bf16 v[48:51], v[170:173], v[178:181], v[48:51]
	v_mfma_f32_16x16x32_bf16 v[36:39], v[148:151], v[198:201], v[36:39]
	v_mfma_f32_16x16x32_bf16 v[32:35], v[170:173], v[198:201], v[32:35]
	v_mfma_f32_16x16x32_bf16 v[20:23], v[148:151], v[206:209], v[20:23]
	v_mfma_f32_16x16x32_bf16 v[16:19], v[170:173], v[206:209], v[16:19]
	v_mfma_f32_16x16x32_bf16 v[4:7], v[148:151], v[214:217], v[4:7]
	v_mfma_f32_16x16x32_bf16 v[0:3], v[170:173], v[214:217], v[0:3]
	s_barrier
	ds_read_b128 v[128:131], v187
	ds_read_b128 v[132:135], v187 offset:1024
	ds_read_b128 v[136:139], v187 offset:2048
	ds_read_b128 v[140:143], v187 offset:3072
	ds_read_b128 v[144:147], v189
	ds_read_b128 v[148:151], v189 offset:1024
	ds_read_b128 v[166:169], v189 offset:2048
	ds_read_b128 v[170:173], v189 offset:3072
	s_add_u32 s38, s38, s0
	s_addc_u32 s39, s39, s1
	s_mov_b32 m0, s45
	v_lshl_add_u64 v[228:229], s[38:39], 0, v[158:159]
	ds_read_b128 v[174:177], v186 offset:32768
	ds_read_b128 v[178:181], v186 offset:33792
	ds_read_b128 v[194:197], v186 offset:34816
	ds_read_b128 v[198:201], v186 offset:35840
	ds_read_b128 v[202:205], v186 offset:36864
	ds_read_b128 v[206:209], v186 offset:37888
	ds_read_b128 v[210:213], v186 offset:38912
	ds_read_b128 v[214:217], v186 offset:39936
	global_load_lds_dwordx4 v[228:229], off
	v_lshl_add_u64 v[228:229], s[38:39], 0, v[154:155]
	s_mov_b32 m0, s46
	s_nop 0
	global_load_lds_dwordx4 v[228:229], off
	s_waitcnt vmcnt(8)
	s_waitcnt lgkmcnt(0)
	s_barrier
	s_waitcnt lgkmcnt(0)
	v_mfma_f32_16x16x32_bf16 v[124:127], v[128:131], v[174:177], v[124:127]
	v_mfma_f32_16x16x32_bf16 v[120:123], v[136:139], v[174:177], v[120:123]
	v_mfma_f32_16x16x32_bf16 v[108:111], v[128:131], v[194:197], v[108:111]
	v_mfma_f32_16x16x32_bf16 v[104:107], v[136:139], v[194:197], v[104:107]
	v_mfma_f32_16x16x32_bf16 v[92:95], v[128:131], v[202:205], v[92:95]
	v_mfma_f32_16x16x32_bf16 v[88:91], v[136:139], v[202:205], v[88:91]
	v_mfma_f32_16x16x32_bf16 v[76:79], v[128:131], v[210:213], v[76:79]
	v_mfma_f32_16x16x32_bf16 v[72:75], v[136:139], v[210:213], v[72:75]
	v_mfma_f32_16x16x32_bf16 v[124:127], v[132:135], v[178:181], v[124:127]
	v_mfma_f32_16x16x32_bf16 v[120:123], v[140:143], v[178:181], v[120:123]
	v_mfma_f32_16x16x32_bf16 v[108:111], v[132:135], v[198:201], v[108:111]
	v_mfma_f32_16x16x32_bf16 v[104:107], v[140:143], v[198:201], v[104:107]
	v_mfma_f32_16x16x32_bf16 v[92:95], v[132:135], v[206:209], v[92:95]
	v_mfma_f32_16x16x32_bf16 v[88:91], v[140:143], v[206:209], v[88:91]
	v_mfma_f32_16x16x32_bf16 v[76:79], v[132:135], v[214:217], v[76:79]
	v_mfma_f32_16x16x32_bf16 v[72:75], v[140:143], v[214:217], v[72:75]
	v_mfma_f32_16x16x32_bf16 v[116:119], v[144:147], v[174:177], v[116:119]
	v_mfma_f32_16x16x32_bf16 v[112:115], v[166:169], v[174:177], v[112:115]
	v_mfma_f32_16x16x32_bf16 v[100:103], v[144:147], v[194:197], v[100:103]
	v_mfma_f32_16x16x32_bf16 v[96:99], v[166:169], v[194:197], v[96:99]
	v_mfma_f32_16x16x32_bf16 v[84:87], v[144:147], v[202:205], v[84:87]
	v_mfma_f32_16x16x32_bf16 v[80:83], v[166:169], v[202:205], v[80:83]
	v_mfma_f32_16x16x32_bf16 v[68:71], v[144:147], v[210:213], v[68:71]
	v_mfma_f32_16x16x32_bf16 v[64:67], v[166:169], v[210:213], v[64:67]
	v_mfma_f32_16x16x32_bf16 v[116:119], v[148:151], v[178:181], v[116:119]
	v_mfma_f32_16x16x32_bf16 v[112:115], v[170:173], v[178:181], v[112:115]
	v_mfma_f32_16x16x32_bf16 v[100:103], v[148:151], v[198:201], v[100:103]
	v_mfma_f32_16x16x32_bf16 v[96:99], v[170:173], v[198:201], v[96:99]
	v_mfma_f32_16x16x32_bf16 v[84:87], v[148:151], v[206:209], v[84:87]
	v_mfma_f32_16x16x32_bf16 v[80:83], v[170:173], v[206:209], v[80:83]
	v_mfma_f32_16x16x32_bf16 v[68:71], v[148:151], v[214:217], v[68:71]
	v_mfma_f32_16x16x32_bf16 v[64:67], v[170:173], v[214:217], v[64:67]
	s_barrier
	s_mov_b32 m0, s58
	v_lshl_add_u64 v[190:191], v[190:191], 0, s[24:25]
	ds_read_b128 v[174:177], v186 offset:49152
	ds_read_b128 v[178:181], v186 offset:50176
	ds_read_b128 v[194:197], v186 offset:51200
	ds_read_b128 v[198:201], v186 offset:52224
	ds_read_b128 v[202:205], v186 offset:53248
	ds_read_b128 v[206:209], v186 offset:54272
	ds_read_b128 v[210:213], v186 offset:55296
	ds_read_b128 v[214:217], v186 offset:56320
	global_load_lds_dwordx4 v[190:191], off
	v_lshl_add_u64 v[190:191], v[218:219], 0, s[24:25]
	s_mov_b32 m0, s59
	s_nop 0
	global_load_lds_dwordx4 v[190:191], off
	v_lshl_add_u64 v[190:191], v[220:221], 0, s[24:25]
	s_mov_b32 m0, s60
	s_nop 0
	global_load_lds_dwordx4 v[190:191], off
	v_lshl_add_u64 v[190:191], v[222:223], 0, s[24:25]
	s_mov_b32 m0, s61
	s_nop 0
	global_load_lds_dwordx4 v[190:191], off
	v_lshl_add_u64 v[190:191], v[224:225], 0, s[24:25]
	s_mov_b32 m0, s48
	s_nop 0
	global_load_lds_dwordx4 v[190:191], off
	v_lshl_add_u64 v[190:191], v[226:227], 0, s[24:25]
	s_mov_b32 m0, s49
	s_nop 0
	global_load_lds_dwordx4 v[190:191], off
	s_waitcnt vmcnt(8)
	s_waitcnt lgkmcnt(0)
	s_barrier
	s_waitcnt lgkmcnt(0)
	v_mfma_f32_16x16x32_bf16 v[60:63], v[128:131], v[174:177], v[60:63]
	v_mfma_f32_16x16x32_bf16 v[56:59], v[136:139], v[174:177], v[56:59]
	v_mfma_f32_16x16x32_bf16 v[44:47], v[128:131], v[194:197], v[44:47]
	v_mfma_f32_16x16x32_bf16 v[40:43], v[136:139], v[194:197], v[40:43]
	v_mfma_f32_16x16x32_bf16 v[28:31], v[128:131], v[202:205], v[28:31]
	v_mfma_f32_16x16x32_bf16 v[24:27], v[136:139], v[202:205], v[24:27]
	v_mfma_f32_16x16x32_bf16 v[12:15], v[128:131], v[210:213], v[12:15]
	v_mfma_f32_16x16x32_bf16 v[8:11], v[136:139], v[210:213], v[8:11]
	v_mfma_f32_16x16x32_bf16 v[60:63], v[132:135], v[178:181], v[60:63]
	v_mfma_f32_16x16x32_bf16 v[56:59], v[140:143], v[178:181], v[56:59]
	v_mfma_f32_16x16x32_bf16 v[44:47], v[132:135], v[198:201], v[44:47]
	v_mfma_f32_16x16x32_bf16 v[40:43], v[140:143], v[198:201], v[40:43]
	v_mfma_f32_16x16x32_bf16 v[28:31], v[132:135], v[206:209], v[28:31]
	v_mfma_f32_16x16x32_bf16 v[24:27], v[140:143], v[206:209], v[24:27]
	v_mfma_f32_16x16x32_bf16 v[12:15], v[132:135], v[214:217], v[12:15]
	v_mfma_f32_16x16x32_bf16 v[8:11], v[140:143], v[214:217], v[8:11]
	v_mfma_f32_16x16x32_bf16 v[52:55], v[144:147], v[174:177], v[52:55]
	v_mfma_f32_16x16x32_bf16 v[48:51], v[166:169], v[174:177], v[48:51]
	v_mfma_f32_16x16x32_bf16 v[36:39], v[144:147], v[194:197], v[36:39]
	v_mfma_f32_16x16x32_bf16 v[32:35], v[166:169], v[194:197], v[32:35]
	v_mfma_f32_16x16x32_bf16 v[20:23], v[144:147], v[202:205], v[20:23]
	v_mfma_f32_16x16x32_bf16 v[16:19], v[166:169], v[202:205], v[16:19]
	v_mfma_f32_16x16x32_bf16 v[4:7], v[144:147], v[210:213], v[4:7]
	v_mfma_f32_16x16x32_bf16 v[0:3], v[166:169], v[210:213], v[0:3]
	v_mfma_f32_16x16x32_bf16 v[52:55], v[148:151], v[178:181], v[52:55]
	v_mfma_f32_16x16x32_bf16 v[48:51], v[170:173], v[178:181], v[48:51]
	v_mfma_f32_16x16x32_bf16 v[36:39], v[148:151], v[198:201], v[36:39]
	v_mfma_f32_16x16x32_bf16 v[32:35], v[170:173], v[198:201], v[32:35]
	v_mfma_f32_16x16x32_bf16 v[20:23], v[148:151], v[206:209], v[20:23]
	v_mfma_f32_16x16x32_bf16 v[16:19], v[170:173], v[206:209], v[16:19]
	v_mfma_f32_16x16x32_bf16 v[4:7], v[148:151], v[214:217], v[4:7]
	v_mfma_f32_16x16x32_bf16 v[0:3], v[170:173], v[214:217], v[0:3]
	s_barrier
	s_add_u32 s36, s36, 0x100
	s_addc_u32 s37, s37, 0
	s_add_u32 s66, s66, 0x100
	s_addc_u32 s67, s67, 0
	s_cmp_ge_i32 s68, s50
	s_mov_b32 s38, s68
	s_cbranch_scc0 .LBB0_1189

.LBB0_1285:
	s_waitcnt lgkmcnt(0)
	s_barrier
	s_waitcnt lgkmcnt(0)
	v_mfma_f32_16x16x32_bf16 v[60:63], v[144:147], v[184:187], v[60:63]
	v_mfma_f32_16x16x32_bf16 v[56:59], v[152:155], v[184:187], v[56:59]
	v_mfma_f32_16x16x32_bf16 v[44:47], v[144:147], v[176:179], v[44:47]
	v_mfma_f32_16x16x32_bf16 v[40:43], v[152:155], v[176:179], v[40:43]
	v_mfma_f32_16x16x32_bf16 v[28:31], v[144:147], v[168:171], v[28:31]
	v_mfma_f32_16x16x32_bf16 v[24:27], v[152:155], v[168:171], v[24:27]
	v_mfma_f32_16x16x32_bf16 v[12:15], v[144:147], v[160:163], v[12:15]
	v_mfma_f32_16x16x32_bf16 v[8:11], v[152:155], v[160:163], v[8:11]
	v_mfma_f32_16x16x32_bf16 v[60:63], v[148:151], v[188:191], v[60:63]
	v_mfma_f32_16x16x32_bf16 v[56:59], v[156:159], v[188:191], v[56:59]
	v_mfma_f32_16x16x32_bf16 v[44:47], v[148:151], v[180:183], v[44:47]
	v_mfma_f32_16x16x32_bf16 v[40:43], v[156:159], v[180:183], v[40:43]
	v_mfma_f32_16x16x32_bf16 v[28:31], v[148:151], v[172:175], v[28:31]
	v_mfma_f32_16x16x32_bf16 v[24:27], v[156:159], v[172:175], v[24:27]
	v_mfma_f32_16x16x32_bf16 v[12:15], v[148:151], v[164:167], v[12:15]
	v_mfma_f32_16x16x32_bf16 v[8:11], v[156:159], v[164:167], v[8:11]
	v_mfma_f32_16x16x32_bf16 v[52:55], v[128:131], v[184:187], v[52:55]
	v_mfma_f32_16x16x32_bf16 v[48:51], v[136:139], v[184:187], v[48:51]
	v_mfma_f32_16x16x32_bf16 v[36:39], v[128:131], v[176:179], v[36:39]
	v_mfma_f32_16x16x32_bf16 v[32:35], v[136:139], v[176:179], v[32:35]
	v_mfma_f32_16x16x32_bf16 v[20:23], v[128:131], v[168:171], v[20:23]
	v_mfma_f32_16x16x32_bf16 v[16:19], v[136:139], v[168:171], v[16:19]
	v_mfma_f32_16x16x32_bf16 v[4:7], v[128:131], v[160:163], v[4:7]
	v_mfma_f32_16x16x32_bf16 v[0:3], v[136:139], v[160:163], v[0:3]
	v_mfma_f32_16x16x32_bf16 v[52:55], v[132:135], v[188:191], v[52:55]
	v_mfma_f32_16x16x32_bf16 v[48:51], v[140:143], v[188:191], v[48:51]
	v_mfma_f32_16x16x32_bf16 v[36:39], v[132:135], v[180:183], v[36:39]
	v_mfma_f32_16x16x32_bf16 v[32:35], v[140:143], v[180:183], v[32:35]
	v_mfma_f32_16x16x32_bf16 v[20:23], v[132:135], v[172:175], v[20:23]
	v_mfma_f32_16x16x32_bf16 v[16:19], v[140:143], v[172:175], v[16:19]
	v_mfma_f32_16x16x32_bf16 v[4:7], v[132:135], v[164:167], v[4:7]
	v_mfma_f32_16x16x32_bf16 v[0:3], v[140:143], v[164:167], v[0:3]
	s_barrier
	s_add_i32 s50, 0, 0x18000
	s_add_i32 s51, 0, 0x1c000
	v_add_u32_e32 v140, s50, v220
	v_add_u32_e32 v156, s51, v220
	ds_read_b128 v[128:131], v140
	ds_read_b128 v[132:135], v140 offset:1024
	ds_read_b128 v[136:139], v140 offset:2048
	ds_read_b128 v[140:143], v140 offset:3072
	ds_read_b128 v[144:147], v156
	ds_read_b128 v[148:151], v156 offset:1024
	ds_read_b128 v[152:155], v156 offset:2048
	ds_read_b128 v[156:159], v156 offset:3072
	s_add_u32 s46, s48, 0x40000
	s_addc_u32 s47, s49, 0
	s_mov_b32 m0, s62
	v_lshl_add_u64 v[232:233], s[46:47], 0, v[194:195]
	ds_read_b128 v[160:163], v223 offset:32768
	ds_read_b128 v[164:167], v223 offset:33792
	ds_read_b128 v[168:171], v223 offset:34816
	ds_read_b128 v[172:175], v223 offset:35840
	ds_read_b128 v[176:179], v223 offset:36864
	ds_read_b128 v[180:183], v223 offset:37888
	ds_read_b128 v[184:187], v223 offset:38912
	ds_read_b128 v[188:191], v223 offset:39936
	global_load_lds_dwordx4 v[232:233], off
	v_lshl_add_u64 v[232:233], s[46:47], 0, v[198:199]
	s_mov_b32 m0, s63
	s_nop 0
	global_load_lds_dwordx4 v[232:233], off
	s_waitcnt vmcnt(8)
	s_waitcnt lgkmcnt(0)
	s_barrier
	s_waitcnt lgkmcnt(0)
	v_mfma_f32_16x16x32_bf16 v[124:127], v[128:131], v[160:163], v[124:127]
	v_mfma_f32_16x16x32_bf16 v[120:123], v[136:139], v[160:163], v[120:123]
	v_mfma_f32_16x16x32_bf16 v[108:111], v[128:131], v[168:171], v[108:111]
	v_mfma_f32_16x16x32_bf16 v[104:107], v[136:139], v[168:171], v[104:107]
	v_mfma_f32_16x16x32_bf16 v[92:95], v[128:131], v[176:179], v[92:95]
	v_mfma_f32_16x16x32_bf16 v[88:91], v[136:139], v[176:179], v[88:91]
	v_mfma_f32_16x16x32_bf16 v[76:79], v[128:131], v[184:187], v[76:79]
	v_mfma_f32_16x16x32_bf16 v[72:75], v[136:139], v[184:187], v[72:75]
	v_mfma_f32_16x16x32_bf16 v[124:127], v[132:135], v[164:167], v[124:127]
	v_mfma_f32_16x16x32_bf16 v[120:123], v[140:143], v[164:167], v[120:123]
	v_mfma_f32_16x16x32_bf16 v[108:111], v[132:135], v[172:175], v[108:111]
	v_mfma_f32_16x16x32_bf16 v[104:107], v[140:143], v[172:175], v[104:107]
	v_mfma_f32_16x16x32_bf16 v[92:95], v[132:135], v[180:183], v[92:95]
	v_mfma_f32_16x16x32_bf16 v[88:91], v[140:143], v[180:183], v[88:91]
	v_mfma_f32_16x16x32_bf16 v[76:79], v[132:135], v[188:191], v[76:79]
	v_mfma_f32_16x16x32_bf16 v[72:75], v[140:143], v[188:191], v[72:75]
	v_mfma_f32_16x16x32_bf16 v[116:119], v[144:147], v[160:163], v[116:119]
	v_mfma_f32_16x16x32_bf16 v[112:115], v[152:155], v[160:163], v[112:115]
	v_mfma_f32_16x16x32_bf16 v[100:103], v[144:147], v[168:171], v[100:103]
	v_mfma_f32_16x16x32_bf16 v[96:99], v[152:155], v[168:171], v[96:99]
	v_mfma_f32_16x16x32_bf16 v[84:87], v[144:147], v[176:179], v[84:87]
	v_mfma_f32_16x16x32_bf16 v[80:83], v[152:155], v[176:179], v[80:83]
	v_mfma_f32_16x16x32_bf16 v[68:71], v[144:147], v[184:187], v[68:71]
	v_mfma_f32_16x16x32_bf16 v[64:67], v[152:155], v[184:187], v[64:67]
	v_mfma_f32_16x16x32_bf16 v[116:119], v[148:151], v[164:167], v[116:119]
	v_mfma_f32_16x16x32_bf16 v[112:115], v[156:159], v[164:167], v[112:115]
	v_mfma_f32_16x16x32_bf16 v[100:103], v[148:151], v[172:175], v[100:103]
	v_mfma_f32_16x16x32_bf16 v[96:99], v[156:159], v[172:175], v[96:99]
	v_mfma_f32_16x16x32_bf16 v[84:87], v[148:151], v[180:183], v[84:87]
	v_mfma_f32_16x16x32_bf16 v[80:83], v[156:159], v[180:183], v[80:83]
	v_mfma_f32_16x16x32_bf16 v[68:71], v[148:151], v[188:191], v[68:71]
	v_mfma_f32_16x16x32_bf16 v[64:67], v[156:159], v[188:191], v[64:67]
	s_barrier
	s_add_i32 s46, s50, s55
	v_lshl_add_u64 v[218:219], v[218:219], 0, s[16:17]
	s_mov_b32 m0, s46
	ds_read_b128 v[160:163], v223 offset:49152
	ds_read_b128 v[164:167], v223 offset:50176
	ds_read_b128 v[168:171], v223 offset:51200
	ds_read_b128 v[172:175], v223 offset:52224
	ds_read_b128 v[176:179], v223 offset:53248
	ds_read_b128 v[180:183], v223 offset:54272
	ds_read_b128 v[184:187], v223 offset:55296
	ds_read_b128 v[188:191], v223 offset:56320
	global_load_lds_dwordx4 v[218:219], off
	s_add_i32 m0, s46, 0x2000
	s_add_u32 s44, s44, 0x40080
	v_lshl_add_u64 v[216:217], v[216:217], 0, s[16:17]
	s_addc_u32 s45, s45, 0
	s_add_i32 s46, s51, s55
	global_load_lds_dwordx4 v[216:217], off
	v_lshl_add_u64 v[216:217], s[44:45], 0, v[196:197]
	s_mov_b32 m0, s46
	v_lshl_add_u64 v[212:213], v[212:213], 0, s[16:17]
	global_load_lds_dwordx4 v[216:217], off
	v_lshl_add_u64 v[216:217], s[44:45], 0, v[200:201]
	s_add_i32 m0, s46, 0x2000
	s_nop 0
	global_load_lds_dwordx4 v[216:217], off
	s_mov_b32 m0, s65
	s_nop 0
	global_load_lds_dwordx4 v[212:213], off
	v_lshl_add_u64 v[212:213], v[214:215], 0, s[16:17]
	s_mov_b32 m0, s66
	s_nop 0
	global_load_lds_dwordx4 v[212:213], off
	s_waitcnt vmcnt(8)
	s_waitcnt lgkmcnt(0)
	s_barrier
	s_waitcnt lgkmcnt(0)
	v_mfma_f32_16x16x32_bf16 v[60:63], v[128:131], v[160:163], v[60:63]
	v_mfma_f32_16x16x32_bf16 v[56:59], v[136:139], v[160:163], v[56:59]
	v_mfma_f32_16x16x32_bf16 v[44:47], v[128:131], v[168:171], v[44:47]
	v_mfma_f32_16x16x32_bf16 v[40:43], v[136:139], v[168:171], v[40:43]
	v_mfma_f32_16x16x32_bf16 v[28:31], v[128:131], v[176:179], v[28:31]
	v_mfma_f32_16x16x32_bf16 v[24:27], v[136:139], v[176:179], v[24:27]
	v_mfma_f32_16x16x32_bf16 v[12:15], v[128:131], v[184:187], v[12:15]
	v_mfma_f32_16x16x32_bf16 v[8:11], v[136:139], v[184:187], v[8:11]
	v_mfma_f32_16x16x32_bf16 v[60:63], v[132:135], v[164:167], v[60:63]
	v_mfma_f32_16x16x32_bf16 v[56:59], v[140:143], v[164:167], v[56:59]
	v_mfma_f32_16x16x32_bf16 v[44:47], v[132:135], v[172:175], v[44:47]
	v_mfma_f32_16x16x32_bf16 v[40:43], v[140:143], v[172:175], v[40:43]
	v_mfma_f32_16x16x32_bf16 v[28:31], v[132:135], v[180:183], v[28:31]
	v_mfma_f32_16x16x32_bf16 v[24:27], v[140:143], v[180:183], v[24:27]
	v_mfma_f32_16x16x32_bf16 v[12:15], v[132:135], v[188:191], v[12:15]
	v_mfma_f32_16x16x32_bf16 v[8:11], v[140:143], v[188:191], v[8:11]
	v_mfma_f32_16x16x32_bf16 v[52:55], v[144:147], v[160:163], v[52:55]
	v_mfma_f32_16x16x32_bf16 v[48:51], v[152:155], v[160:163], v[48:51]
	v_mfma_f32_16x16x32_bf16 v[36:39], v[144:147], v[168:171], v[36:39]
	v_mfma_f32_16x16x32_bf16 v[32:35], v[152:155], v[168:171], v[32:35]
	v_mfma_f32_16x16x32_bf16 v[20:23], v[144:147], v[176:179], v[20:23]
	v_mfma_f32_16x16x32_bf16 v[16:19], v[152:155], v[176:179], v[16:19]
	v_mfma_f32_16x16x32_bf16 v[4:7], v[144:147], v[184:187], v[4:7]
	v_mfma_f32_16x16x32_bf16 v[0:3], v[152:155], v[184:187], v[0:3]
	v_mfma_f32_16x16x32_bf16 v[52:55], v[148:151], v[164:167], v[52:55]
	v_mfma_f32_16x16x32_bf16 v[48:51], v[156:159], v[164:167], v[48:51]
	v_mfma_f32_16x16x32_bf16 v[36:39], v[148:151], v[172:175], v[36:39]
	v_mfma_f32_16x16x32_bf16 v[32:35], v[156:159], v[172:175], v[32:35]
	v_mfma_f32_16x16x32_bf16 v[20:23], v[148:151], v[180:183], v[20:23]
	v_mfma_f32_16x16x32_bf16 v[16:19], v[156:159], v[180:183], v[16:19]
	v_mfma_f32_16x16x32_bf16 v[4:7], v[148:151], v[188:191], v[4:7]
	v_mfma_f32_16x16x32_bf16 v[0:3], v[156:159], v[188:191], v[0:3]
	s_barrier
	s_add_i32 s85, s85, 2
	s_add_u32 s42, s42, 0x100
	s_addc_u32 s43, s43, 0
	s_add_u32 s83, s83, 0x100
	s_addc_u32 s84, s84, 0
	s_cmp_gt_u32 s85, 13
	s_cbranch_scc1 .LBB0_1296

.LBB0_1292:
	s_add_u32 s48, s42, 0xfffc0080
	s_addc_u32 s49, s43, -1
	s_waitcnt lgkmcnt(0)
	s_and_b64 s[44:45], s[44:45], exec
	s_cselect_b32 s49, s31, s49
	s_cselect_b32 s48, s81, s48
	s_cselect_b32 s45, s29, s84
	s_cselect_b32 s44, s82, s83
	s_barrier
	s_waitcnt lgkmcnt(0)
	v_mfma_f32_16x16x32_bf16 v[124:127], v[144:147], v[184:187], v[124:127]
	v_mfma_f32_16x16x32_bf16 v[120:123], v[152:155], v[184:187], v[120:123]
	v_mfma_f32_16x16x32_bf16 v[108:111], v[144:147], v[176:179], v[108:111]
	v_mfma_f32_16x16x32_bf16 v[104:107], v[152:155], v[176:179], v[104:107]
	v_mfma_f32_16x16x32_bf16 v[92:95], v[144:147], v[168:171], v[92:95]
	v_mfma_f32_16x16x32_bf16 v[88:91], v[152:155], v[168:171], v[88:91]
	v_mfma_f32_16x16x32_bf16 v[76:79], v[144:147], v[160:163], v[76:79]
	v_mfma_f32_16x16x32_bf16 v[72:75], v[152:155], v[160:163], v[72:75]
	v_mfma_f32_16x16x32_bf16 v[124:127], v[148:151], v[188:191], v[124:127]
	v_mfma_f32_16x16x32_bf16 v[120:123], v[156:159], v[188:191], v[120:123]
	v_mfma_f32_16x16x32_bf16 v[108:111], v[148:151], v[180:183], v[108:111]
	v_mfma_f32_16x16x32_bf16 v[104:107], v[156:159], v[180:183], v[104:107]
	v_mfma_f32_16x16x32_bf16 v[92:95], v[148:151], v[172:175], v[92:95]
	v_mfma_f32_16x16x32_bf16 v[88:91], v[156:159], v[172:175], v[88:91]
	v_mfma_f32_16x16x32_bf16 v[76:79], v[148:151], v[164:167], v[76:79]
	v_mfma_f32_16x16x32_bf16 v[72:75], v[156:159], v[164:167], v[72:75]
	v_mfma_f32_16x16x32_bf16 v[116:119], v[128:131], v[184:187], v[116:119]
	v_mfma_f32_16x16x32_bf16 v[112:115], v[136:139], v[184:187], v[112:115]
	v_mfma_f32_16x16x32_bf16 v[100:103], v[128:131], v[176:179], v[100:103]
	v_mfma_f32_16x16x32_bf16 v[96:99], v[136:139], v[176:179], v[96:99]
	v_mfma_f32_16x16x32_bf16 v[84:87], v[128:131], v[168:171], v[84:87]
	v_mfma_f32_16x16x32_bf16 v[80:83], v[136:139], v[168:171], v[80:83]
	v_mfma_f32_16x16x32_bf16 v[68:71], v[128:131], v[160:163], v[68:71]
	v_mfma_f32_16x16x32_bf16 v[64:67], v[136:139], v[160:163], v[64:67]
	v_mfma_f32_16x16x32_bf16 v[116:119], v[132:135], v[188:191], v[116:119]
	v_mfma_f32_16x16x32_bf16 v[112:115], v[140:143], v[188:191], v[112:115]
	v_mfma_f32_16x16x32_bf16 v[100:103], v[132:135], v[180:183], v[100:103]
	v_mfma_f32_16x16x32_bf16 v[96:99], v[140:143], v[180:183], v[96:99]
	v_mfma_f32_16x16x32_bf16 v[84:87], v[132:135], v[172:175], v[84:87]
	v_mfma_f32_16x16x32_bf16 v[80:83], v[140:143], v[172:175], v[80:83]
	v_mfma_f32_16x16x32_bf16 v[68:71], v[132:135], v[164:167], v[68:71]
	v_mfma_f32_16x16x32_bf16 v[64:67], v[140:143], v[164:167], v[64:67]
	s_barrier
	s_mov_b32 m0, s57
	v_lshl_add_u64 v[218:219], s[44:45], 0, v[196:197]
	s_add_u32 s50, s44, 0x40000
	ds_read_b128 v[184:187], v223 offset:16384
	ds_read_b128 v[188:191], v223 offset:17408
	ds_read_b128 v[176:179], v223 offset:18432
	ds_read_b128 v[180:183], v223 offset:19456
	ds_read_b128 v[168:171], v223 offset:20480
	ds_read_b128 v[172:175], v223 offset:21504
	ds_read_b128 v[160:163], v223 offset:22528
	ds_read_b128 v[164:167], v223 offset:23552
	global_load_lds_dwordx4 v[218:219], off
	v_lshl_add_u64 v[216:217], s[44:45], 0, v[200:201]
	s_mov_b32 m0, s58
	s_addc_u32 s51, s45, 0
	global_load_lds_dwordx4 v[216:217], off
	v_lshl_add_u64 v[212:213], s[50:51], 0, v[196:197]
	s_mov_b32 m0, s59
	v_lshl_add_u64 v[214:215], s[48:49], 0, v[198:199]
	global_load_lds_dwordx4 v[212:213], off
	v_lshl_add_u64 v[212:213], s[50:51], 0, v[200:201]
	s_mov_b32 m0, s60
	s_mov_b64 s[50:51], -1
	global_load_lds_dwordx4 v[212:213], off
	v_lshl_add_u64 v[212:213], s[48:49], 0, v[194:195]
	s_mov_b32 m0, s56
	s_and_b64 vcc, exec, s[46:47]
	global_load_lds_dwordx4 v[212:213], off
	s_mov_b32 m0, s61
	s_nop 0
	global_load_lds_dwordx4 v[214:215], off
	s_cbranch_vccz .LBB0_1294
	s_waitcnt vmcnt(8)
	s_mov_b64 s[50:51], 0

.LBB0_1507:
	s_waitcnt lgkmcnt(0)
	s_barrier
	s_waitcnt lgkmcnt(0)
	v_mfma_f32_16x16x32_bf16 v[60:63], v[144:147], v[184:187], v[60:63]
	v_mfma_f32_16x16x32_bf16 v[56:59], v[152:155], v[184:187], v[56:59]
	v_mfma_f32_16x16x32_bf16 v[44:47], v[144:147], v[176:179], v[44:47]
	v_mfma_f32_16x16x32_bf16 v[40:43], v[152:155], v[176:179], v[40:43]
	v_mfma_f32_16x16x32_bf16 v[28:31], v[144:147], v[168:171], v[28:31]
	v_mfma_f32_16x16x32_bf16 v[24:27], v[152:155], v[168:171], v[24:27]
	v_mfma_f32_16x16x32_bf16 v[12:15], v[144:147], v[160:163], v[12:15]
	v_mfma_f32_16x16x32_bf16 v[8:11], v[152:155], v[160:163], v[8:11]
	v_mfma_f32_16x16x32_bf16 v[60:63], v[148:151], v[188:191], v[60:63]
	v_mfma_f32_16x16x32_bf16 v[56:59], v[156:159], v[188:191], v[56:59]
	v_mfma_f32_16x16x32_bf16 v[44:47], v[148:151], v[180:183], v[44:47]
	v_mfma_f32_16x16x32_bf16 v[40:43], v[156:159], v[180:183], v[40:43]
	v_mfma_f32_16x16x32_bf16 v[28:31], v[148:151], v[172:175], v[28:31]
	v_mfma_f32_16x16x32_bf16 v[24:27], v[156:159], v[172:175], v[24:27]
	v_mfma_f32_16x16x32_bf16 v[12:15], v[148:151], v[164:167], v[12:15]
	v_mfma_f32_16x16x32_bf16 v[8:11], v[156:159], v[164:167], v[8:11]
	v_mfma_f32_16x16x32_bf16 v[52:55], v[124:127], v[184:187], v[52:55]
	v_mfma_f32_16x16x32_bf16 v[48:51], v[136:139], v[184:187], v[48:51]
	v_mfma_f32_16x16x32_bf16 v[36:39], v[124:127], v[176:179], v[36:39]
	v_mfma_f32_16x16x32_bf16 v[32:35], v[136:139], v[176:179], v[32:35]
	v_mfma_f32_16x16x32_bf16 v[20:23], v[124:127], v[168:171], v[20:23]
	v_mfma_f32_16x16x32_bf16 v[16:19], v[136:139], v[168:171], v[16:19]
	v_mfma_f32_16x16x32_bf16 v[4:7], v[124:127], v[160:163], v[4:7]
	v_mfma_f32_16x16x32_bf16 v[0:3], v[136:139], v[160:163], v[0:3]
	v_mfma_f32_16x16x32_bf16 v[52:55], v[128:131], v[188:191], v[52:55]
	v_mfma_f32_16x16x32_bf16 v[48:51], v[140:143], v[188:191], v[48:51]
	v_mfma_f32_16x16x32_bf16 v[36:39], v[128:131], v[180:183], v[36:39]
	v_mfma_f32_16x16x32_bf16 v[32:35], v[140:143], v[180:183], v[32:35]
	v_mfma_f32_16x16x32_bf16 v[20:23], v[128:131], v[172:175], v[20:23]
	v_mfma_f32_16x16x32_bf16 v[16:19], v[140:143], v[172:175], v[16:19]
	v_mfma_f32_16x16x32_bf16 v[4:7], v[128:131], v[164:167], v[4:7]
	v_mfma_f32_16x16x32_bf16 v[0:3], v[140:143], v[164:167], v[0:3]
	s_barrier
	s_add_i32 s44, 0, 0x18000
	s_add_i32 s45, 0, 0x1c000
	v_add_u32_e32 v140, s44, v219
	v_add_u32_e32 v156, s45, v219
	ds_read_b128 v[124:127], v140
	ds_read_b128 v[128:131], v140 offset:1024
	ds_read_b128 v[136:139], v140 offset:2048
	ds_read_b128 v[140:143], v140 offset:3072
	ds_read_b128 v[144:147], v156
	ds_read_b128 v[148:151], v156 offset:1024
	ds_read_b128 v[152:155], v156 offset:2048
	ds_read_b128 v[156:159], v156 offset:3072
	s_add_u32 s40, s42, 0x40000
	s_addc_u32 s41, s43, 0
	s_mov_b32 m0, s54
	v_lshl_add_u64 v[232:233], s[40:41], 0, v[194:195]
	ds_read_b128 v[160:163], v222 offset:32768
	ds_read_b128 v[164:167], v222 offset:33792
	ds_read_b128 v[168:171], v222 offset:34816
	ds_read_b128 v[172:175], v222 offset:35840
	ds_read_b128 v[176:179], v222 offset:36864
	ds_read_b128 v[180:183], v222 offset:37888
	ds_read_b128 v[184:187], v222 offset:38912
	ds_read_b128 v[188:191], v222 offset:39936
	global_load_lds_dwordx4 v[232:233], off
	v_lshl_add_u64 v[232:233], s[40:41], 0, v[198:199]
	s_mov_b32 m0, s55
	s_nop 0
	global_load_lds_dwordx4 v[232:233], off
	s_waitcnt vmcnt(8)
	s_waitcnt lgkmcnt(0)
	s_barrier
	s_waitcnt lgkmcnt(0)
	v_mfma_f32_16x16x32_bf16 v[132:135], v[124:127], v[160:163], v[132:135]
	v_mfma_f32_16x16x32_bf16 v[120:123], v[136:139], v[160:163], v[120:123]
	v_mfma_f32_16x16x32_bf16 v[108:111], v[124:127], v[168:171], v[108:111]
	v_mfma_f32_16x16x32_bf16 v[104:107], v[136:139], v[168:171], v[104:107]
	v_mfma_f32_16x16x32_bf16 v[92:95], v[124:127], v[176:179], v[92:95]
	v_mfma_f32_16x16x32_bf16 v[88:91], v[136:139], v[176:179], v[88:91]
	v_mfma_f32_16x16x32_bf16 v[76:79], v[124:127], v[184:187], v[76:79]
	v_mfma_f32_16x16x32_bf16 v[72:75], v[136:139], v[184:187], v[72:75]
	v_mfma_f32_16x16x32_bf16 v[132:135], v[128:131], v[164:167], v[132:135]
	v_mfma_f32_16x16x32_bf16 v[120:123], v[140:143], v[164:167], v[120:123]
	v_mfma_f32_16x16x32_bf16 v[108:111], v[128:131], v[172:175], v[108:111]
	v_mfma_f32_16x16x32_bf16 v[104:107], v[140:143], v[172:175], v[104:107]
	v_mfma_f32_16x16x32_bf16 v[92:95], v[128:131], v[180:183], v[92:95]
	v_mfma_f32_16x16x32_bf16 v[88:91], v[140:143], v[180:183], v[88:91]
	v_mfma_f32_16x16x32_bf16 v[76:79], v[128:131], v[188:191], v[76:79]
	v_mfma_f32_16x16x32_bf16 v[72:75], v[140:143], v[188:191], v[72:75]
	v_mfma_f32_16x16x32_bf16 v[116:119], v[144:147], v[160:163], v[116:119]
	v_mfma_f32_16x16x32_bf16 v[112:115], v[152:155], v[160:163], v[112:115]
	v_mfma_f32_16x16x32_bf16 v[100:103], v[144:147], v[168:171], v[100:103]
	v_mfma_f32_16x16x32_bf16 v[96:99], v[152:155], v[168:171], v[96:99]
	v_mfma_f32_16x16x32_bf16 v[84:87], v[144:147], v[176:179], v[84:87]
	v_mfma_f32_16x16x32_bf16 v[80:83], v[152:155], v[176:179], v[80:83]
	v_mfma_f32_16x16x32_bf16 v[68:71], v[144:147], v[184:187], v[68:71]
	v_mfma_f32_16x16x32_bf16 v[64:67], v[152:155], v[184:187], v[64:67]
	v_mfma_f32_16x16x32_bf16 v[116:119], v[148:151], v[164:167], v[116:119]
	v_mfma_f32_16x16x32_bf16 v[112:115], v[156:159], v[164:167], v[112:115]
	v_mfma_f32_16x16x32_bf16 v[100:103], v[148:151], v[172:175], v[100:103]
	v_mfma_f32_16x16x32_bf16 v[96:99], v[156:159], v[172:175], v[96:99]
	v_mfma_f32_16x16x32_bf16 v[84:87], v[148:151], v[180:183], v[84:87]
	v_mfma_f32_16x16x32_bf16 v[80:83], v[156:159], v[180:183], v[80:83]
	v_mfma_f32_16x16x32_bf16 v[68:71], v[148:151], v[188:191], v[68:71]
	v_mfma_f32_16x16x32_bf16 v[64:67], v[156:159], v[188:191], v[64:67]
	s_barrier
	s_add_i32 s40, s44, s47
	v_lshl_add_u64 v[216:217], v[216:217], 0, s[6:7]
	s_mov_b32 m0, s40
	ds_read_b128 v[160:163], v222 offset:49152
	ds_read_b128 v[164:167], v222 offset:50176
	ds_read_b128 v[168:171], v222 offset:51200
	ds_read_b128 v[172:175], v222 offset:52224
	ds_read_b128 v[176:179], v222 offset:53248
	ds_read_b128 v[180:183], v222 offset:54272
	ds_read_b128 v[184:187], v222 offset:55296
	ds_read_b128 v[188:191], v222 offset:56320
	global_load_lds_dwordx4 v[216:217], off
	s_add_i32 m0, s40, 0x2000
	s_add_u32 s38, s38, 0x40080
	v_lshl_add_u64 v[214:215], v[214:215], 0, s[6:7]
	s_addc_u32 s39, s39, 0
	s_add_i32 s40, s45, s47
	global_load_lds_dwordx4 v[214:215], off
	v_lshl_add_u64 v[214:215], s[38:39], 0, v[196:197]
	s_mov_b32 m0, s40
	v_lshl_add_u64 v[210:211], v[210:211], 0, s[6:7]
	global_load_lds_dwordx4 v[214:215], off
	v_lshl_add_u64 v[214:215], s[38:39], 0, v[200:201]
	s_add_i32 m0, s40, 0x2000
	s_nop 0
	global_load_lds_dwordx4 v[214:215], off
	s_mov_b32 m0, s57
	s_nop 0
	global_load_lds_dwordx4 v[210:211], off
	v_lshl_add_u64 v[210:211], v[212:213], 0, s[6:7]
	s_mov_b32 m0, s58
	s_nop 0
	global_load_lds_dwordx4 v[210:211], off
	s_waitcnt vmcnt(8)
	s_waitcnt lgkmcnt(0)
	s_barrier
	s_waitcnt lgkmcnt(0)
	v_mfma_f32_16x16x32_bf16 v[60:63], v[124:127], v[160:163], v[60:63]
	v_mfma_f32_16x16x32_bf16 v[56:59], v[136:139], v[160:163], v[56:59]
	v_mfma_f32_16x16x32_bf16 v[44:47], v[124:127], v[168:171], v[44:47]
	v_mfma_f32_16x16x32_bf16 v[40:43], v[136:139], v[168:171], v[40:43]
	v_mfma_f32_16x16x32_bf16 v[28:31], v[124:127], v[176:179], v[28:31]
	v_mfma_f32_16x16x32_bf16 v[24:27], v[136:139], v[176:179], v[24:27]
	v_mfma_f32_16x16x32_bf16 v[12:15], v[124:127], v[184:187], v[12:15]
	v_mfma_f32_16x16x32_bf16 v[8:11], v[136:139], v[184:187], v[8:11]
	v_mfma_f32_16x16x32_bf16 v[60:63], v[128:131], v[164:167], v[60:63]
	v_mfma_f32_16x16x32_bf16 v[56:59], v[140:143], v[164:167], v[56:59]
	v_mfma_f32_16x16x32_bf16 v[44:47], v[128:131], v[172:175], v[44:47]
	v_mfma_f32_16x16x32_bf16 v[40:43], v[140:143], v[172:175], v[40:43]
	v_mfma_f32_16x16x32_bf16 v[28:31], v[128:131], v[180:183], v[28:31]
	v_mfma_f32_16x16x32_bf16 v[24:27], v[140:143], v[180:183], v[24:27]
	v_mfma_f32_16x16x32_bf16 v[12:15], v[128:131], v[188:191], v[12:15]
	v_mfma_f32_16x16x32_bf16 v[8:11], v[140:143], v[188:191], v[8:11]
	v_mfma_f32_16x16x32_bf16 v[52:55], v[144:147], v[160:163], v[52:55]
	v_mfma_f32_16x16x32_bf16 v[48:51], v[152:155], v[160:163], v[48:51]
	v_mfma_f32_16x16x32_bf16 v[36:39], v[144:147], v[168:171], v[36:39]
	v_mfma_f32_16x16x32_bf16 v[32:35], v[152:155], v[168:171], v[32:35]
	v_mfma_f32_16x16x32_bf16 v[20:23], v[144:147], v[176:179], v[20:23]
	v_mfma_f32_16x16x32_bf16 v[16:19], v[152:155], v[176:179], v[16:19]
	v_mfma_f32_16x16x32_bf16 v[4:7], v[144:147], v[184:187], v[4:7]
	v_mfma_f32_16x16x32_bf16 v[0:3], v[152:155], v[184:187], v[0:3]
	v_mfma_f32_16x16x32_bf16 v[52:55], v[148:151], v[164:167], v[52:55]
	v_mfma_f32_16x16x32_bf16 v[48:51], v[156:159], v[164:167], v[48:51]
	v_mfma_f32_16x16x32_bf16 v[36:39], v[148:151], v[172:175], v[36:39]
	v_mfma_f32_16x16x32_bf16 v[32:35], v[156:159], v[172:175], v[32:35]
	v_mfma_f32_16x16x32_bf16 v[20:23], v[148:151], v[180:183], v[20:23]
	v_mfma_f32_16x16x32_bf16 v[16:19], v[156:159], v[180:183], v[16:19]
	v_mfma_f32_16x16x32_bf16 v[4:7], v[148:151], v[188:191], v[4:7]
	v_mfma_f32_16x16x32_bf16 v[0:3], v[156:159], v[188:191], v[0:3]
	s_barrier
	s_add_i32 s66, s66, 2
	s_add_u32 s36, s36, 0x100
	s_addc_u32 s37, s37, 0
	s_add_u32 s64, s64, 0x100
	s_addc_u32 s65, s65, 0
	s_cmp_gt_u32 s66, 13
	s_cbranch_scc1 .LBB0_1518

.LBB0_1514:
	s_add_u32 s42, s36, 0xfffc0080
	s_addc_u32 s43, s37, -1
	s_waitcnt lgkmcnt(0)
	s_and_b64 s[38:39], s[38:39], exec
	s_cselect_b32 s43, s25, s43
	s_cselect_b32 s42, s62, s42
	s_cselect_b32 s39, s23, s65
	s_cselect_b32 s38, s63, s64
	s_barrier
	s_waitcnt lgkmcnt(0)
	v_mfma_f32_16x16x32_bf16 v[132:135], v[144:147], v[184:187], v[132:135]
	v_mfma_f32_16x16x32_bf16 v[120:123], v[152:155], v[184:187], v[120:123]
	v_mfma_f32_16x16x32_bf16 v[108:111], v[144:147], v[176:179], v[108:111]
	v_mfma_f32_16x16x32_bf16 v[104:107], v[152:155], v[176:179], v[104:107]
	v_mfma_f32_16x16x32_bf16 v[92:95], v[144:147], v[168:171], v[92:95]
	v_mfma_f32_16x16x32_bf16 v[88:91], v[152:155], v[168:171], v[88:91]
	v_mfma_f32_16x16x32_bf16 v[76:79], v[144:147], v[160:163], v[76:79]
	v_mfma_f32_16x16x32_bf16 v[72:75], v[152:155], v[160:163], v[72:75]
	v_mfma_f32_16x16x32_bf16 v[132:135], v[148:151], v[188:191], v[132:135]
	v_mfma_f32_16x16x32_bf16 v[120:123], v[156:159], v[188:191], v[120:123]
	v_mfma_f32_16x16x32_bf16 v[108:111], v[148:151], v[180:183], v[108:111]
	v_mfma_f32_16x16x32_bf16 v[104:107], v[156:159], v[180:183], v[104:107]
	v_mfma_f32_16x16x32_bf16 v[92:95], v[148:151], v[172:175], v[92:95]
	v_mfma_f32_16x16x32_bf16 v[88:91], v[156:159], v[172:175], v[88:91]
	v_mfma_f32_16x16x32_bf16 v[76:79], v[148:151], v[164:167], v[76:79]
	v_mfma_f32_16x16x32_bf16 v[72:75], v[156:159], v[164:167], v[72:75]
	v_mfma_f32_16x16x32_bf16 v[116:119], v[124:127], v[184:187], v[116:119]
	v_mfma_f32_16x16x32_bf16 v[112:115], v[136:139], v[184:187], v[112:115]
	v_mfma_f32_16x16x32_bf16 v[100:103], v[124:127], v[176:179], v[100:103]
	v_mfma_f32_16x16x32_bf16 v[96:99], v[136:139], v[176:179], v[96:99]
	v_mfma_f32_16x16x32_bf16 v[84:87], v[124:127], v[168:171], v[84:87]
	v_mfma_f32_16x16x32_bf16 v[80:83], v[136:139], v[168:171], v[80:83]
	v_mfma_f32_16x16x32_bf16 v[68:71], v[124:127], v[160:163], v[68:71]
	v_mfma_f32_16x16x32_bf16 v[64:67], v[136:139], v[160:163], v[64:67]
	v_mfma_f32_16x16x32_bf16 v[116:119], v[128:131], v[188:191], v[116:119]
	v_mfma_f32_16x16x32_bf16 v[112:115], v[140:143], v[188:191], v[112:115]
	v_mfma_f32_16x16x32_bf16 v[100:103], v[128:131], v[180:183], v[100:103]
	v_mfma_f32_16x16x32_bf16 v[96:99], v[140:143], v[180:183], v[96:99]
	v_mfma_f32_16x16x32_bf16 v[84:87], v[128:131], v[172:175], v[84:87]
	v_mfma_f32_16x16x32_bf16 v[80:83], v[140:143], v[172:175], v[80:83]
	v_mfma_f32_16x16x32_bf16 v[68:71], v[128:131], v[164:167], v[68:71]
	v_mfma_f32_16x16x32_bf16 v[64:67], v[140:143], v[164:167], v[64:67]
	s_barrier
	s_mov_b32 m0, s49
	v_lshl_add_u64 v[216:217], s[38:39], 0, v[196:197]
	s_add_u32 s44, s38, 0x40000
	ds_read_b128 v[184:187], v222 offset:16384
	ds_read_b128 v[188:191], v222 offset:17408
	ds_read_b128 v[176:179], v222 offset:18432
	ds_read_b128 v[180:183], v222 offset:19456
	ds_read_b128 v[168:171], v222 offset:20480
	ds_read_b128 v[172:175], v222 offset:21504
	ds_read_b128 v[160:163], v222 offset:22528
	ds_read_b128 v[164:167], v222 offset:23552
	global_load_lds_dwordx4 v[216:217], off
	v_lshl_add_u64 v[214:215], s[38:39], 0, v[200:201]
	s_mov_b32 m0, s50
	s_addc_u32 s45, s39, 0
	global_load_lds_dwordx4 v[214:215], off
	v_lshl_add_u64 v[210:211], s[44:45], 0, v[196:197]
	s_mov_b32 m0, s51
	v_lshl_add_u64 v[212:213], s[42:43], 0, v[198:199]
	global_load_lds_dwordx4 v[210:211], off
	v_lshl_add_u64 v[210:211], s[44:45], 0, v[200:201]
	s_mov_b32 m0, s52
	s_mov_b64 s[44:45], -1
	global_load_lds_dwordx4 v[210:211], off
	v_lshl_add_u64 v[210:211], s[42:43], 0, v[194:195]
	s_mov_b32 m0, s48
	s_and_b64 vcc, exec, s[40:41]
	global_load_lds_dwordx4 v[210:211], off
	s_mov_b32 m0, s53
	s_nop 0
	global_load_lds_dwordx4 v[212:213], off
	s_cbranch_vccz .LBB0_1516
	s_waitcnt vmcnt(8)
	s_mov_b64 s[44:45], 0
